# GEMM_IN store epilogue rewritten by hand: one wave-uniform range check, row addresses computed once, v_permlane32_swap pairs so each lane stores 8 consecutive bf16 columns (16 dwordx4 instead of 32 gu
# speedup vs baseline: 1.3157x; 1.0245x over previous
; template <int TJ, bool SWAP, int NK, class Epi>
; DI void gemm_phase(const u16* __restrict__ A, size_t strideAz, int lda, const u16* __restrict__ Bt, size_t strideBz, int ldb,
;                    int Z, int Mt, int Nt, int GM, int K, char* smem, const Epi& epi, int vt) {
;     ...
;   for (int base = 0; base < total; base += G) {
;     const int q = base + vt;
;     if (q >= total) continue;
;     const int z = q / per, qq = q - z * per;
;     const int grp = qq / (GM * Nt), within = qq - grp * GM * Nt;
;     const int mt = grp * GM + (within % GM), nt = within / GM;
;     const u16* Ag = A + z * strideAz + (size_t)(mt * 256) * lda;
;     const u16* Bg = Bt + z * strideBz + (size_t)(nt * BN) * ldb;
;     u32x4 ra[2][8], rb[2][NB];
;     f32x16 acc[4][TJ];
; #pragma unroll
;     for (int i = 0; i < 4; ++i)
; #pragma unroll
;       for (int j = 0; j < TJ; ++j)
; #pragma unroll
;         for (int e = 0; e < 16; ++e) acc[i][j][e] = 0.f;
;     __syncthreads();
; #pragma unroll
;     for (int i = 0; i < 8; ++i) ra[0][i] = *(const u32x4*)(Ag + aoff[i]);
; #pragma unroll
;     for (int i = 0; i < NB; ++i) rb[0][i] = *(const u32x4*)(Bg + boff[i]);
; #pragma unroll
;     for (int i = 0; i < 8; ++i) ra[1][i] = *(const u32x4*)(Ag + 64 + aoff[i]);
; #pragma unroll
;     for (int i = 0; i < NB; ++i) rb[1][i] = *(const u32x4*)(Bg + 64 + boff[i]);
; #pragma unroll
;     for (int i = 0; i < 8; ++i) *(u32x4*)(As + lds_st + (32 * i) * 72) = ra[0][i];
; #pragma unroll
;     for (int i = 0; i < NB; ++i) *(u32x4*)(Bs + lds_st + (32 * i) * 72) = rb[0][i];
;     __syncthreads();
;     bf16x8 af[2][4], bfr[2][TJ];
; #pragma unroll
;     for (int kt = 0; kt < NK; ++kt) {
;       constexpr int dummy = 0; (void)dummy;
;       const int u = kt & 1;
;       const u16* as = As + u * 256 * 72 + (128 * wm + r) * 72 + 8 * h;
;       const u16* bs = Bs + u * BN * 72 + (32 * TJ * wn + r) * 72 + 8 * h;
;       if (kt == 0) {
; #pragma unroll
;         for (int i = 0; i < 4; ++i) af[0][i] = *(const bf16x8*)(as + (32 * i) * 72);
; #pragma unroll
;         for (int j = 0; j < TJ; ++j) bfr[0][j] = *(const bf16x8*)(bs + (32 * j) * 72);
;       }
; #pragma unroll
;       for (int ks = 0; ks < 4; ++ks) {
;         if (ks < 3) {
; #pragma unroll
;           for (int i = 0; i < 4; ++i) af[(ks + 1) & 1][i] = *(const bf16x8*)(as + (32 * i) * 72 + 16 * (ks + 1));
; #pragma unroll
.LBB0_428:
	s_add_i32 s0, s94, s20
	s_cmpk_gt_i32 s0, 0xe3f
	s_cbranch_scc1 .LBB0_427
	s_mul_hi_i32 s1, s0, 0x8fb823ef
	s_add_i32 s1, s1, s0
	s_lshr_b32 s6, s1, 31
	s_ashr_i32 s1, s1, 11
	s_add_i32 s1, s1, s6
	s_mulk_i32 s1, 0xe40
	s_sub_i32 s0, s0, s1
	s_mul_i32 s1, s0, 0xffff8fb9
	s_lshr_b32 s1, s1, 16
	s_add_i32 s1, s1, s0
	s_sext_i32_i16 s6, s1
	s_ashr_i32 s6, s6, 7
	s_bfe_u32 s1, s1, 0x1000f
	s_add_i32 s6, s6, s1
	s_sext_i32_i16 s1, s6
	s_mul_i32 s6, s1, 0xff1c
	s_add_i32 s0, s6, s0
	s_sext_i32_i16 s6, s0
	s_bfe_u32 s6, s6, 0x2001d
	s_add_i32 s6, s0, s6
	s_sext_i32_i16 s7, s6
	s_and_b32 s6, s6, 0xfffc
	s_sub_i32 s0, s0, s6
	s_sext_i32_i16 s0, s0
	s_lshl_b32 s1, s1, 10
	s_lshl_b32 s0, s0, 8
	s_add_i32 s0, s0, s1
	s_ashr_i32 s1, s0, 31
	s_lshl_b64 s[8:9], s[0:1], 11
	s_lshl_b32 s1, s7, 5
	s_and_b32 s6, s1, 0xffffff80
	s_ashr_i32 s7, s6, 31
	s_lshl_b64 s[10:11], s[6:7], 11
	v_readlane_b32 s12, v252, 54
	v_readlane_b32 s13, v252, 55
	s_add_u32 s8, s12, s8
	s_addc_u32 s9, s13, s9
	v_readlane_b32 s1, v255, 0
	v_lshl_add_u64 v[102:103], s[8:9], 0, v[72:73]
	v_lshl_add_u64 v[100:101], s[8:9], 0, v[74:75]
	v_lshl_add_u64 v[98:99], s[8:9], 0, v[76:77]
	v_lshl_add_u64 v[96:97], s[8:9], 0, v[78:79]
	v_lshl_add_u64 v[94:95], v[198:199], 1, s[8:9]
	v_lshl_add_u64 v[92:93], v[64:65], 1, s[8:9]
	v_lshl_add_u64 v[90:91], v[66:67], 1, s[8:9]
	v_lshl_add_u64 v[88:89], v[68:69], 1, s[8:9]
	s_add_u32 s8, s1, s10
	v_readlane_b32 s1, v255, 1
	s_addc_u32 s9, s1, s11
	v_lshl_add_u64 v[86:87], s[8:9], 0, v[72:73]
	v_lshl_add_u64 v[84:85], s[8:9], 0, v[74:75]
	v_lshl_add_u64 v[82:83], s[8:9], 0, v[76:77]
	v_lshl_add_u64 v[80:81], s[8:9], 0, v[78:79]
	s_barrier
	global_load_dwordx4 v[0:3], v[102:103], off
	global_load_dwordx4 v[4:7], v[100:101], off
	global_load_dwordx4 v[8:11], v[98:99], off
	global_load_dwordx4 v[12:15], v[96:97], off
	global_load_dwordx4 v[16:19], v[94:95], off
	global_load_dwordx4 v[20:23], v[92:93], off
	global_load_dwordx4 v[24:27], v[90:91], off
	global_load_dwordx4 v[28:31], v[88:89], off
	global_load_dwordx4 v[32:35], v[86:87], off
	global_load_dwordx4 v[36:39], v[84:85], off
	global_load_dwordx4 v[40:43], v[82:83], off
	global_load_dwordx4 v[44:47], v[80:81], off
	global_load_dwordx4 v[52:55], v[102:103], off offset:128
	global_load_dwordx4 v[60:63], v[100:101], off offset:128
	global_load_dwordx4 v[110:113], v[98:99], off offset:128
	global_load_dwordx4 v[114:117], v[96:97], off offset:128
	global_load_dwordx4 v[118:121], v[94:95], off offset:128
	global_load_dwordx4 v[122:125], v[92:93], off offset:128
	global_load_dwordx4 v[126:129], v[90:91], off offset:128
	global_load_dwordx4 v[130:133], v[88:89], off offset:128
	global_load_dwordx4 v[134:137], v[86:87], off offset:128
	global_load_dwordx4 v[138:141], v[84:85], off offset:128
	global_load_dwordx4 v[142:145], v[82:83], off offset:128
	global_load_dwordx4 v[146:149], v[80:81], off offset:128
	s_waitcnt vmcnt(23)
	ds_write_b128 v104, v[0:3]
	s_waitcnt vmcnt(22)
	ds_write_b128 v104, v[4:7] offset:4608
	s_waitcnt vmcnt(21)
	ds_write_b128 v104, v[8:11] offset:9216
	s_waitcnt vmcnt(20)
	ds_write_b128 v104, v[12:15] offset:13824
	s_waitcnt vmcnt(19)
	ds_write_b128 v104, v[16:19] offset:18432
	s_waitcnt vmcnt(18)
	ds_write_b128 v104, v[20:23] offset:23040
	s_waitcnt vmcnt(17)
	ds_write_b128 v104, v[24:27] offset:27648
	s_waitcnt vmcnt(16)
	ds_write_b128 v104, v[28:31] offset:32256
	s_waitcnt vmcnt(15)
	ds_write_b128 v105, v[32:35]
	s_waitcnt vmcnt(14)
	ds_write_b128 v105, v[36:39] offset:4608
	s_waitcnt vmcnt(13)
	ds_write_b128 v105, v[40:43] offset:9216
	s_waitcnt vmcnt(12)
	ds_write_b128 v105, v[44:47] offset:13824
	s_waitcnt lgkmcnt(0)
	s_barrier
	ds_read_b128 v[0:3], v70
	ds_read_b128 v[4:7], v70 offset:32
	ds_read_b128 v[8:11], v70 offset:4608
	ds_read_b128 v[12:15], v70 offset:4640
	ds_read_b128 v[16:19], v70 offset:9216
	ds_read_b128 v[20:23], v70 offset:9248
	ds_read_b128 v[24:27], v70 offset:13824
	ds_read_b128 v[28:31], v70 offset:13856
	ds_read_b128 v[32:35], v71
	ds_read_b128 v[36:39], v71 offset:32
	ds_read_b128 v[40:43], v71 offset:4608
	ds_read_b128 v[44:47], v71 offset:4640
	s_waitcnt lgkmcnt(3)
	v_mfma_f32_32x32x16_bf16 a[112:127], v[32:35], v[0:3], 0
	global_load_dwordx4 v[48:51], v[90:91], off offset:256
	s_waitcnt lgkmcnt(1)
	v_mfma_f32_32x32x16_bf16 a[96:111], v[40:43], v[0:3], 0
	global_load_dwordx4 v[0:3], v[102:103], off offset:256
	v_mfma_f32_32x32x16_bf16 a[80:95], v[32:35], v[8:11], 0
	global_load_dwordx4 v[56:59], v[88:89], off offset:256
	v_mfma_f32_32x32x16_bf16 a[64:79], v[40:43], v[8:11], 0
	global_load_dwordx4 v[8:11], v[100:101], off offset:256
	v_mfma_f32_32x32x16_bf16 a[48:63], v[32:35], v[16:19], 0
	v_mfma_f32_32x32x16_bf16 a[32:47], v[40:43], v[16:19], 0
	v_mfma_f32_32x32x16_bf16 a[0:15], v[40:43], v[24:27], 0
	global_load_dwordx4 v[40:43], v[92:93], off offset:256
	global_load_dwordx4 v[16:19], v[98:99], off offset:256
	v_mfma_f32_32x32x16_bf16 a[16:31], v[32:35], v[24:27], 0
	global_load_dwordx4 v[32:35], v[94:95], off offset:256
	global_load_dwordx4 v[24:27], v[96:97], off offset:256
	ds_read_b128 v[150:153], v70 offset:64
	ds_read_b128 v[154:157], v70 offset:4672
	ds_read_b128 v[158:161], v70 offset:9280
	ds_read_b128 v[162:165], v70 offset:13888
	ds_read_b128 v[166:169], v71 offset:64
	ds_read_b128 v[170:173], v71 offset:4672
	v_mfma_f32_32x32x16_bf16 a[112:127], v[36:39], v[4:7], a[112:127]
	s_waitcnt vmcnt(19)
	ds_write_b128 v104, v[52:55] offset:36864
	s_waitcnt vmcnt(18)
	ds_write_b128 v104, v[60:63] offset:41472
	s_waitcnt lgkmcnt(8)
	v_mfma_f32_32x32x16_bf16 a[96:111], v[44:47], v[4:7], a[96:111]
	s_waitcnt vmcnt(17)
; template <int TJ, bool SWAP, int NK, class Epi>
; DI void gemm_phase(const u16* __restrict__ A, size_t strideAz, int lda, const u16* __restrict__ Bt, size_t strideBz, int ldb,
;                    int Z, int Mt, int Nt, int GM, int K, char* smem, const Epi& epi, int vt) {
;     ...
;     for (int kt = 0; kt < NK; ++kt) {
;       constexpr int dummy = 0; (void)dummy;
;       const int u = kt & 1;
;       const u16* as = As + u * 256 * 72 + (128 * wm + r) * 72 + 8 * h;
;       const u16* bs = Bs + u * BN * 72 + (32 * TJ * wn + r) * 72 + 8 * h;
;       if (kt == 0) {
; #pragma unroll
;         for (int i = 0; i < 4; ++i) af[0][i] = *(const bf16x8*)(as + (32 * i) * 72);
; #pragma unroll
;         for (int j = 0; j < TJ; ++j) bfr[0][j] = *(const bf16x8*)(bs + (32 * j) * 72);
;       }
; #pragma unroll
;       for (int ks = 0; ks < 4; ++ks) {
;         if (ks < 3) {
; #pragma unroll
;           for (int i = 0; i < 4; ++i) af[(ks + 1) & 1][i] = *(const bf16x8*)(as + (32 * i) * 72 + 16 * (ks + 1));
; #pragma unroll
;           for (int j = 0; j < TJ; ++j) bfr[(ks + 1) & 1][j] = *(const bf16x8*)(bs + (32 * j) * 72 + 16 * (ks + 1));
;         } else if (kt + 1 < NK) {
;           const u16* asn = As + (u ^ 1) * 256 * 72 + (128 * wm + r) * 72 + 8 * h;
;           const u16* bsn = Bs + (u ^ 1) * BN * 72 + (32 * TJ * wn + r) * 72 + 8 * h;
; #pragma unroll
;           for (int i = 0; i < 4; ++i) af[0][i] = *(const bf16x8*)(asn + (32 * i) * 72);
; #pragma unroll
;           for (int j = 0; j < TJ; ++j) bfr[0][j] = *(const bf16x8*)(bsn + (32 * j) * 72);
;         }
;         __builtin_amdgcn_sched_barrier(0);
; #pragma unroll
;         for (int i = 0; i < 4; ++i)
; #pragma unroll
;           for (int j = 0; j < TJ; ++j)
;             acc[i][j] = SWAP ? MFMA32(bfr[ks & 1][j], af[ks & 1][i], acc[i][j]) : MFMA32(af[ks & 1][i], bfr[ks & 1][j], acc[i][j]);
;         if (ks == 0 && kt + 2 < NK) {
;           const u16* ag = Ag + (kt + 2) * 64;
; #pragma unroll
;           for (int i = 0; i < 8; ++i) ra[u][i] = *(const u32x4*)(ag + aoff[i]);
; #pragma unroll
;           for (int i = 0; i < 8; ++i) { __builtin_amdgcn_sched_group_barrier(0x008, 1, 0); __builtin_amdgcn_sched_group_barrier(0x020, 1, 0); }
;         }
;         if (ks == 2 && kt + 2 < NK) {
;           const u16* bg = Bg + (kt + 2) * 64;
; #pragma unroll
	ds_write_b128 v104, v[110:113] offset:46080
	s_waitcnt vmcnt(16)
	ds_write_b128 v104, v[114:117] offset:50688
	v_mfma_f32_32x32x16_bf16 a[80:95], v[36:39], v[12:15], a[80:95]
	s_waitcnt vmcnt(15)
	ds_write_b128 v104, v[118:121] offset:55296
	s_waitcnt vmcnt(14)
	ds_write_b128 v104, v[122:125] offset:59904
	v_mfma_f32_32x32x16_bf16 a[64:79], v[44:47], v[12:15], a[64:79]
	s_waitcnt vmcnt(13)
	ds_write_b128 v104, v[126:129] offset:64512
	s_waitcnt vmcnt(12)
	ds_write_b128 v108, v[130:133]
	v_mfma_f32_32x32x16_bf16 a[48:63], v[36:39], v[20:23], a[48:63]
	s_waitcnt vmcnt(11)
	ds_write_b128 v105, v[134:137] offset:18432
	s_waitcnt vmcnt(10)
	ds_write_b128 v105, v[138:141] offset:23040
	v_mfma_f32_32x32x16_bf16 a[32:47], v[44:47], v[20:23], a[32:47]
	s_waitcnt vmcnt(9)
	ds_write_b128 v105, v[142:145] offset:27648
	s_waitcnt vmcnt(8)
	ds_write_b128 v105, v[146:149] offset:32256
	v_mfma_f32_32x32x16_bf16 a[16:31], v[36:39], v[28:31], a[16:31]
	v_mfma_f32_32x32x16_bf16 a[0:15], v[44:47], v[28:31], a[0:15]
	ds_read_b128 v[4:7], v70 offset:96
	ds_read_b128 v[12:15], v70 offset:4704
	ds_read_b128 v[20:23], v70 offset:9312
	ds_read_b128 v[28:31], v70 offset:13920
	ds_read_b128 v[36:39], v71 offset:96
	ds_read_b128 v[44:47], v71 offset:4704
	s_waitcnt lgkmcnt(14)
	v_mfma_f32_32x32x16_bf16 a[112:127], v[166:169], v[150:153], a[112:127]
	global_load_dwordx4 v[110:113], v[86:87], off offset:256
	v_mfma_f32_32x32x16_bf16 a[96:111], v[170:173], v[150:153], a[96:111]
	global_load_dwordx4 v[114:117], v[84:85], off offset:256
	v_mfma_f32_32x32x16_bf16 a[80:95], v[166:169], v[154:157], a[80:95]
	global_load_dwordx4 v[118:121], v[82:83], off offset:256
	v_mfma_f32_32x32x16_bf16 a[64:79], v[170:173], v[154:157], a[64:79]
	global_load_dwordx4 v[122:125], v[80:81], off offset:256
	v_mfma_f32_32x32x16_bf16 a[48:63], v[166:169], v[158:161], a[48:63]
	v_mfma_f32_32x32x16_bf16 a[32:47], v[170:173], v[158:161], a[32:47]
	v_mfma_f32_32x32x16_bf16 a[16:31], v[166:169], v[162:165], a[16:31]
	v_mfma_f32_32x32x16_bf16 a[0:15], v[170:173], v[162:165], a[0:15]
	s_waitcnt lgkmcnt(0)
	s_barrier
	ds_read_b128 v[52:55], v70 offset:36864
	ds_read_b128 v[60:63], v70 offset:41472
	ds_read_b128 v[126:129], v70 offset:46080
	ds_read_b128 v[130:133], v70 offset:50688
	ds_read_b128 v[134:137], v71 offset:18432
	ds_read_b128 v[138:141], v71 offset:23040
	v_mfma_f32_32x32x16_bf16 a[112:127], v[36:39], v[4:7], a[112:127]
	v_mfma_f32_32x32x16_bf16 a[96:111], v[44:47], v[4:7], a[96:111]
	v_mfma_f32_32x32x16_bf16 a[80:95], v[36:39], v[12:15], a[80:95]
	v_mfma_f32_32x32x16_bf16 a[64:79], v[44:47], v[12:15], a[64:79]
	v_mfma_f32_32x32x16_bf16 a[48:63], v[36:39], v[20:23], a[48:63]
	v_mfma_f32_32x32x16_bf16 a[32:47], v[44:47], v[20:23], a[32:47]
	v_mfma_f32_32x32x16_bf16 a[16:31], v[36:39], v[28:31], a[16:31]
	v_mfma_f32_32x32x16_bf16 a[0:15], v[44:47], v[28:31], a[0:15]
	ds_read_b128 v[142:145], v70 offset:36896
	ds_read_b128 v[146:149], v70 offset:41504
	ds_read_b128 v[150:153], v70 offset:46112
	ds_read_b128 v[154:157], v70 offset:50720
	ds_read_b128 v[158:161], v71 offset:18464
	ds_read_b128 v[162:165], v71 offset:23072
	s_waitcnt lgkmcnt(7)
	v_mfma_f32_32x32x16_bf16 a[112:127], v[134:137], v[52:55], a[112:127]
	global_load_dwordx4 v[4:7], v[102:103], off offset:384
	s_waitcnt lgkmcnt(6)
	v_mfma_f32_32x32x16_bf16 a[96:111], v[138:141], v[52:55], a[96:111]
	global_load_dwordx4 v[12:15], v[100:101], off offset:384
	v_mfma_f32_32x32x16_bf16 a[80:95], v[134:137], v[60:63], a[80:95]
	global_load_dwordx4 v[20:23], v[98:99], off offset:384
	v_mfma_f32_32x32x16_bf16 a[64:79], v[138:141], v[60:63], a[64:79]
	global_load_dwordx4 v[28:31], v[96:97], off offset:384
	v_mfma_f32_32x32x16_bf16 a[48:63], v[134:137], v[126:129], a[48:63]
	global_load_dwordx4 v[36:39], v[94:95], off offset:384
	v_mfma_f32_32x32x16_bf16 a[32:47], v[138:141], v[126:129], a[32:47]
	global_load_dwordx4 v[44:47], v[92:93], off offset:384
	v_mfma_f32_32x32x16_bf16 a[16:31], v[134:137], v[130:133], a[16:31]
	global_load_dwordx4 v[52:55], v[90:91], off offset:384
	v_mfma_f32_32x32x16_bf16 a[0:15], v[138:141], v[130:133], a[0:15]
	global_load_dwordx4 v[60:63], v[88:89], off offset:384
	ds_read_b128 v[126:129], v70 offset:36928
	ds_read_b128 v[130:133], v70 offset:41536
	ds_read_b128 v[134:137], v70 offset:46144
	ds_read_b128 v[138:141], v70 offset:50752
	ds_read_b128 v[166:169], v71 offset:18496
	ds_read_b128 v[170:173], v71 offset:23104
	s_waitcnt lgkmcnt(7)
	v_mfma_f32_32x32x16_bf16 a[112:127], v[158:161], v[142:145], a[112:127]
	s_waitcnt vmcnt(18)
	ds_write_b128 v104, v[0:3]
	s_waitcnt vmcnt(16)
	ds_write_b128 v104, v[8:11] offset:4608
	s_waitcnt lgkmcnt(8)
	v_mfma_f32_32x32x16_bf16 a[96:111], v[162:165], v[142:145], a[96:111]
	s_waitcnt vmcnt(14)
	ds_write_b128 v104, v[16:19] offset:9216
	s_waitcnt vmcnt(12)
	ds_write_b128 v104, v[24:27] offset:13824
	v_mfma_f32_32x32x16_bf16 a[80:95], v[158:161], v[146:149], a[80:95]
	ds_write_b128 v104, v[32:35] offset:18432
	ds_write_b128 v104, v[40:43] offset:23040
	v_mfma_f32_32x32x16_bf16 a[64:79], v[162:165], v[146:149], a[64:79]
	ds_write_b128 v104, v[48:51] offset:27648
	ds_write_b128 v104, v[56:59] offset:32256
	v_mfma_f32_32x32x16_bf16 a[48:63], v[158:161], v[150:153], a[48:63]
	s_waitcnt vmcnt(11)
	ds_write_b128 v105, v[110:113]
	s_waitcnt vmcnt(10)
	ds_write_b128 v105, v[114:117] offset:4608
	v_mfma_f32_32x32x16_bf16 a[32:47], v[162:165], v[150:153], a[32:47]
	s_waitcnt vmcnt(9)
	ds_write_b128 v105, v[118:121] offset:9216
	s_waitcnt vmcnt(8)
	ds_write_b128 v105, v[122:125] offset:13824
	v_mfma_f32_32x32x16_bf16 a[16:31], v[158:161], v[154:157], a[16:31]
	v_mfma_f32_32x32x16_bf16 a[0:15], v[162:165], v[154:157], a[0:15]
	ds_read_b128 v[0:3], v70 offset:36960
	ds_read_b128 v[8:11], v70 offset:41568
	ds_read_b128 v[16:19], v70 offset:46176
	ds_read_b128 v[24:27], v70 offset:50784
	ds_read_b128 v[32:35], v71 offset:18528
	ds_read_b128 v[40:43], v71 offset:23136
	s_waitcnt lgkmcnt(14)
	v_mfma_f32_32x32x16_bf16 a[112:127], v[166:169], v[126:129], a[112:127]
	global_load_dwordx4 v[110:113], v[86:87], off offset:384
	v_mfma_f32_32x32x16_bf16 a[96:111], v[170:173], v[126:129], a[96:111]
	global_load_dwordx4 v[114:117], v[84:85], off offset:384
	v_mfma_f32_32x32x16_bf16 a[80:95], v[166:169], v[130:133], a[80:95]
	global_load_dwordx4 v[118:121], v[82:83], off offset:384
	v_mfma_f32_32x32x16_bf16 a[64:79], v[170:173], v[130:133], a[64:79]
	global_load_dwordx4 v[122:125], v[80:81], off offset:384
	v_mfma_f32_32x32x16_bf16 a[48:63], v[166:169], v[134:137], a[48:63]
	v_mfma_f32_32x32x16_bf16 a[32:47], v[170:173], v[134:137], a[32:47]
	v_mfma_f32_32x32x16_bf16 a[16:31], v[166:169], v[138:141], a[16:31]
	v_mfma_f32_32x32x16_bf16 a[0:15], v[170:173], v[138:141], a[0:15]
	s_waitcnt lgkmcnt(0)
	s_barrier
; template <int TJ, bool SWAP, int NK, class Epi>
; DI void gemm_phase(const u16* __restrict__ A, size_t strideAz, int lda, const u16* __restrict__ Bt, size_t strideBz, int ldb,
;                    int Z, int Mt, int Nt, int GM, int K, char* smem, const Epi& epi, int vt) {
;     ...
;     for (int kt = 0; kt < NK; ++kt) {
;       constexpr int dummy = 0; (void)dummy;
;       const int u = kt & 1;
;       const u16* as = As + u * 256 * 72 + (128 * wm + r) * 72 + 8 * h;
;       const u16* bs = Bs + u * BN * 72 + (32 * TJ * wn + r) * 72 + 8 * h;
;       if (kt == 0) {
; #pragma unroll
;         for (int i = 0; i < 4; ++i) af[0][i] = *(const bf16x8*)(as + (32 * i) * 72);
; #pragma unroll
;         for (int j = 0; j < TJ; ++j) bfr[0][j] = *(const bf16x8*)(bs + (32 * j) * 72);
;       }
; #pragma unroll
;       for (int ks = 0; ks < 4; ++ks) {
;         if (ks < 3) {
; #pragma unroll
;           for (int i = 0; i < 4; ++i) af[(ks + 1) & 1][i] = *(const bf16x8*)(as + (32 * i) * 72 + 16 * (ks + 1));
; #pragma unroll
;           for (int j = 0; j < TJ; ++j) bfr[(ks + 1) & 1][j] = *(const bf16x8*)(bs + (32 * j) * 72 + 16 * (ks + 1));
;         } else if (kt + 1 < NK) {
;           const u16* asn = As + (u ^ 1) * 256 * 72 + (128 * wm + r) * 72 + 8 * h;
;           const u16* bsn = Bs + (u ^ 1) * BN * 72 + (32 * TJ * wn + r) * 72 + 8 * h;
; #pragma unroll
;           for (int i = 0; i < 4; ++i) af[0][i] = *(const bf16x8*)(asn + (32 * i) * 72);
; #pragma unroll
;           for (int j = 0; j < TJ; ++j) bfr[0][j] = *(const bf16x8*)(bsn + (32 * j) * 72);
;         }
;         __builtin_amdgcn_sched_barrier(0);
; #pragma unroll
;         for (int i = 0; i < 4; ++i)
; #pragma unroll
;           for (int j = 0; j < TJ; ++j)
;             acc[i][j] = SWAP ? MFMA32(bfr[ks & 1][j], af[ks & 1][i], acc[i][j]) : MFMA32(af[ks & 1][i], bfr[ks & 1][j], acc[i][j]);
;         if (ks == 0 && kt + 2 < NK) {
;           const u16* ag = Ag + (kt + 2) * 64;
; #pragma unroll
;           for (int i = 0; i < 8; ++i) ra[u][i] = *(const u32x4*)(ag + aoff[i]);
; #pragma unroll
;           for (int i = 0; i < 8; ++i) { __builtin_amdgcn_sched_group_barrier(0x008, 1, 0); __builtin_amdgcn_sched_group_barrier(0x020, 1, 0); }
;         }
;         if (ks == 2 && kt + 2 < NK) {
;           const u16* bg = Bg + (kt + 2) * 64;
; #pragma unroll
	ds_read_b128 v[48:51], v70
	ds_read_b128 v[56:59], v70 offset:4608
	ds_read_b128 v[126:129], v70 offset:9216
	ds_read_b128 v[130:133], v70 offset:13824
	ds_read_b128 v[134:137], v71
	ds_read_b128 v[138:141], v71 offset:4608
	v_mfma_f32_32x32x16_bf16 a[112:127], v[32:35], v[0:3], a[112:127]
	v_mfma_f32_32x32x16_bf16 a[96:111], v[40:43], v[0:3], a[96:111]
	v_mfma_f32_32x32x16_bf16 a[80:95], v[32:35], v[8:11], a[80:95]
	v_mfma_f32_32x32x16_bf16 a[64:79], v[40:43], v[8:11], a[64:79]
	v_mfma_f32_32x32x16_bf16 a[48:63], v[32:35], v[16:19], a[48:63]
	v_mfma_f32_32x32x16_bf16 a[32:47], v[40:43], v[16:19], a[32:47]
	v_mfma_f32_32x32x16_bf16 a[16:31], v[32:35], v[24:27], a[16:31]
	v_mfma_f32_32x32x16_bf16 a[0:15], v[40:43], v[24:27], a[0:15]
	ds_read_b128 v[142:145], v70 offset:32
	ds_read_b128 v[146:149], v70 offset:4640
	ds_read_b128 v[150:153], v70 offset:9248
	ds_read_b128 v[154:157], v70 offset:13856
	ds_read_b128 v[158:161], v71 offset:32
	ds_read_b128 v[162:165], v71 offset:4640
	s_waitcnt lgkmcnt(7)
	v_mfma_f32_32x32x16_bf16 a[112:127], v[134:137], v[48:51], a[112:127]
	global_load_dwordx4 v[0:3], v[102:103], off offset:512
	s_waitcnt lgkmcnt(6)
	v_mfma_f32_32x32x16_bf16 a[96:111], v[138:141], v[48:51], a[96:111]
	global_load_dwordx4 v[8:11], v[100:101], off offset:512
	v_mfma_f32_32x32x16_bf16 a[80:95], v[134:137], v[56:59], a[80:95]
	global_load_dwordx4 v[16:19], v[98:99], off offset:512
	v_mfma_f32_32x32x16_bf16 a[64:79], v[138:141], v[56:59], a[64:79]
	global_load_dwordx4 v[24:27], v[96:97], off offset:512
	v_mfma_f32_32x32x16_bf16 a[48:63], v[134:137], v[126:129], a[48:63]
	global_load_dwordx4 v[32:35], v[94:95], off offset:512
	v_mfma_f32_32x32x16_bf16 a[32:47], v[138:141], v[126:129], a[32:47]
	global_load_dwordx4 v[40:43], v[92:93], off offset:512
	v_mfma_f32_32x32x16_bf16 a[16:31], v[134:137], v[130:133], a[16:31]
	global_load_dwordx4 v[48:51], v[90:91], off offset:512
	v_mfma_f32_32x32x16_bf16 a[0:15], v[138:141], v[130:133], a[0:15]
	global_load_dwordx4 v[56:59], v[88:89], off offset:512
	ds_read_b128 v[126:129], v70 offset:64
	ds_read_b128 v[130:133], v70 offset:4672
	ds_read_b128 v[134:137], v70 offset:9280
	ds_read_b128 v[138:141], v70 offset:13888
	ds_read_b128 v[166:169], v71 offset:64
	ds_read_b128 v[170:173], v71 offset:4672
	s_waitcnt lgkmcnt(7)
	v_mfma_f32_32x32x16_bf16 a[112:127], v[158:161], v[142:145], a[112:127]
	s_waitcnt vmcnt(19)
	ds_write_b128 v104, v[4:7] offset:36864
	s_waitcnt vmcnt(18)
	ds_write_b128 v104, v[12:15] offset:41472
	s_waitcnt lgkmcnt(8)
	v_mfma_f32_32x32x16_bf16 a[96:111], v[162:165], v[142:145], a[96:111]
	s_waitcnt vmcnt(17)
	ds_write_b128 v104, v[20:23] offset:46080
	s_waitcnt vmcnt(16)
	ds_write_b128 v104, v[28:31] offset:50688
	v_mfma_f32_32x32x16_bf16 a[80:95], v[158:161], v[146:149], a[80:95]
	s_waitcnt vmcnt(15)
	ds_write_b128 v104, v[36:39] offset:55296
	s_waitcnt vmcnt(14)
	ds_write_b128 v104, v[44:47] offset:59904
	v_mfma_f32_32x32x16_bf16 a[64:79], v[162:165], v[146:149], a[64:79]
	s_waitcnt vmcnt(13)
	ds_write_b128 v104, v[52:55] offset:64512
	s_waitcnt vmcnt(12)
	ds_write_b128 v108, v[60:63]
	v_mfma_f32_32x32x16_bf16 a[48:63], v[158:161], v[150:153], a[48:63]
	s_waitcnt vmcnt(11)
	ds_write_b128 v105, v[110:113] offset:18432
	s_waitcnt vmcnt(10)
	ds_write_b128 v105, v[114:117] offset:23040
	v_mfma_f32_32x32x16_bf16 a[32:47], v[162:165], v[150:153], a[32:47]
	s_waitcnt vmcnt(9)
	ds_write_b128 v105, v[118:121] offset:27648
	s_waitcnt vmcnt(8)
	ds_write_b128 v105, v[122:125] offset:32256
	v_mfma_f32_32x32x16_bf16 a[16:31], v[158:161], v[154:157], a[16:31]
	v_mfma_f32_32x32x16_bf16 a[0:15], v[162:165], v[154:157], a[0:15]
	ds_read_b128 v[4:7], v70 offset:96
	ds_read_b128 v[12:15], v70 offset:4704
	ds_read_b128 v[20:23], v70 offset:9312
	ds_read_b128 v[28:31], v70 offset:13920
	ds_read_b128 v[36:39], v71 offset:96
	ds_read_b128 v[44:47], v71 offset:4704
	s_waitcnt lgkmcnt(14)
	v_mfma_f32_32x32x16_bf16 a[112:127], v[166:169], v[126:129], a[112:127]
	global_load_dwordx4 v[110:113], v[86:87], off offset:512
	v_mfma_f32_32x32x16_bf16 a[96:111], v[170:173], v[126:129], a[96:111]
	global_load_dwordx4 v[114:117], v[84:85], off offset:512
	v_mfma_f32_32x32x16_bf16 a[80:95], v[166:169], v[130:133], a[80:95]
	global_load_dwordx4 v[118:121], v[82:83], off offset:512
	v_mfma_f32_32x32x16_bf16 a[64:79], v[170:173], v[130:133], a[64:79]
	global_load_dwordx4 v[122:125], v[80:81], off offset:512
	v_mfma_f32_32x32x16_bf16 a[48:63], v[166:169], v[134:137], a[48:63]
	v_mfma_f32_32x32x16_bf16 a[32:47], v[170:173], v[134:137], a[32:47]
	v_mfma_f32_32x32x16_bf16 a[16:31], v[166:169], v[138:141], a[16:31]
	v_mfma_f32_32x32x16_bf16 a[0:15], v[170:173], v[138:141], a[0:15]
	s_waitcnt lgkmcnt(0)
	s_barrier
; template <int TJ, bool SWAP, int NK, class Epi>
; DI void gemm_phase(const u16* __restrict__ A, size_t strideAz, int lda, const u16* __restrict__ Bt, size_t strideBz, int ldb,
;                    int Z, int Mt, int Nt, int GM, int K, char* smem, const Epi& epi, int vt) {
;     ...
;     for (int kt = 0; kt < NK; ++kt) {
;       constexpr int dummy = 0; (void)dummy;
;       const int u = kt & 1;
;       const u16* as = As + u * 256 * 72 + (128 * wm + r) * 72 + 8 * h;
;       const u16* bs = Bs + u * BN * 72 + (32 * TJ * wn + r) * 72 + 8 * h;
;       if (kt == 0) {
; #pragma unroll
;         for (int i = 0; i < 4; ++i) af[0][i] = *(const bf16x8*)(as + (32 * i) * 72);
; #pragma unroll
;         for (int j = 0; j < TJ; ++j) bfr[0][j] = *(const bf16x8*)(bs + (32 * j) * 72);
;       }
; #pragma unroll
;       for (int ks = 0; ks < 4; ++ks) {
;         if (ks < 3) {
; #pragma unroll
;           for (int i = 0; i < 4; ++i) af[(ks + 1) & 1][i] = *(const bf16x8*)(as + (32 * i) * 72 + 16 * (ks + 1));
; #pragma unroll
;           for (int j = 0; j < TJ; ++j) bfr[(ks + 1) & 1][j] = *(const bf16x8*)(bs + (32 * j) * 72 + 16 * (ks + 1));
;         } else if (kt + 1 < NK) {
;           const u16* asn = As + (u ^ 1) * 256 * 72 + (128 * wm + r) * 72 + 8 * h;
;           const u16* bsn = Bs + (u ^ 1) * BN * 72 + (32 * TJ * wn + r) * 72 + 8 * h;
; #pragma unroll
;           for (int i = 0; i < 4; ++i) af[0][i] = *(const bf16x8*)(asn + (32 * i) * 72);
; #pragma unroll
;           for (int j = 0; j < TJ; ++j) bfr[0][j] = *(const bf16x8*)(bsn + (32 * j) * 72);
;         }
;         __builtin_amdgcn_sched_barrier(0);
; #pragma unroll
;         for (int i = 0; i < 4; ++i)
; #pragma unroll
;           for (int j = 0; j < TJ; ++j)
;             acc[i][j] = SWAP ? MFMA32(bfr[ks & 1][j], af[ks & 1][i], acc[i][j]) : MFMA32(af[ks & 1][i], bfr[ks & 1][j], acc[i][j]);
;         if (ks == 0 && kt + 2 < NK) {
;           const u16* ag = Ag + (kt + 2) * 64;
; #pragma unroll
;           for (int i = 0; i < 8; ++i) ra[u][i] = *(const u32x4*)(ag + aoff[i]);
; #pragma unroll
;           for (int i = 0; i < 8; ++i) { __builtin_amdgcn_sched_group_barrier(0x008, 1, 0); __builtin_amdgcn_sched_group_barrier(0x020, 1, 0); }
;         }
;         if (ks == 2 && kt + 2 < NK) {
;           const u16* bg = Bg + (kt + 2) * 64;
; #pragma unroll
	ds_read_b128 v[52:55], v70 offset:36864
	ds_read_b128 v[60:63], v70 offset:41472
	ds_read_b128 v[126:129], v70 offset:46080
	ds_read_b128 v[130:133], v70 offset:50688
	ds_read_b128 v[134:137], v71 offset:18432
	ds_read_b128 v[138:141], v71 offset:23040
	v_mfma_f32_32x32x16_bf16 a[112:127], v[36:39], v[4:7], a[112:127]
	v_mfma_f32_32x32x16_bf16 a[96:111], v[44:47], v[4:7], a[96:111]
	v_mfma_f32_32x32x16_bf16 a[80:95], v[36:39], v[12:15], a[80:95]
	v_mfma_f32_32x32x16_bf16 a[64:79], v[44:47], v[12:15], a[64:79]
	v_mfma_f32_32x32x16_bf16 a[48:63], v[36:39], v[20:23], a[48:63]
	v_mfma_f32_32x32x16_bf16 a[32:47], v[44:47], v[20:23], a[32:47]
	v_mfma_f32_32x32x16_bf16 a[16:31], v[36:39], v[28:31], a[16:31]
	v_mfma_f32_32x32x16_bf16 a[0:15], v[44:47], v[28:31], a[0:15]
	ds_read_b128 v[142:145], v70 offset:36896
	ds_read_b128 v[146:149], v70 offset:41504
	ds_read_b128 v[150:153], v70 offset:46112
	ds_read_b128 v[154:157], v70 offset:50720
	ds_read_b128 v[158:161], v71 offset:18464
	ds_read_b128 v[162:165], v71 offset:23072
	s_waitcnt lgkmcnt(7)
	v_mfma_f32_32x32x16_bf16 a[112:127], v[134:137], v[52:55], a[112:127]
	global_load_dwordx4 v[4:7], v[102:103], off offset:640
	s_waitcnt lgkmcnt(6)
	v_mfma_f32_32x32x16_bf16 a[96:111], v[138:141], v[52:55], a[96:111]
	global_load_dwordx4 v[12:15], v[100:101], off offset:640
	v_mfma_f32_32x32x16_bf16 a[80:95], v[134:137], v[60:63], a[80:95]
	global_load_dwordx4 v[20:23], v[98:99], off offset:640
	v_mfma_f32_32x32x16_bf16 a[64:79], v[138:141], v[60:63], a[64:79]
	global_load_dwordx4 v[28:31], v[96:97], off offset:640
	v_mfma_f32_32x32x16_bf16 a[48:63], v[134:137], v[126:129], a[48:63]
	global_load_dwordx4 v[36:39], v[94:95], off offset:640
	v_mfma_f32_32x32x16_bf16 a[32:47], v[138:141], v[126:129], a[32:47]
	global_load_dwordx4 v[44:47], v[92:93], off offset:640
	v_mfma_f32_32x32x16_bf16 a[16:31], v[134:137], v[130:133], a[16:31]
	global_load_dwordx4 v[52:55], v[90:91], off offset:640
	v_mfma_f32_32x32x16_bf16 a[0:15], v[138:141], v[130:133], a[0:15]
	global_load_dwordx4 v[60:63], v[88:89], off offset:640
	ds_read_b128 v[126:129], v70 offset:36928
	ds_read_b128 v[130:133], v70 offset:41536
	ds_read_b128 v[134:137], v70 offset:46144
	ds_read_b128 v[138:141], v70 offset:50752
	ds_read_b128 v[166:169], v71 offset:18496
	ds_read_b128 v[170:173], v71 offset:23104
	s_waitcnt lgkmcnt(7)
	v_mfma_f32_32x32x16_bf16 a[112:127], v[158:161], v[142:145], a[112:127]
	s_waitcnt vmcnt(19)
	ds_write_b128 v104, v[0:3]
	s_waitcnt vmcnt(18)
	ds_write_b128 v104, v[8:11] offset:4608
	s_waitcnt lgkmcnt(8)
	v_mfma_f32_32x32x16_bf16 a[96:111], v[162:165], v[142:145], a[96:111]
	s_waitcnt vmcnt(17)
	ds_write_b128 v104, v[16:19] offset:9216
	s_waitcnt vmcnt(16)
	ds_write_b128 v104, v[24:27] offset:13824
	v_mfma_f32_32x32x16_bf16 a[80:95], v[158:161], v[146:149], a[80:95]
	s_waitcnt vmcnt(15)
	ds_write_b128 v104, v[32:35] offset:18432
	s_waitcnt vmcnt(14)
	ds_write_b128 v104, v[40:43] offset:23040
	v_mfma_f32_32x32x16_bf16 a[64:79], v[162:165], v[146:149], a[64:79]
	s_waitcnt vmcnt(13)
	ds_write_b128 v104, v[48:51] offset:27648
	s_waitcnt vmcnt(12)
	ds_write_b128 v104, v[56:59] offset:32256
	v_mfma_f32_32x32x16_bf16 a[48:63], v[158:161], v[150:153], a[48:63]
	s_waitcnt vmcnt(11)
	ds_write_b128 v105, v[110:113]
	s_waitcnt vmcnt(10)
	ds_write_b128 v105, v[114:117] offset:4608
	v_mfma_f32_32x32x16_bf16 a[32:47], v[162:165], v[150:153], a[32:47]
	s_waitcnt vmcnt(9)
	ds_write_b128 v105, v[118:121] offset:9216
	s_waitcnt vmcnt(8)
	ds_write_b128 v105, v[122:125] offset:13824
	v_mfma_f32_32x32x16_bf16 a[16:31], v[158:161], v[154:157], a[16:31]
	v_mfma_f32_32x32x16_bf16 a[0:15], v[162:165], v[154:157], a[0:15]
	ds_read_b128 v[0:3], v70 offset:36960
	ds_read_b128 v[8:11], v70 offset:41568
	ds_read_b128 v[16:19], v70 offset:46176
	ds_read_b128 v[24:27], v70 offset:50784
	ds_read_b128 v[32:35], v71 offset:18528
	ds_read_b128 v[40:43], v71 offset:23136
	s_waitcnt lgkmcnt(14)
	v_mfma_f32_32x32x16_bf16 a[112:127], v[166:169], v[126:129], a[112:127]
	global_load_dwordx4 v[110:113], v[86:87], off offset:640
	v_mfma_f32_32x32x16_bf16 a[96:111], v[170:173], v[126:129], a[96:111]
	global_load_dwordx4 v[114:117], v[84:85], off offset:640
	v_mfma_f32_32x32x16_bf16 a[80:95], v[166:169], v[130:133], a[80:95]
	global_load_dwordx4 v[118:121], v[82:83], off offset:640
	v_mfma_f32_32x32x16_bf16 a[64:79], v[170:173], v[130:133], a[64:79]
	global_load_dwordx4 v[122:125], v[80:81], off offset:640
	v_mfma_f32_32x32x16_bf16 a[48:63], v[166:169], v[134:137], a[48:63]
	v_mfma_f32_32x32x16_bf16 a[32:47], v[170:173], v[134:137], a[32:47]
	v_mfma_f32_32x32x16_bf16 a[16:31], v[166:169], v[138:141], a[16:31]
	v_mfma_f32_32x32x16_bf16 a[0:15], v[170:173], v[138:141], a[0:15]
	s_waitcnt lgkmcnt(0)
	s_barrier
; template <int TJ, bool SWAP, int NK, class Epi>
; DI void gemm_phase(const u16* __restrict__ A, size_t strideAz, int lda, const u16* __restrict__ Bt, size_t strideBz, int ldb,
;                    int Z, int Mt, int Nt, int GM, int K, char* smem, const Epi& epi, int vt) {
;     ...
;     for (int kt = 0; kt < NK; ++kt) {
;       constexpr int dummy = 0; (void)dummy;
;       const int u = kt & 1;
;       const u16* as = As + u * 256 * 72 + (128 * wm + r) * 72 + 8 * h;
;       const u16* bs = Bs + u * BN * 72 + (32 * TJ * wn + r) * 72 + 8 * h;
;       if (kt == 0) {
; #pragma unroll
;         for (int i = 0; i < 4; ++i) af[0][i] = *(const bf16x8*)(as + (32 * i) * 72);
; #pragma unroll
;         for (int j = 0; j < TJ; ++j) bfr[0][j] = *(const bf16x8*)(bs + (32 * j) * 72);
;       }
; #pragma unroll
;       for (int ks = 0; ks < 4; ++ks) {
;         if (ks < 3) {
; #pragma unroll
;           for (int i = 0; i < 4; ++i) af[(ks + 1) & 1][i] = *(const bf16x8*)(as + (32 * i) * 72 + 16 * (ks + 1));
; #pragma unroll
;           for (int j = 0; j < TJ; ++j) bfr[(ks + 1) & 1][j] = *(const bf16x8*)(bs + (32 * j) * 72 + 16 * (ks + 1));
;         } else if (kt + 1 < NK) {
;           const u16* asn = As + (u ^ 1) * 256 * 72 + (128 * wm + r) * 72 + 8 * h;
;           const u16* bsn = Bs + (u ^ 1) * BN * 72 + (32 * TJ * wn + r) * 72 + 8 * h;
; #pragma unroll
;           for (int i = 0; i < 4; ++i) af[0][i] = *(const bf16x8*)(asn + (32 * i) * 72);
; #pragma unroll
;           for (int j = 0; j < TJ; ++j) bfr[0][j] = *(const bf16x8*)(bsn + (32 * j) * 72);
;         }
;         __builtin_amdgcn_sched_barrier(0);
; #pragma unroll
;         for (int i = 0; i < 4; ++i)
; #pragma unroll
;           for (int j = 0; j < TJ; ++j)
;             acc[i][j] = SWAP ? MFMA32(bfr[ks & 1][j], af[ks & 1][i], acc[i][j]) : MFMA32(af[ks & 1][i], bfr[ks & 1][j], acc[i][j]);
;         if (ks == 0 && kt + 2 < NK) {
;           const u16* ag = Ag + (kt + 2) * 64;
; #pragma unroll
;           for (int i = 0; i < 8; ++i) ra[u][i] = *(const u32x4*)(ag + aoff[i]);
; #pragma unroll
;           for (int i = 0; i < 8; ++i) { __builtin_amdgcn_sched_group_barrier(0x008, 1, 0); __builtin_amdgcn_sched_group_barrier(0x020, 1, 0); }
;         }
;         if (ks == 2 && kt + 2 < NK) {
;           const u16* bg = Bg + (kt + 2) * 64;
; #pragma unroll
	ds_read_b128 v[48:51], v70
	ds_read_b128 v[56:59], v70 offset:4608
	ds_read_b128 v[126:129], v70 offset:9216
	ds_read_b128 v[130:133], v70 offset:13824
	ds_read_b128 v[134:137], v71
	ds_read_b128 v[138:141], v71 offset:4608
	v_mfma_f32_32x32x16_bf16 a[112:127], v[32:35], v[0:3], a[112:127]
	v_mfma_f32_32x32x16_bf16 a[96:111], v[40:43], v[0:3], a[96:111]
	v_mfma_f32_32x32x16_bf16 a[80:95], v[32:35], v[8:11], a[80:95]
	v_mfma_f32_32x32x16_bf16 a[64:79], v[40:43], v[8:11], a[64:79]
	v_mfma_f32_32x32x16_bf16 a[48:63], v[32:35], v[16:19], a[48:63]
	v_mfma_f32_32x32x16_bf16 a[32:47], v[40:43], v[16:19], a[32:47]
	v_mfma_f32_32x32x16_bf16 a[16:31], v[32:35], v[24:27], a[16:31]
	v_mfma_f32_32x32x16_bf16 a[0:15], v[40:43], v[24:27], a[0:15]
	ds_read_b128 v[142:145], v70 offset:32
	ds_read_b128 v[146:149], v70 offset:4640
	ds_read_b128 v[150:153], v70 offset:9248
	ds_read_b128 v[154:157], v70 offset:13856
	ds_read_b128 v[158:161], v71 offset:32
	ds_read_b128 v[162:165], v71 offset:4640
	s_waitcnt lgkmcnt(7)
	v_mfma_f32_32x32x16_bf16 a[112:127], v[134:137], v[48:51], a[112:127]
	global_load_dwordx4 v[0:3], v[102:103], off offset:768
	s_waitcnt lgkmcnt(6)
	v_mfma_f32_32x32x16_bf16 a[96:111], v[138:141], v[48:51], a[96:111]
	global_load_dwordx4 v[8:11], v[100:101], off offset:768
	v_mfma_f32_32x32x16_bf16 a[80:95], v[134:137], v[56:59], a[80:95]
	global_load_dwordx4 v[16:19], v[98:99], off offset:768
	v_mfma_f32_32x32x16_bf16 a[64:79], v[138:141], v[56:59], a[64:79]
	global_load_dwordx4 v[24:27], v[96:97], off offset:768
	v_mfma_f32_32x32x16_bf16 a[48:63], v[134:137], v[126:129], a[48:63]
	global_load_dwordx4 v[32:35], v[94:95], off offset:768
	v_mfma_f32_32x32x16_bf16 a[32:47], v[138:141], v[126:129], a[32:47]
	global_load_dwordx4 v[40:43], v[92:93], off offset:768
	v_mfma_f32_32x32x16_bf16 a[16:31], v[134:137], v[130:133], a[16:31]
	global_load_dwordx4 v[48:51], v[90:91], off offset:768
	v_mfma_f32_32x32x16_bf16 a[0:15], v[138:141], v[130:133], a[0:15]
	global_load_dwordx4 v[56:59], v[88:89], off offset:768
	ds_read_b128 v[126:129], v70 offset:64
	ds_read_b128 v[130:133], v70 offset:4672
	ds_read_b128 v[134:137], v70 offset:9280
	ds_read_b128 v[138:141], v70 offset:13888
	ds_read_b128 v[166:169], v71 offset:64
	ds_read_b128 v[170:173], v71 offset:4672
	s_waitcnt lgkmcnt(7)
	v_mfma_f32_32x32x16_bf16 a[112:127], v[158:161], v[142:145], a[112:127]
	s_waitcnt vmcnt(19)
	ds_write_b128 v104, v[4:7] offset:36864
	s_waitcnt vmcnt(18)
	ds_write_b128 v104, v[12:15] offset:41472
	s_waitcnt lgkmcnt(8)
	v_mfma_f32_32x32x16_bf16 a[96:111], v[162:165], v[142:145], a[96:111]
	s_waitcnt vmcnt(17)
	ds_write_b128 v104, v[20:23] offset:46080
	s_waitcnt vmcnt(16)
	ds_write_b128 v104, v[28:31] offset:50688
	v_mfma_f32_32x32x16_bf16 a[80:95], v[158:161], v[146:149], a[80:95]
	s_waitcnt vmcnt(15)
	ds_write_b128 v104, v[36:39] offset:55296
	s_waitcnt vmcnt(14)
	ds_write_b128 v104, v[44:47] offset:59904
	v_mfma_f32_32x32x16_bf16 a[64:79], v[162:165], v[146:149], a[64:79]
	s_waitcnt vmcnt(13)
	ds_write_b128 v104, v[52:55] offset:64512
	s_waitcnt vmcnt(12)
	ds_write_b128 v108, v[60:63]
	v_mfma_f32_32x32x16_bf16 a[48:63], v[158:161], v[150:153], a[48:63]
	s_waitcnt vmcnt(11)
	ds_write_b128 v105, v[110:113] offset:18432
	s_waitcnt vmcnt(10)
	ds_write_b128 v105, v[114:117] offset:23040
	v_mfma_f32_32x32x16_bf16 a[32:47], v[162:165], v[150:153], a[32:47]
	s_waitcnt vmcnt(9)
	ds_write_b128 v105, v[118:121] offset:27648
	s_waitcnt vmcnt(8)
	ds_write_b128 v105, v[122:125] offset:32256
	v_mfma_f32_32x32x16_bf16 a[16:31], v[158:161], v[154:157], a[16:31]
	v_mfma_f32_32x32x16_bf16 a[0:15], v[162:165], v[154:157], a[0:15]
	ds_read_b128 v[4:7], v70 offset:96
	ds_read_b128 v[12:15], v70 offset:4704
	ds_read_b128 v[20:23], v70 offset:9312
	ds_read_b128 v[28:31], v70 offset:13920
	ds_read_b128 v[36:39], v71 offset:96
	ds_read_b128 v[44:47], v71 offset:4704
	s_waitcnt lgkmcnt(14)
	v_mfma_f32_32x32x16_bf16 a[112:127], v[166:169], v[126:129], a[112:127]
	global_load_dwordx4 v[110:113], v[86:87], off offset:768
	v_mfma_f32_32x32x16_bf16 a[96:111], v[170:173], v[126:129], a[96:111]
	global_load_dwordx4 v[114:117], v[84:85], off offset:768
	v_mfma_f32_32x32x16_bf16 a[80:95], v[166:169], v[130:133], a[80:95]
	global_load_dwordx4 v[118:121], v[82:83], off offset:768
	v_mfma_f32_32x32x16_bf16 a[64:79], v[170:173], v[130:133], a[64:79]
	global_load_dwordx4 v[122:125], v[80:81], off offset:768
	v_mfma_f32_32x32x16_bf16 a[48:63], v[166:169], v[134:137], a[48:63]
	v_mfma_f32_32x32x16_bf16 a[32:47], v[170:173], v[134:137], a[32:47]
	v_mfma_f32_32x32x16_bf16 a[16:31], v[166:169], v[138:141], a[16:31]
	v_mfma_f32_32x32x16_bf16 a[0:15], v[170:173], v[138:141], a[0:15]
	s_waitcnt lgkmcnt(0)
	s_barrier
; template <int TJ, bool SWAP, int NK, class Epi>
; DI void gemm_phase(const u16* __restrict__ A, size_t strideAz, int lda, const u16* __restrict__ Bt, size_t strideBz, int ldb,
;                    int Z, int Mt, int Nt, int GM, int K, char* smem, const Epi& epi, int vt) {
;     ...
;     for (int kt = 0; kt < NK; ++kt) {
;       constexpr int dummy = 0; (void)dummy;
;       const int u = kt & 1;
;       const u16* as = As + u * 256 * 72 + (128 * wm + r) * 72 + 8 * h;
;       const u16* bs = Bs + u * BN * 72 + (32 * TJ * wn + r) * 72 + 8 * h;
;       if (kt == 0) {
; #pragma unroll
;         for (int i = 0; i < 4; ++i) af[0][i] = *(const bf16x8*)(as + (32 * i) * 72);
; #pragma unroll
;         for (int j = 0; j < TJ; ++j) bfr[0][j] = *(const bf16x8*)(bs + (32 * j) * 72);
;       }
; #pragma unroll
;       for (int ks = 0; ks < 4; ++ks) {
;         if (ks < 3) {
; #pragma unroll
;           for (int i = 0; i < 4; ++i) af[(ks + 1) & 1][i] = *(const bf16x8*)(as + (32 * i) * 72 + 16 * (ks + 1));
; #pragma unroll
;           for (int j = 0; j < TJ; ++j) bfr[(ks + 1) & 1][j] = *(const bf16x8*)(bs + (32 * j) * 72 + 16 * (ks + 1));
;         } else if (kt + 1 < NK) {
;           const u16* asn = As + (u ^ 1) * 256 * 72 + (128 * wm + r) * 72 + 8 * h;
;           const u16* bsn = Bs + (u ^ 1) * BN * 72 + (32 * TJ * wn + r) * 72 + 8 * h;
; #pragma unroll
;           for (int i = 0; i < 4; ++i) af[0][i] = *(const bf16x8*)(asn + (32 * i) * 72);
; #pragma unroll
;           for (int j = 0; j < TJ; ++j) bfr[0][j] = *(const bf16x8*)(bsn + (32 * j) * 72);
;         }
;         __builtin_amdgcn_sched_barrier(0);
; #pragma unroll
;         for (int i = 0; i < 4; ++i)
; #pragma unroll
;           for (int j = 0; j < TJ; ++j)
;             acc[i][j] = SWAP ? MFMA32(bfr[ks & 1][j], af[ks & 1][i], acc[i][j]) : MFMA32(af[ks & 1][i], bfr[ks & 1][j], acc[i][j]);
;         if (ks == 0 && kt + 2 < NK) {
;           const u16* ag = Ag + (kt + 2) * 64;
; #pragma unroll
;           for (int i = 0; i < 8; ++i) ra[u][i] = *(const u32x4*)(ag + aoff[i]);
; #pragma unroll
;           for (int i = 0; i < 8; ++i) { __builtin_amdgcn_sched_group_barrier(0x008, 1, 0); __builtin_amdgcn_sched_group_barrier(0x020, 1, 0); }
;         }
;         if (ks == 2 && kt + 2 < NK) {
;           const u16* bg = Bg + (kt + 2) * 64;
; #pragma unroll
	ds_read_b128 v[52:55], v70 offset:36864
	ds_read_b128 v[60:63], v70 offset:41472
	ds_read_b128 v[126:129], v70 offset:46080
	ds_read_b128 v[130:133], v70 offset:50688
	ds_read_b128 v[134:137], v71 offset:18432
	ds_read_b128 v[138:141], v71 offset:23040
	v_mfma_f32_32x32x16_bf16 a[112:127], v[36:39], v[4:7], a[112:127]
	v_mfma_f32_32x32x16_bf16 a[96:111], v[44:47], v[4:7], a[96:111]
	v_mfma_f32_32x32x16_bf16 a[80:95], v[36:39], v[12:15], a[80:95]
	v_mfma_f32_32x32x16_bf16 a[64:79], v[44:47], v[12:15], a[64:79]
	v_mfma_f32_32x32x16_bf16 a[48:63], v[36:39], v[20:23], a[48:63]
	v_mfma_f32_32x32x16_bf16 a[32:47], v[44:47], v[20:23], a[32:47]
	v_mfma_f32_32x32x16_bf16 a[16:31], v[36:39], v[28:31], a[16:31]
	v_mfma_f32_32x32x16_bf16 a[0:15], v[44:47], v[28:31], a[0:15]
	ds_read_b128 v[142:145], v70 offset:36896
	ds_read_b128 v[146:149], v70 offset:41504
	ds_read_b128 v[150:153], v70 offset:46112
	ds_read_b128 v[154:157], v70 offset:50720
	ds_read_b128 v[158:161], v71 offset:18464
	ds_read_b128 v[162:165], v71 offset:23072
	s_waitcnt lgkmcnt(7)
	v_mfma_f32_32x32x16_bf16 a[112:127], v[134:137], v[52:55], a[112:127]
	global_load_dwordx4 v[4:7], v[102:103], off offset:896
	s_waitcnt lgkmcnt(6)
	v_mfma_f32_32x32x16_bf16 a[96:111], v[138:141], v[52:55], a[96:111]
	global_load_dwordx4 v[12:15], v[100:101], off offset:896
	v_mfma_f32_32x32x16_bf16 a[80:95], v[134:137], v[60:63], a[80:95]
	global_load_dwordx4 v[20:23], v[98:99], off offset:896
	v_mfma_f32_32x32x16_bf16 a[64:79], v[138:141], v[60:63], a[64:79]
	global_load_dwordx4 v[28:31], v[96:97], off offset:896
	v_mfma_f32_32x32x16_bf16 a[48:63], v[134:137], v[126:129], a[48:63]
	global_load_dwordx4 v[36:39], v[94:95], off offset:896
	v_mfma_f32_32x32x16_bf16 a[32:47], v[138:141], v[126:129], a[32:47]
	global_load_dwordx4 v[44:47], v[92:93], off offset:896
	v_mfma_f32_32x32x16_bf16 a[16:31], v[134:137], v[130:133], a[16:31]
	global_load_dwordx4 v[52:55], v[90:91], off offset:896
	v_mfma_f32_32x32x16_bf16 a[0:15], v[138:141], v[130:133], a[0:15]
	global_load_dwordx4 v[60:63], v[88:89], off offset:896
	ds_read_b128 v[126:129], v70 offset:36928
	ds_read_b128 v[130:133], v70 offset:41536
	ds_read_b128 v[134:137], v70 offset:46144
	ds_read_b128 v[138:141], v70 offset:50752
	ds_read_b128 v[166:169], v71 offset:18496
	ds_read_b128 v[170:173], v71 offset:23104
	s_waitcnt lgkmcnt(7)
	v_mfma_f32_32x32x16_bf16 a[112:127], v[158:161], v[142:145], a[112:127]
	s_waitcnt vmcnt(19)
	ds_write_b128 v104, v[0:3]
	s_waitcnt vmcnt(18)
	ds_write_b128 v104, v[8:11] offset:4608
	s_waitcnt lgkmcnt(8)
	v_mfma_f32_32x32x16_bf16 a[96:111], v[162:165], v[142:145], a[96:111]
	s_waitcnt vmcnt(17)
	ds_write_b128 v104, v[16:19] offset:9216
	s_waitcnt vmcnt(16)
	ds_write_b128 v104, v[24:27] offset:13824
	v_mfma_f32_32x32x16_bf16 a[80:95], v[158:161], v[146:149], a[80:95]
	s_waitcnt vmcnt(15)
	ds_write_b128 v104, v[32:35] offset:18432
	s_waitcnt vmcnt(14)
	ds_write_b128 v104, v[40:43] offset:23040
	v_mfma_f32_32x32x16_bf16 a[64:79], v[162:165], v[146:149], a[64:79]
	s_waitcnt vmcnt(13)
	ds_write_b128 v104, v[48:51] offset:27648
	s_waitcnt vmcnt(12)
	ds_write_b128 v104, v[56:59] offset:32256
	v_mfma_f32_32x32x16_bf16 a[48:63], v[158:161], v[150:153], a[48:63]
	s_waitcnt vmcnt(11)
	ds_write_b128 v105, v[110:113]
	s_waitcnt vmcnt(10)
	ds_write_b128 v105, v[114:117] offset:4608
	v_mfma_f32_32x32x16_bf16 a[32:47], v[162:165], v[150:153], a[32:47]
	s_waitcnt vmcnt(9)
	ds_write_b128 v105, v[118:121] offset:9216
	s_waitcnt vmcnt(8)
	ds_write_b128 v105, v[122:125] offset:13824
	v_mfma_f32_32x32x16_bf16 a[16:31], v[158:161], v[154:157], a[16:31]
	v_mfma_f32_32x32x16_bf16 a[0:15], v[162:165], v[154:157], a[0:15]
	ds_read_b128 v[0:3], v70 offset:36960
	ds_read_b128 v[8:11], v70 offset:41568
	ds_read_b128 v[16:19], v70 offset:46176
	ds_read_b128 v[24:27], v70 offset:50784
	ds_read_b128 v[32:35], v71 offset:18528
	ds_read_b128 v[40:43], v71 offset:23136
	s_waitcnt lgkmcnt(14)
	v_mfma_f32_32x32x16_bf16 a[112:127], v[166:169], v[126:129], a[112:127]
	global_load_dwordx4 v[110:113], v[86:87], off offset:896
	v_mfma_f32_32x32x16_bf16 a[96:111], v[170:173], v[126:129], a[96:111]
	global_load_dwordx4 v[114:117], v[84:85], off offset:896
	v_mfma_f32_32x32x16_bf16 a[80:95], v[166:169], v[130:133], a[80:95]
	global_load_dwordx4 v[118:121], v[82:83], off offset:896
	v_mfma_f32_32x32x16_bf16 a[64:79], v[170:173], v[130:133], a[64:79]
	global_load_dwordx4 v[122:125], v[80:81], off offset:896
	v_mfma_f32_32x32x16_bf16 a[48:63], v[166:169], v[134:137], a[48:63]
	v_mfma_f32_32x32x16_bf16 a[32:47], v[170:173], v[134:137], a[32:47]
	v_mfma_f32_32x32x16_bf16 a[16:31], v[166:169], v[138:141], a[16:31]
	v_mfma_f32_32x32x16_bf16 a[0:15], v[170:173], v[138:141], a[0:15]
	s_waitcnt lgkmcnt(0)
	s_barrier
; template <int TJ, bool SWAP, int NK, class Epi>
; DI void gemm_phase(const u16* __restrict__ A, size_t strideAz, int lda, const u16* __restrict__ Bt, size_t strideBz, int ldb,
;                    int Z, int Mt, int Nt, int GM, int K, char* smem, const Epi& epi, int vt) {
;     ...
;     for (int kt = 0; kt < NK; ++kt) {
;       constexpr int dummy = 0; (void)dummy;
;       const int u = kt & 1;
;       const u16* as = As + u * 256 * 72 + (128 * wm + r) * 72 + 8 * h;
;       const u16* bs = Bs + u * BN * 72 + (32 * TJ * wn + r) * 72 + 8 * h;
;       if (kt == 0) {
; #pragma unroll
;         for (int i = 0; i < 4; ++i) af[0][i] = *(const bf16x8*)(as + (32 * i) * 72);
; #pragma unroll
;         for (int j = 0; j < TJ; ++j) bfr[0][j] = *(const bf16x8*)(bs + (32 * j) * 72);
;       }
; #pragma unroll
;       for (int ks = 0; ks < 4; ++ks) {
;         if (ks < 3) {
; #pragma unroll
;           for (int i = 0; i < 4; ++i) af[(ks + 1) & 1][i] = *(const bf16x8*)(as + (32 * i) * 72 + 16 * (ks + 1));
; #pragma unroll
;           for (int j = 0; j < TJ; ++j) bfr[(ks + 1) & 1][j] = *(const bf16x8*)(bs + (32 * j) * 72 + 16 * (ks + 1));
;         } else if (kt + 1 < NK) {
;           const u16* asn = As + (u ^ 1) * 256 * 72 + (128 * wm + r) * 72 + 8 * h;
;           const u16* bsn = Bs + (u ^ 1) * BN * 72 + (32 * TJ * wn + r) * 72 + 8 * h;
; #pragma unroll
;           for (int i = 0; i < 4; ++i) af[0][i] = *(const bf16x8*)(asn + (32 * i) * 72);
; #pragma unroll
;           for (int j = 0; j < TJ; ++j) bfr[0][j] = *(const bf16x8*)(bsn + (32 * j) * 72);
;         }
;         __builtin_amdgcn_sched_barrier(0);
; #pragma unroll
;         for (int i = 0; i < 4; ++i)
; #pragma unroll
;           for (int j = 0; j < TJ; ++j)
;             acc[i][j] = SWAP ? MFMA32(bfr[ks & 1][j], af[ks & 1][i], acc[i][j]) : MFMA32(af[ks & 1][i], bfr[ks & 1][j], acc[i][j]);
;         if (ks == 0 && kt + 2 < NK) {
;           const u16* ag = Ag + (kt + 2) * 64;
; #pragma unroll
;           for (int i = 0; i < 8; ++i) ra[u][i] = *(const u32x4*)(ag + aoff[i]);
; #pragma unroll
;           for (int i = 0; i < 8; ++i) { __builtin_amdgcn_sched_group_barrier(0x008, 1, 0); __builtin_amdgcn_sched_group_barrier(0x020, 1, 0); }
;         }
;         if (ks == 2 && kt + 2 < NK) {
;           const u16* bg = Bg + (kt + 2) * 64;
; #pragma unroll
	ds_read_b128 v[48:51], v70
	ds_read_b128 v[56:59], v70 offset:4608
	ds_read_b128 v[126:129], v70 offset:9216
	ds_read_b128 v[130:133], v70 offset:13824
	ds_read_b128 v[134:137], v71
	ds_read_b128 v[138:141], v71 offset:4608
	v_mfma_f32_32x32x16_bf16 a[112:127], v[32:35], v[0:3], a[112:127]
	v_mfma_f32_32x32x16_bf16 a[96:111], v[40:43], v[0:3], a[96:111]
	v_mfma_f32_32x32x16_bf16 a[80:95], v[32:35], v[8:11], a[80:95]
	v_mfma_f32_32x32x16_bf16 a[64:79], v[40:43], v[8:11], a[64:79]
	v_mfma_f32_32x32x16_bf16 a[48:63], v[32:35], v[16:19], a[48:63]
	v_mfma_f32_32x32x16_bf16 a[32:47], v[40:43], v[16:19], a[32:47]
	v_mfma_f32_32x32x16_bf16 a[16:31], v[32:35], v[24:27], a[16:31]
	v_mfma_f32_32x32x16_bf16 a[0:15], v[40:43], v[24:27], a[0:15]
	ds_read_b128 v[142:145], v70 offset:32
	ds_read_b128 v[146:149], v70 offset:4640
	ds_read_b128 v[150:153], v70 offset:9248
	ds_read_b128 v[154:157], v70 offset:13856
	ds_read_b128 v[158:161], v71 offset:32
	ds_read_b128 v[162:165], v71 offset:4640
	s_waitcnt lgkmcnt(7)
	v_mfma_f32_32x32x16_bf16 a[112:127], v[134:137], v[48:51], a[112:127]
	global_load_dwordx4 v[0:3], v[102:103], off offset:1024
	s_waitcnt lgkmcnt(6)
	v_mfma_f32_32x32x16_bf16 a[96:111], v[138:141], v[48:51], a[96:111]
	global_load_dwordx4 v[8:11], v[100:101], off offset:1024
	v_mfma_f32_32x32x16_bf16 a[80:95], v[134:137], v[56:59], a[80:95]
	global_load_dwordx4 v[16:19], v[98:99], off offset:1024
	v_mfma_f32_32x32x16_bf16 a[64:79], v[138:141], v[56:59], a[64:79]
	global_load_dwordx4 v[24:27], v[96:97], off offset:1024
	v_mfma_f32_32x32x16_bf16 a[48:63], v[134:137], v[126:129], a[48:63]
	global_load_dwordx4 v[32:35], v[94:95], off offset:1024
	v_mfma_f32_32x32x16_bf16 a[32:47], v[138:141], v[126:129], a[32:47]
	global_load_dwordx4 v[40:43], v[92:93], off offset:1024
	v_mfma_f32_32x32x16_bf16 a[16:31], v[134:137], v[130:133], a[16:31]
	global_load_dwordx4 v[48:51], v[90:91], off offset:1024
	v_mfma_f32_32x32x16_bf16 a[0:15], v[138:141], v[130:133], a[0:15]
	global_load_dwordx4 v[56:59], v[88:89], off offset:1024
	ds_read_b128 v[126:129], v70 offset:64
	ds_read_b128 v[130:133], v70 offset:4672
	ds_read_b128 v[134:137], v70 offset:9280
	ds_read_b128 v[138:141], v70 offset:13888
	ds_read_b128 v[166:169], v71 offset:64
	ds_read_b128 v[170:173], v71 offset:4672
	s_waitcnt lgkmcnt(7)
	v_mfma_f32_32x32x16_bf16 a[112:127], v[158:161], v[142:145], a[112:127]
	s_waitcnt vmcnt(19)
	ds_write_b128 v104, v[4:7] offset:36864
	s_waitcnt vmcnt(18)
	ds_write_b128 v104, v[12:15] offset:41472
	s_waitcnt lgkmcnt(8)
	v_mfma_f32_32x32x16_bf16 a[96:111], v[162:165], v[142:145], a[96:111]
	s_waitcnt vmcnt(17)
	ds_write_b128 v104, v[20:23] offset:46080
	s_waitcnt vmcnt(16)
	ds_write_b128 v104, v[28:31] offset:50688
	v_mfma_f32_32x32x16_bf16 a[80:95], v[158:161], v[146:149], a[80:95]
	s_waitcnt vmcnt(15)
	ds_write_b128 v104, v[36:39] offset:55296
	s_waitcnt vmcnt(14)
	ds_write_b128 v104, v[44:47] offset:59904
	v_mfma_f32_32x32x16_bf16 a[64:79], v[162:165], v[146:149], a[64:79]
	s_waitcnt vmcnt(13)
	ds_write_b128 v104, v[52:55] offset:64512
	s_waitcnt vmcnt(12)
	ds_write_b128 v108, v[60:63]
	v_mfma_f32_32x32x16_bf16 a[48:63], v[158:161], v[150:153], a[48:63]
	s_waitcnt vmcnt(11)
	ds_write_b128 v105, v[110:113] offset:18432
	s_waitcnt vmcnt(10)
	ds_write_b128 v105, v[114:117] offset:23040
	v_mfma_f32_32x32x16_bf16 a[32:47], v[162:165], v[150:153], a[32:47]
	s_waitcnt vmcnt(9)
	ds_write_b128 v105, v[118:121] offset:27648
	s_waitcnt vmcnt(8)
	ds_write_b128 v105, v[122:125] offset:32256
	v_mfma_f32_32x32x16_bf16 a[16:31], v[158:161], v[154:157], a[16:31]
	v_mfma_f32_32x32x16_bf16 a[0:15], v[162:165], v[154:157], a[0:15]
	ds_read_b128 v[4:7], v70 offset:96
	ds_read_b128 v[12:15], v70 offset:4704
	ds_read_b128 v[20:23], v70 offset:9312
	ds_read_b128 v[28:31], v70 offset:13920
	ds_read_b128 v[36:39], v71 offset:96
	ds_read_b128 v[44:47], v71 offset:4704
	s_waitcnt lgkmcnt(14)
	v_mfma_f32_32x32x16_bf16 a[112:127], v[166:169], v[126:129], a[112:127]
	global_load_dwordx4 v[110:113], v[86:87], off offset:1024
	v_mfma_f32_32x32x16_bf16 a[96:111], v[170:173], v[126:129], a[96:111]
	global_load_dwordx4 v[114:117], v[84:85], off offset:1024
	v_mfma_f32_32x32x16_bf16 a[80:95], v[166:169], v[130:133], a[80:95]
	global_load_dwordx4 v[118:121], v[82:83], off offset:1024
	v_mfma_f32_32x32x16_bf16 a[64:79], v[170:173], v[130:133], a[64:79]
	global_load_dwordx4 v[122:125], v[80:81], off offset:1024
	v_mfma_f32_32x32x16_bf16 a[48:63], v[166:169], v[134:137], a[48:63]
	v_mfma_f32_32x32x16_bf16 a[32:47], v[170:173], v[134:137], a[32:47]
	v_mfma_f32_32x32x16_bf16 a[16:31], v[166:169], v[138:141], a[16:31]
	v_mfma_f32_32x32x16_bf16 a[0:15], v[170:173], v[138:141], a[0:15]
	s_waitcnt lgkmcnt(0)
	s_barrier
; template <int TJ, bool SWAP, int NK, class Epi>
; DI void gemm_phase(const u16* __restrict__ A, size_t strideAz, int lda, const u16* __restrict__ Bt, size_t strideBz, int ldb,
;                    int Z, int Mt, int Nt, int GM, int K, char* smem, const Epi& epi, int vt) {
;     ...
;     for (int kt = 0; kt < NK; ++kt) {
;       constexpr int dummy = 0; (void)dummy;
;       const int u = kt & 1;
;       const u16* as = As + u * 256 * 72 + (128 * wm + r) * 72 + 8 * h;
;       const u16* bs = Bs + u * BN * 72 + (32 * TJ * wn + r) * 72 + 8 * h;
;       if (kt == 0) {
; #pragma unroll
;         for (int i = 0; i < 4; ++i) af[0][i] = *(const bf16x8*)(as + (32 * i) * 72);
; #pragma unroll
;         for (int j = 0; j < TJ; ++j) bfr[0][j] = *(const bf16x8*)(bs + (32 * j) * 72);
;       }
; #pragma unroll
;       for (int ks = 0; ks < 4; ++ks) {
;         if (ks < 3) {
; #pragma unroll
;           for (int i = 0; i < 4; ++i) af[(ks + 1) & 1][i] = *(const bf16x8*)(as + (32 * i) * 72 + 16 * (ks + 1));
; #pragma unroll
;           for (int j = 0; j < TJ; ++j) bfr[(ks + 1) & 1][j] = *(const bf16x8*)(bs + (32 * j) * 72 + 16 * (ks + 1));
;         } else if (kt + 1 < NK) {
;           const u16* asn = As + (u ^ 1) * 256 * 72 + (128 * wm + r) * 72 + 8 * h;
;           const u16* bsn = Bs + (u ^ 1) * BN * 72 + (32 * TJ * wn + r) * 72 + 8 * h;
; #pragma unroll
;           for (int i = 0; i < 4; ++i) af[0][i] = *(const bf16x8*)(asn + (32 * i) * 72);
; #pragma unroll
;           for (int j = 0; j < TJ; ++j) bfr[0][j] = *(const bf16x8*)(bsn + (32 * j) * 72);
;         }
;         __builtin_amdgcn_sched_barrier(0);
; #pragma unroll
;         for (int i = 0; i < 4; ++i)
; #pragma unroll
;           for (int j = 0; j < TJ; ++j)
;             acc[i][j] = SWAP ? MFMA32(bfr[ks & 1][j], af[ks & 1][i], acc[i][j]) : MFMA32(af[ks & 1][i], bfr[ks & 1][j], acc[i][j]);
;         if (ks == 0 && kt + 2 < NK) {
;           const u16* ag = Ag + (kt + 2) * 64;
; #pragma unroll
;           for (int i = 0; i < 8; ++i) ra[u][i] = *(const u32x4*)(ag + aoff[i]);
; #pragma unroll
;           for (int i = 0; i < 8; ++i) { __builtin_amdgcn_sched_group_barrier(0x008, 1, 0); __builtin_amdgcn_sched_group_barrier(0x020, 1, 0); }
;         }
;         if (ks == 2 && kt + 2 < NK) {
;           const u16* bg = Bg + (kt + 2) * 64;
; #pragma unroll
	ds_read_b128 v[52:55], v70 offset:36864
	ds_read_b128 v[60:63], v70 offset:41472
	ds_read_b128 v[126:129], v70 offset:46080
	ds_read_b128 v[130:133], v70 offset:50688
	ds_read_b128 v[134:137], v71 offset:18432
	ds_read_b128 v[138:141], v71 offset:23040
	v_mfma_f32_32x32x16_bf16 a[112:127], v[36:39], v[4:7], a[112:127]
	v_mfma_f32_32x32x16_bf16 a[96:111], v[44:47], v[4:7], a[96:111]
	v_mfma_f32_32x32x16_bf16 a[80:95], v[36:39], v[12:15], a[80:95]
	v_mfma_f32_32x32x16_bf16 a[64:79], v[44:47], v[12:15], a[64:79]
	v_mfma_f32_32x32x16_bf16 a[48:63], v[36:39], v[20:23], a[48:63]
	v_mfma_f32_32x32x16_bf16 a[32:47], v[44:47], v[20:23], a[32:47]
	v_mfma_f32_32x32x16_bf16 a[16:31], v[36:39], v[28:31], a[16:31]
	v_mfma_f32_32x32x16_bf16 a[0:15], v[44:47], v[28:31], a[0:15]
	ds_read_b128 v[142:145], v70 offset:36896
	ds_read_b128 v[146:149], v70 offset:41504
	ds_read_b128 v[150:153], v70 offset:46112
	ds_read_b128 v[154:157], v70 offset:50720
	ds_read_b128 v[158:161], v71 offset:18464
	ds_read_b128 v[162:165], v71 offset:23072
	s_waitcnt lgkmcnt(7)
	v_mfma_f32_32x32x16_bf16 a[112:127], v[134:137], v[52:55], a[112:127]
	global_load_dwordx4 v[4:7], v[102:103], off offset:1152
	s_waitcnt lgkmcnt(6)
	v_mfma_f32_32x32x16_bf16 a[96:111], v[138:141], v[52:55], a[96:111]
	global_load_dwordx4 v[12:15], v[100:101], off offset:1152
	v_mfma_f32_32x32x16_bf16 a[80:95], v[134:137], v[60:63], a[80:95]
	global_load_dwordx4 v[20:23], v[98:99], off offset:1152
	v_mfma_f32_32x32x16_bf16 a[64:79], v[138:141], v[60:63], a[64:79]
	global_load_dwordx4 v[28:31], v[96:97], off offset:1152
	v_mfma_f32_32x32x16_bf16 a[48:63], v[134:137], v[126:129], a[48:63]
	global_load_dwordx4 v[36:39], v[94:95], off offset:1152
	v_mfma_f32_32x32x16_bf16 a[32:47], v[138:141], v[126:129], a[32:47]
	global_load_dwordx4 v[44:47], v[92:93], off offset:1152
	v_mfma_f32_32x32x16_bf16 a[16:31], v[134:137], v[130:133], a[16:31]
	global_load_dwordx4 v[52:55], v[90:91], off offset:1152
	v_mfma_f32_32x32x16_bf16 a[0:15], v[138:141], v[130:133], a[0:15]
	global_load_dwordx4 v[60:63], v[88:89], off offset:1152
	ds_read_b128 v[126:129], v70 offset:36928
	ds_read_b128 v[130:133], v70 offset:41536
	ds_read_b128 v[134:137], v70 offset:46144
	ds_read_b128 v[138:141], v70 offset:50752
	ds_read_b128 v[166:169], v71 offset:18496
	ds_read_b128 v[170:173], v71 offset:23104
	s_waitcnt lgkmcnt(7)
	v_mfma_f32_32x32x16_bf16 a[112:127], v[158:161], v[142:145], a[112:127]
	s_waitcnt vmcnt(19)
	ds_write_b128 v104, v[0:3]
	s_waitcnt vmcnt(18)
	ds_write_b128 v104, v[8:11] offset:4608
	s_waitcnt lgkmcnt(8)
	v_mfma_f32_32x32x16_bf16 a[96:111], v[162:165], v[142:145], a[96:111]
	s_waitcnt vmcnt(17)
	ds_write_b128 v104, v[16:19] offset:9216
	s_waitcnt vmcnt(16)
	ds_write_b128 v104, v[24:27] offset:13824
	v_mfma_f32_32x32x16_bf16 a[80:95], v[158:161], v[146:149], a[80:95]
	s_waitcnt vmcnt(15)
	ds_write_b128 v104, v[32:35] offset:18432
	s_waitcnt vmcnt(14)
	ds_write_b128 v104, v[40:43] offset:23040
	v_mfma_f32_32x32x16_bf16 a[64:79], v[162:165], v[146:149], a[64:79]
	s_waitcnt vmcnt(13)
	ds_write_b128 v104, v[48:51] offset:27648
	s_waitcnt vmcnt(12)
	ds_write_b128 v104, v[56:59] offset:32256
	v_mfma_f32_32x32x16_bf16 a[48:63], v[158:161], v[150:153], a[48:63]
	s_waitcnt vmcnt(11)
	ds_write_b128 v105, v[110:113]
	s_waitcnt vmcnt(10)
	ds_write_b128 v105, v[114:117] offset:4608
	v_mfma_f32_32x32x16_bf16 a[32:47], v[162:165], v[150:153], a[32:47]
	s_waitcnt vmcnt(9)
	ds_write_b128 v105, v[118:121] offset:9216
	s_waitcnt vmcnt(8)
	ds_write_b128 v105, v[122:125] offset:13824
	v_mfma_f32_32x32x16_bf16 a[16:31], v[158:161], v[154:157], a[16:31]
	v_mfma_f32_32x32x16_bf16 a[0:15], v[162:165], v[154:157], a[0:15]
	ds_read_b128 v[0:3], v70 offset:36960
	ds_read_b128 v[8:11], v70 offset:41568
	ds_read_b128 v[16:19], v70 offset:46176
	ds_read_b128 v[24:27], v70 offset:50784
	ds_read_b128 v[32:35], v71 offset:18528
	ds_read_b128 v[40:43], v71 offset:23136
	s_waitcnt lgkmcnt(14)
	v_mfma_f32_32x32x16_bf16 a[112:127], v[166:169], v[126:129], a[112:127]
	global_load_dwordx4 v[110:113], v[86:87], off offset:1152
	v_mfma_f32_32x32x16_bf16 a[96:111], v[170:173], v[126:129], a[96:111]
	global_load_dwordx4 v[114:117], v[84:85], off offset:1152
	v_mfma_f32_32x32x16_bf16 a[80:95], v[166:169], v[130:133], a[80:95]
	global_load_dwordx4 v[118:121], v[82:83], off offset:1152
	v_mfma_f32_32x32x16_bf16 a[64:79], v[170:173], v[130:133], a[64:79]
	global_load_dwordx4 v[122:125], v[80:81], off offset:1152
	v_mfma_f32_32x32x16_bf16 a[48:63], v[166:169], v[134:137], a[48:63]
	v_mfma_f32_32x32x16_bf16 a[32:47], v[170:173], v[134:137], a[32:47]
	v_mfma_f32_32x32x16_bf16 a[16:31], v[166:169], v[138:141], a[16:31]
	v_mfma_f32_32x32x16_bf16 a[0:15], v[170:173], v[138:141], a[0:15]
	s_waitcnt lgkmcnt(0)
	s_barrier
; template <int TJ, bool SWAP, int NK, class Epi>
; DI void gemm_phase(const u16* __restrict__ A, size_t strideAz, int lda, const u16* __restrict__ Bt, size_t strideBz, int ldb,
;                    int Z, int Mt, int Nt, int GM, int K, char* smem, const Epi& epi, int vt) {
;     ...
;     for (int kt = 0; kt < NK; ++kt) {
;       constexpr int dummy = 0; (void)dummy;
;       const int u = kt & 1;
;       const u16* as = As + u * 256 * 72 + (128 * wm + r) * 72 + 8 * h;
;       const u16* bs = Bs + u * BN * 72 + (32 * TJ * wn + r) * 72 + 8 * h;
;       if (kt == 0) {
; #pragma unroll
;         for (int i = 0; i < 4; ++i) af[0][i] = *(const bf16x8*)(as + (32 * i) * 72);
; #pragma unroll
;         for (int j = 0; j < TJ; ++j) bfr[0][j] = *(const bf16x8*)(bs + (32 * j) * 72);
;       }
; #pragma unroll
;       for (int ks = 0; ks < 4; ++ks) {
;         if (ks < 3) {
; #pragma unroll
;           for (int i = 0; i < 4; ++i) af[(ks + 1) & 1][i] = *(const bf16x8*)(as + (32 * i) * 72 + 16 * (ks + 1));
; #pragma unroll
;           for (int j = 0; j < TJ; ++j) bfr[(ks + 1) & 1][j] = *(const bf16x8*)(bs + (32 * j) * 72 + 16 * (ks + 1));
;         } else if (kt + 1 < NK) {
;           const u16* asn = As + (u ^ 1) * 256 * 72 + (128 * wm + r) * 72 + 8 * h;
;           const u16* bsn = Bs + (u ^ 1) * BN * 72 + (32 * TJ * wn + r) * 72 + 8 * h;
; #pragma unroll
;           for (int i = 0; i < 4; ++i) af[0][i] = *(const bf16x8*)(asn + (32 * i) * 72);
; #pragma unroll
;           for (int j = 0; j < TJ; ++j) bfr[0][j] = *(const bf16x8*)(bsn + (32 * j) * 72);
;         }
;         __builtin_amdgcn_sched_barrier(0);
; #pragma unroll
;         for (int i = 0; i < 4; ++i)
; #pragma unroll
;           for (int j = 0; j < TJ; ++j)
;             acc[i][j] = SWAP ? MFMA32(bfr[ks & 1][j], af[ks & 1][i], acc[i][j]) : MFMA32(af[ks & 1][i], bfr[ks & 1][j], acc[i][j]);
;         if (ks == 0 && kt + 2 < NK) {
;           const u16* ag = Ag + (kt + 2) * 64;
; #pragma unroll
;           for (int i = 0; i < 8; ++i) ra[u][i] = *(const u32x4*)(ag + aoff[i]);
; #pragma unroll
;           for (int i = 0; i < 8; ++i) { __builtin_amdgcn_sched_group_barrier(0x008, 1, 0); __builtin_amdgcn_sched_group_barrier(0x020, 1, 0); }
;         }
;         if (ks == 2 && kt + 2 < NK) {
;           const u16* bg = Bg + (kt + 2) * 64;
; #pragma unroll
	ds_read_b128 v[48:51], v70
	ds_read_b128 v[56:59], v70 offset:4608
	ds_read_b128 v[126:129], v70 offset:9216
	ds_read_b128 v[130:133], v70 offset:13824
	ds_read_b128 v[134:137], v71
	ds_read_b128 v[138:141], v71 offset:4608
	v_mfma_f32_32x32x16_bf16 a[112:127], v[32:35], v[0:3], a[112:127]
	v_mfma_f32_32x32x16_bf16 a[96:111], v[40:43], v[0:3], a[96:111]
	v_mfma_f32_32x32x16_bf16 a[80:95], v[32:35], v[8:11], a[80:95]
	v_mfma_f32_32x32x16_bf16 a[64:79], v[40:43], v[8:11], a[64:79]
	v_mfma_f32_32x32x16_bf16 a[48:63], v[32:35], v[16:19], a[48:63]
	v_mfma_f32_32x32x16_bf16 a[32:47], v[40:43], v[16:19], a[32:47]
	v_mfma_f32_32x32x16_bf16 a[16:31], v[32:35], v[24:27], a[16:31]
	v_mfma_f32_32x32x16_bf16 a[0:15], v[40:43], v[24:27], a[0:15]
	ds_read_b128 v[142:145], v70 offset:32
	ds_read_b128 v[146:149], v70 offset:4640
	ds_read_b128 v[150:153], v70 offset:9248
	ds_read_b128 v[154:157], v70 offset:13856
	ds_read_b128 v[158:161], v71 offset:32
	ds_read_b128 v[162:165], v71 offset:4640
	s_waitcnt lgkmcnt(7)
	v_mfma_f32_32x32x16_bf16 a[112:127], v[134:137], v[48:51], a[112:127]
	global_load_dwordx4 v[0:3], v[102:103], off offset:1280
	s_waitcnt lgkmcnt(6)
	v_mfma_f32_32x32x16_bf16 a[96:111], v[138:141], v[48:51], a[96:111]
	global_load_dwordx4 v[8:11], v[100:101], off offset:1280
	v_mfma_f32_32x32x16_bf16 a[80:95], v[134:137], v[56:59], a[80:95]
	global_load_dwordx4 v[16:19], v[98:99], off offset:1280
	v_mfma_f32_32x32x16_bf16 a[64:79], v[138:141], v[56:59], a[64:79]
	global_load_dwordx4 v[24:27], v[96:97], off offset:1280
	v_mfma_f32_32x32x16_bf16 a[48:63], v[134:137], v[126:129], a[48:63]
	global_load_dwordx4 v[32:35], v[94:95], off offset:1280
	v_mfma_f32_32x32x16_bf16 a[32:47], v[138:141], v[126:129], a[32:47]
	global_load_dwordx4 v[40:43], v[92:93], off offset:1280
	v_mfma_f32_32x32x16_bf16 a[16:31], v[134:137], v[130:133], a[16:31]
	global_load_dwordx4 v[48:51], v[90:91], off offset:1280
	v_mfma_f32_32x32x16_bf16 a[0:15], v[138:141], v[130:133], a[0:15]
	global_load_dwordx4 v[56:59], v[88:89], off offset:1280
	ds_read_b128 v[126:129], v70 offset:64
	ds_read_b128 v[130:133], v70 offset:4672
	ds_read_b128 v[134:137], v70 offset:9280
	ds_read_b128 v[138:141], v70 offset:13888
	ds_read_b128 v[166:169], v71 offset:64
	ds_read_b128 v[170:173], v71 offset:4672
	s_waitcnt lgkmcnt(7)
	v_mfma_f32_32x32x16_bf16 a[112:127], v[158:161], v[142:145], a[112:127]
	s_waitcnt vmcnt(19)
	ds_write_b128 v104, v[4:7] offset:36864
	s_waitcnt vmcnt(18)
	ds_write_b128 v104, v[12:15] offset:41472
	s_waitcnt lgkmcnt(8)
	v_mfma_f32_32x32x16_bf16 a[96:111], v[162:165], v[142:145], a[96:111]
	s_waitcnt vmcnt(17)
	ds_write_b128 v104, v[20:23] offset:46080
	s_waitcnt vmcnt(16)
	ds_write_b128 v104, v[28:31] offset:50688
	v_mfma_f32_32x32x16_bf16 a[80:95], v[158:161], v[146:149], a[80:95]
	s_waitcnt vmcnt(15)
	ds_write_b128 v104, v[36:39] offset:55296
	s_waitcnt vmcnt(14)
	ds_write_b128 v104, v[44:47] offset:59904
	v_mfma_f32_32x32x16_bf16 a[64:79], v[162:165], v[146:149], a[64:79]
	s_waitcnt vmcnt(13)
	ds_write_b128 v104, v[52:55] offset:64512
	s_waitcnt vmcnt(12)
	ds_write_b128 v108, v[60:63]
	v_mfma_f32_32x32x16_bf16 a[48:63], v[158:161], v[150:153], a[48:63]
	s_waitcnt vmcnt(11)
	ds_write_b128 v105, v[110:113] offset:18432
	s_waitcnt vmcnt(10)
	ds_write_b128 v105, v[114:117] offset:23040
	v_mfma_f32_32x32x16_bf16 a[32:47], v[162:165], v[150:153], a[32:47]
	s_waitcnt vmcnt(9)
	ds_write_b128 v105, v[118:121] offset:27648
	s_waitcnt vmcnt(8)
	ds_write_b128 v105, v[122:125] offset:32256
	v_mfma_f32_32x32x16_bf16 a[16:31], v[158:161], v[154:157], a[16:31]
	v_mfma_f32_32x32x16_bf16 a[0:15], v[162:165], v[154:157], a[0:15]
	ds_read_b128 v[4:7], v70 offset:96
	ds_read_b128 v[12:15], v70 offset:4704
	ds_read_b128 v[20:23], v70 offset:9312
	ds_read_b128 v[28:31], v70 offset:13920
	ds_read_b128 v[36:39], v71 offset:96
	ds_read_b128 v[44:47], v71 offset:4704
	s_waitcnt lgkmcnt(14)
	v_mfma_f32_32x32x16_bf16 a[112:127], v[166:169], v[126:129], a[112:127]
	global_load_dwordx4 v[110:113], v[86:87], off offset:1280
	v_mfma_f32_32x32x16_bf16 a[96:111], v[170:173], v[126:129], a[96:111]
	global_load_dwordx4 v[114:117], v[84:85], off offset:1280
	v_mfma_f32_32x32x16_bf16 a[80:95], v[166:169], v[130:133], a[80:95]
	global_load_dwordx4 v[118:121], v[82:83], off offset:1280
	v_mfma_f32_32x32x16_bf16 a[64:79], v[170:173], v[130:133], a[64:79]
	global_load_dwordx4 v[122:125], v[80:81], off offset:1280
	v_mfma_f32_32x32x16_bf16 a[48:63], v[166:169], v[134:137], a[48:63]
	v_mfma_f32_32x32x16_bf16 a[32:47], v[170:173], v[134:137], a[32:47]
	v_mfma_f32_32x32x16_bf16 a[16:31], v[166:169], v[138:141], a[16:31]
	v_mfma_f32_32x32x16_bf16 a[0:15], v[170:173], v[138:141], a[0:15]
	s_waitcnt lgkmcnt(0)
	s_barrier
; template <int TJ, bool SWAP, int NK, class Epi>
; DI void gemm_phase(const u16* __restrict__ A, size_t strideAz, int lda, const u16* __restrict__ Bt, size_t strideBz, int ldb,
;                    int Z, int Mt, int Nt, int GM, int K, char* smem, const Epi& epi, int vt) {
;     ...
;     for (int kt = 0; kt < NK; ++kt) {
;       constexpr int dummy = 0; (void)dummy;
;       const int u = kt & 1;
;       const u16* as = As + u * 256 * 72 + (128 * wm + r) * 72 + 8 * h;
;       const u16* bs = Bs + u * BN * 72 + (32 * TJ * wn + r) * 72 + 8 * h;
;       if (kt == 0) {
; #pragma unroll
;         for (int i = 0; i < 4; ++i) af[0][i] = *(const bf16x8*)(as + (32 * i) * 72);
; #pragma unroll
;         for (int j = 0; j < TJ; ++j) bfr[0][j] = *(const bf16x8*)(bs + (32 * j) * 72);
;       }
; #pragma unroll
;       for (int ks = 0; ks < 4; ++ks) {
;         if (ks < 3) {
; #pragma unroll
;           for (int i = 0; i < 4; ++i) af[(ks + 1) & 1][i] = *(const bf16x8*)(as + (32 * i) * 72 + 16 * (ks + 1));
; #pragma unroll
;           for (int j = 0; j < TJ; ++j) bfr[(ks + 1) & 1][j] = *(const bf16x8*)(bs + (32 * j) * 72 + 16 * (ks + 1));
;         } else if (kt + 1 < NK) {
;           const u16* asn = As + (u ^ 1) * 256 * 72 + (128 * wm + r) * 72 + 8 * h;
;           const u16* bsn = Bs + (u ^ 1) * BN * 72 + (32 * TJ * wn + r) * 72 + 8 * h;
; #pragma unroll
;           for (int i = 0; i < 4; ++i) af[0][i] = *(const bf16x8*)(asn + (32 * i) * 72);
; #pragma unroll
;           for (int j = 0; j < TJ; ++j) bfr[0][j] = *(const bf16x8*)(bsn + (32 * j) * 72);
;         }
;         __builtin_amdgcn_sched_barrier(0);
; #pragma unroll
;         for (int i = 0; i < 4; ++i)
; #pragma unroll
;           for (int j = 0; j < TJ; ++j)
;             acc[i][j] = SWAP ? MFMA32(bfr[ks & 1][j], af[ks & 1][i], acc[i][j]) : MFMA32(af[ks & 1][i], bfr[ks & 1][j], acc[i][j]);
;         if (ks == 0 && kt + 2 < NK) {
;           const u16* ag = Ag + (kt + 2) * 64;
; #pragma unroll
;           for (int i = 0; i < 8; ++i) ra[u][i] = *(const u32x4*)(ag + aoff[i]);
; #pragma unroll
;           for (int i = 0; i < 8; ++i) { __builtin_amdgcn_sched_group_barrier(0x008, 1, 0); __builtin_amdgcn_sched_group_barrier(0x020, 1, 0); }
;         }
;         if (ks == 2 && kt + 2 < NK) {
;           const u16* bg = Bg + (kt + 2) * 64;
; #pragma unroll
	ds_read_b128 v[52:55], v70 offset:36864
	ds_read_b128 v[60:63], v70 offset:41472
	ds_read_b128 v[126:129], v70 offset:46080
	ds_read_b128 v[130:133], v70 offset:50688
	ds_read_b128 v[134:137], v71 offset:18432
	ds_read_b128 v[138:141], v71 offset:23040
	v_mfma_f32_32x32x16_bf16 a[112:127], v[36:39], v[4:7], a[112:127]
	v_mfma_f32_32x32x16_bf16 a[96:111], v[44:47], v[4:7], a[96:111]
	v_mfma_f32_32x32x16_bf16 a[80:95], v[36:39], v[12:15], a[80:95]
	v_mfma_f32_32x32x16_bf16 a[64:79], v[44:47], v[12:15], a[64:79]
	v_mfma_f32_32x32x16_bf16 a[48:63], v[36:39], v[20:23], a[48:63]
	v_mfma_f32_32x32x16_bf16 a[32:47], v[44:47], v[20:23], a[32:47]
	v_mfma_f32_32x32x16_bf16 a[16:31], v[36:39], v[28:31], a[16:31]
	v_mfma_f32_32x32x16_bf16 a[0:15], v[44:47], v[28:31], a[0:15]
	ds_read_b128 v[142:145], v70 offset:36896
	ds_read_b128 v[146:149], v70 offset:41504
	ds_read_b128 v[150:153], v70 offset:46112
	ds_read_b128 v[154:157], v70 offset:50720
	ds_read_b128 v[158:161], v71 offset:18464
	ds_read_b128 v[162:165], v71 offset:23072
	s_waitcnt lgkmcnt(7)
	v_mfma_f32_32x32x16_bf16 a[112:127], v[134:137], v[52:55], a[112:127]
	global_load_dwordx4 v[4:7], v[102:103], off offset:1408
	s_waitcnt lgkmcnt(6)
	v_mfma_f32_32x32x16_bf16 a[96:111], v[138:141], v[52:55], a[96:111]
	global_load_dwordx4 v[12:15], v[100:101], off offset:1408
	v_mfma_f32_32x32x16_bf16 a[80:95], v[134:137], v[60:63], a[80:95]
	global_load_dwordx4 v[20:23], v[98:99], off offset:1408
	v_mfma_f32_32x32x16_bf16 a[64:79], v[138:141], v[60:63], a[64:79]
	global_load_dwordx4 v[28:31], v[96:97], off offset:1408
	v_mfma_f32_32x32x16_bf16 a[48:63], v[134:137], v[126:129], a[48:63]
	global_load_dwordx4 v[36:39], v[94:95], off offset:1408
	v_mfma_f32_32x32x16_bf16 a[32:47], v[138:141], v[126:129], a[32:47]
	global_load_dwordx4 v[44:47], v[92:93], off offset:1408
	v_mfma_f32_32x32x16_bf16 a[16:31], v[134:137], v[130:133], a[16:31]
	global_load_dwordx4 v[52:55], v[90:91], off offset:1408
	v_mfma_f32_32x32x16_bf16 a[0:15], v[138:141], v[130:133], a[0:15]
	global_load_dwordx4 v[60:63], v[88:89], off offset:1408
	ds_read_b128 v[126:129], v70 offset:36928
	ds_read_b128 v[130:133], v70 offset:41536
	ds_read_b128 v[134:137], v70 offset:46144
	ds_read_b128 v[138:141], v70 offset:50752
	ds_read_b128 v[166:169], v71 offset:18496
	ds_read_b128 v[170:173], v71 offset:23104
	s_waitcnt lgkmcnt(7)
	v_mfma_f32_32x32x16_bf16 a[112:127], v[158:161], v[142:145], a[112:127]
	s_waitcnt vmcnt(19)
	ds_write_b128 v104, v[0:3]
	s_waitcnt vmcnt(18)
	ds_write_b128 v104, v[8:11] offset:4608
	s_waitcnt lgkmcnt(8)
	v_mfma_f32_32x32x16_bf16 a[96:111], v[162:165], v[142:145], a[96:111]
	s_waitcnt vmcnt(17)
	ds_write_b128 v104, v[16:19] offset:9216
	s_waitcnt vmcnt(16)
	ds_write_b128 v104, v[24:27] offset:13824
	v_mfma_f32_32x32x16_bf16 a[80:95], v[158:161], v[146:149], a[80:95]
	s_waitcnt vmcnt(15)
	ds_write_b128 v104, v[32:35] offset:18432
	s_waitcnt vmcnt(14)
	ds_write_b128 v104, v[40:43] offset:23040
	v_mfma_f32_32x32x16_bf16 a[64:79], v[162:165], v[146:149], a[64:79]
	s_waitcnt vmcnt(13)
	ds_write_b128 v104, v[48:51] offset:27648
	s_waitcnt vmcnt(12)
	ds_write_b128 v104, v[56:59] offset:32256
	v_mfma_f32_32x32x16_bf16 a[48:63], v[158:161], v[150:153], a[48:63]
	s_waitcnt vmcnt(11)
	ds_write_b128 v105, v[110:113]
	s_waitcnt vmcnt(10)
	ds_write_b128 v105, v[114:117] offset:4608
	v_mfma_f32_32x32x16_bf16 a[32:47], v[162:165], v[150:153], a[32:47]
	s_waitcnt vmcnt(9)
	ds_write_b128 v105, v[118:121] offset:9216
	s_waitcnt vmcnt(8)
	ds_write_b128 v105, v[122:125] offset:13824
	v_mfma_f32_32x32x16_bf16 a[16:31], v[158:161], v[154:157], a[16:31]
	v_mfma_f32_32x32x16_bf16 a[0:15], v[162:165], v[154:157], a[0:15]
	ds_read_b128 v[0:3], v70 offset:36960
	ds_read_b128 v[8:11], v70 offset:41568
	ds_read_b128 v[16:19], v70 offset:46176
	ds_read_b128 v[24:27], v70 offset:50784
	ds_read_b128 v[32:35], v71 offset:18528
	ds_read_b128 v[40:43], v71 offset:23136
	s_waitcnt lgkmcnt(14)
	v_mfma_f32_32x32x16_bf16 a[112:127], v[166:169], v[126:129], a[112:127]
	global_load_dwordx4 v[110:113], v[86:87], off offset:1408
	v_mfma_f32_32x32x16_bf16 a[96:111], v[170:173], v[126:129], a[96:111]
	global_load_dwordx4 v[114:117], v[84:85], off offset:1408
	v_mfma_f32_32x32x16_bf16 a[80:95], v[166:169], v[130:133], a[80:95]
	global_load_dwordx4 v[118:121], v[82:83], off offset:1408
	v_mfma_f32_32x32x16_bf16 a[64:79], v[170:173], v[130:133], a[64:79]
	global_load_dwordx4 v[122:125], v[80:81], off offset:1408
	v_mfma_f32_32x32x16_bf16 a[48:63], v[166:169], v[134:137], a[48:63]
	v_mfma_f32_32x32x16_bf16 a[32:47], v[170:173], v[134:137], a[32:47]
	v_mfma_f32_32x32x16_bf16 a[16:31], v[166:169], v[138:141], a[16:31]
	v_mfma_f32_32x32x16_bf16 a[0:15], v[170:173], v[138:141], a[0:15]
	s_waitcnt lgkmcnt(0)
	s_barrier
; template <int TJ, bool SWAP, int NK, class Epi>
; DI void gemm_phase(const u16* __restrict__ A, size_t strideAz, int lda, const u16* __restrict__ Bt, size_t strideBz, int ldb,
;                    int Z, int Mt, int Nt, int GM, int K, char* smem, const Epi& epi, int vt) {
;     ...
;     for (int kt = 0; kt < NK; ++kt) {
;       constexpr int dummy = 0; (void)dummy;
;       const int u = kt & 1;
;       const u16* as = As + u * 256 * 72 + (128 * wm + r) * 72 + 8 * h;
;       const u16* bs = Bs + u * BN * 72 + (32 * TJ * wn + r) * 72 + 8 * h;
;       if (kt == 0) {
; #pragma unroll
;         for (int i = 0; i < 4; ++i) af[0][i] = *(const bf16x8*)(as + (32 * i) * 72);
; #pragma unroll
;         for (int j = 0; j < TJ; ++j) bfr[0][j] = *(const bf16x8*)(bs + (32 * j) * 72);
;       }
; #pragma unroll
;       for (int ks = 0; ks < 4; ++ks) {
;         if (ks < 3) {
; #pragma unroll
;           for (int i = 0; i < 4; ++i) af[(ks + 1) & 1][i] = *(const bf16x8*)(as + (32 * i) * 72 + 16 * (ks + 1));
; #pragma unroll
;           for (int j = 0; j < TJ; ++j) bfr[(ks + 1) & 1][j] = *(const bf16x8*)(bs + (32 * j) * 72 + 16 * (ks + 1));
;         } else if (kt + 1 < NK) {
;           const u16* asn = As + (u ^ 1) * 256 * 72 + (128 * wm + r) * 72 + 8 * h;
;           const u16* bsn = Bs + (u ^ 1) * BN * 72 + (32 * TJ * wn + r) * 72 + 8 * h;
; #pragma unroll
;           for (int i = 0; i < 4; ++i) af[0][i] = *(const bf16x8*)(asn + (32 * i) * 72);
; #pragma unroll
;           for (int j = 0; j < TJ; ++j) bfr[0][j] = *(const bf16x8*)(bsn + (32 * j) * 72);
;         }
;         __builtin_amdgcn_sched_barrier(0);
; #pragma unroll
;         for (int i = 0; i < 4; ++i)
; #pragma unroll
;           for (int j = 0; j < TJ; ++j)
;             acc[i][j] = SWAP ? MFMA32(bfr[ks & 1][j], af[ks & 1][i], acc[i][j]) : MFMA32(af[ks & 1][i], bfr[ks & 1][j], acc[i][j]);
;         if (ks == 0 && kt + 2 < NK) {
;           const u16* ag = Ag + (kt + 2) * 64;
; #pragma unroll
;           for (int i = 0; i < 8; ++i) ra[u][i] = *(const u32x4*)(ag + aoff[i]);
; #pragma unroll
;           for (int i = 0; i < 8; ++i) { __builtin_amdgcn_sched_group_barrier(0x008, 1, 0); __builtin_amdgcn_sched_group_barrier(0x020, 1, 0); }
;         }
;         if (ks == 2 && kt + 2 < NK) {
;           const u16* bg = Bg + (kt + 2) * 64;
; #pragma unroll
	ds_read_b128 v[48:51], v70
	ds_read_b128 v[56:59], v70 offset:4608
	ds_read_b128 v[126:129], v70 offset:9216
	ds_read_b128 v[130:133], v70 offset:13824
	ds_read_b128 v[134:137], v71
	ds_read_b128 v[138:141], v71 offset:4608
	v_mfma_f32_32x32x16_bf16 a[112:127], v[32:35], v[0:3], a[112:127]
	v_mfma_f32_32x32x16_bf16 a[96:111], v[40:43], v[0:3], a[96:111]
	v_mfma_f32_32x32x16_bf16 a[80:95], v[32:35], v[8:11], a[80:95]
	v_mfma_f32_32x32x16_bf16 a[64:79], v[40:43], v[8:11], a[64:79]
	v_mfma_f32_32x32x16_bf16 a[48:63], v[32:35], v[16:19], a[48:63]
	v_mfma_f32_32x32x16_bf16 a[32:47], v[40:43], v[16:19], a[32:47]
	v_mfma_f32_32x32x16_bf16 a[16:31], v[32:35], v[24:27], a[16:31]
	v_mfma_f32_32x32x16_bf16 a[0:15], v[40:43], v[24:27], a[0:15]
	ds_read_b128 v[142:145], v70 offset:32
	ds_read_b128 v[146:149], v70 offset:4640
	ds_read_b128 v[150:153], v70 offset:9248
	ds_read_b128 v[154:157], v70 offset:13856
	ds_read_b128 v[158:161], v71 offset:32
	ds_read_b128 v[162:165], v71 offset:4640
	s_waitcnt lgkmcnt(7)
	v_mfma_f32_32x32x16_bf16 a[112:127], v[134:137], v[48:51], a[112:127]
	global_load_dwordx4 v[0:3], v[102:103], off offset:1536
	s_waitcnt lgkmcnt(6)
	v_mfma_f32_32x32x16_bf16 a[96:111], v[138:141], v[48:51], a[96:111]
	global_load_dwordx4 v[8:11], v[100:101], off offset:1536
	v_mfma_f32_32x32x16_bf16 a[80:95], v[134:137], v[56:59], a[80:95]
	global_load_dwordx4 v[16:19], v[98:99], off offset:1536
	v_mfma_f32_32x32x16_bf16 a[64:79], v[138:141], v[56:59], a[64:79]
	global_load_dwordx4 v[24:27], v[96:97], off offset:1536
	v_mfma_f32_32x32x16_bf16 a[48:63], v[134:137], v[126:129], a[48:63]
	global_load_dwordx4 v[32:35], v[94:95], off offset:1536
	v_mfma_f32_32x32x16_bf16 a[32:47], v[138:141], v[126:129], a[32:47]
	global_load_dwordx4 v[40:43], v[92:93], off offset:1536
	v_mfma_f32_32x32x16_bf16 a[16:31], v[134:137], v[130:133], a[16:31]
	global_load_dwordx4 v[48:51], v[90:91], off offset:1536
	v_mfma_f32_32x32x16_bf16 a[0:15], v[138:141], v[130:133], a[0:15]
	global_load_dwordx4 v[56:59], v[88:89], off offset:1536
	ds_read_b128 v[126:129], v70 offset:64
	ds_read_b128 v[130:133], v70 offset:4672
	ds_read_b128 v[134:137], v70 offset:9280
	ds_read_b128 v[138:141], v70 offset:13888
	ds_read_b128 v[166:169], v71 offset:64
	ds_read_b128 v[170:173], v71 offset:4672
	s_waitcnt lgkmcnt(7)
	v_mfma_f32_32x32x16_bf16 a[112:127], v[158:161], v[142:145], a[112:127]
	s_waitcnt vmcnt(19)
	ds_write_b128 v104, v[4:7] offset:36864
	s_waitcnt vmcnt(18)
	ds_write_b128 v104, v[12:15] offset:41472
	s_waitcnt lgkmcnt(8)
	v_mfma_f32_32x32x16_bf16 a[96:111], v[162:165], v[142:145], a[96:111]
	s_waitcnt vmcnt(17)
	ds_write_b128 v104, v[20:23] offset:46080
	s_waitcnt vmcnt(16)
	ds_write_b128 v104, v[28:31] offset:50688
	v_mfma_f32_32x32x16_bf16 a[80:95], v[158:161], v[146:149], a[80:95]
	s_waitcnt vmcnt(15)
	ds_write_b128 v104, v[36:39] offset:55296
	s_waitcnt vmcnt(14)
	ds_write_b128 v104, v[44:47] offset:59904
	v_mfma_f32_32x32x16_bf16 a[64:79], v[162:165], v[146:149], a[64:79]
	s_waitcnt vmcnt(13)
	ds_write_b128 v104, v[52:55] offset:64512
	s_waitcnt vmcnt(12)
	ds_write_b128 v108, v[60:63]
	v_mfma_f32_32x32x16_bf16 a[48:63], v[158:161], v[150:153], a[48:63]
	s_waitcnt vmcnt(11)
	ds_write_b128 v105, v[110:113] offset:18432
	s_waitcnt vmcnt(10)
	ds_write_b128 v105, v[114:117] offset:23040
	v_mfma_f32_32x32x16_bf16 a[32:47], v[162:165], v[150:153], a[32:47]
	s_waitcnt vmcnt(9)
	ds_write_b128 v105, v[118:121] offset:27648
	s_waitcnt vmcnt(8)
	ds_write_b128 v105, v[122:125] offset:32256
	v_mfma_f32_32x32x16_bf16 a[16:31], v[158:161], v[154:157], a[16:31]
	v_mfma_f32_32x32x16_bf16 a[0:15], v[162:165], v[154:157], a[0:15]
	ds_read_b128 v[4:7], v70 offset:96
	ds_read_b128 v[12:15], v70 offset:4704
	ds_read_b128 v[20:23], v70 offset:9312
	ds_read_b128 v[28:31], v70 offset:13920
	ds_read_b128 v[36:39], v71 offset:96
	ds_read_b128 v[44:47], v71 offset:4704
	s_waitcnt lgkmcnt(14)
	v_mfma_f32_32x32x16_bf16 a[112:127], v[166:169], v[126:129], a[112:127]
	global_load_dwordx4 v[110:113], v[86:87], off offset:1536
	v_mfma_f32_32x32x16_bf16 a[96:111], v[170:173], v[126:129], a[96:111]
	global_load_dwordx4 v[114:117], v[84:85], off offset:1536
	v_mfma_f32_32x32x16_bf16 a[80:95], v[166:169], v[130:133], a[80:95]
	global_load_dwordx4 v[118:121], v[82:83], off offset:1536
	v_mfma_f32_32x32x16_bf16 a[64:79], v[170:173], v[130:133], a[64:79]
	global_load_dwordx4 v[122:125], v[80:81], off offset:1536
	v_mfma_f32_32x32x16_bf16 a[48:63], v[166:169], v[134:137], a[48:63]
	v_mfma_f32_32x32x16_bf16 a[32:47], v[170:173], v[134:137], a[32:47]
	v_mfma_f32_32x32x16_bf16 a[16:31], v[166:169], v[138:141], a[16:31]
	v_mfma_f32_32x32x16_bf16 a[0:15], v[170:173], v[138:141], a[0:15]
	s_waitcnt lgkmcnt(0)
	s_barrier
; template <int TJ, bool SWAP, int NK, class Epi>
; DI void gemm_phase(const u16* __restrict__ A, size_t strideAz, int lda, const u16* __restrict__ Bt, size_t strideBz, int ldb,
;                    int Z, int Mt, int Nt, int GM, int K, char* smem, const Epi& epi, int vt) {
;     ...
;     for (int kt = 0; kt < NK; ++kt) {
;       constexpr int dummy = 0; (void)dummy;
;       const int u = kt & 1;
;       const u16* as = As + u * 256 * 72 + (128 * wm + r) * 72 + 8 * h;
;       const u16* bs = Bs + u * BN * 72 + (32 * TJ * wn + r) * 72 + 8 * h;
;       if (kt == 0) {
; #pragma unroll
;         for (int i = 0; i < 4; ++i) af[0][i] = *(const bf16x8*)(as + (32 * i) * 72);
; #pragma unroll
;         for (int j = 0; j < TJ; ++j) bfr[0][j] = *(const bf16x8*)(bs + (32 * j) * 72);
;       }
; #pragma unroll
;       for (int ks = 0; ks < 4; ++ks) {
;         if (ks < 3) {
; #pragma unroll
;           for (int i = 0; i < 4; ++i) af[(ks + 1) & 1][i] = *(const bf16x8*)(as + (32 * i) * 72 + 16 * (ks + 1));
; #pragma unroll
;           for (int j = 0; j < TJ; ++j) bfr[(ks + 1) & 1][j] = *(const bf16x8*)(bs + (32 * j) * 72 + 16 * (ks + 1));
;         } else if (kt + 1 < NK) {
;           const u16* asn = As + (u ^ 1) * 256 * 72 + (128 * wm + r) * 72 + 8 * h;
;           const u16* bsn = Bs + (u ^ 1) * BN * 72 + (32 * TJ * wn + r) * 72 + 8 * h;
; #pragma unroll
;           for (int i = 0; i < 4; ++i) af[0][i] = *(const bf16x8*)(asn + (32 * i) * 72);
; #pragma unroll
;           for (int j = 0; j < TJ; ++j) bfr[0][j] = *(const bf16x8*)(bsn + (32 * j) * 72);
;         }
;         __builtin_amdgcn_sched_barrier(0);
; #pragma unroll
;         for (int i = 0; i < 4; ++i)
; #pragma unroll
;           for (int j = 0; j < TJ; ++j)
;             acc[i][j] = SWAP ? MFMA32(bfr[ks & 1][j], af[ks & 1][i], acc[i][j]) : MFMA32(af[ks & 1][i], bfr[ks & 1][j], acc[i][j]);
;         if (ks == 0 && kt + 2 < NK) {
;           const u16* ag = Ag + (kt + 2) * 64;
; #pragma unroll
;           for (int i = 0; i < 8; ++i) ra[u][i] = *(const u32x4*)(ag + aoff[i]);
; #pragma unroll
;           for (int i = 0; i < 8; ++i) { __builtin_amdgcn_sched_group_barrier(0x008, 1, 0); __builtin_amdgcn_sched_group_barrier(0x020, 1, 0); }
;         }
;         if (ks == 2 && kt + 2 < NK) {
;           const u16* bg = Bg + (kt + 2) * 64;
; #pragma unroll
	ds_read_b128 v[52:55], v70 offset:36864
	ds_read_b128 v[60:63], v70 offset:41472
	ds_read_b128 v[126:129], v70 offset:46080
	ds_read_b128 v[130:133], v70 offset:50688
	ds_read_b128 v[134:137], v71 offset:18432
	ds_read_b128 v[138:141], v71 offset:23040
	v_mfma_f32_32x32x16_bf16 a[112:127], v[36:39], v[4:7], a[112:127]
	v_mfma_f32_32x32x16_bf16 a[96:111], v[44:47], v[4:7], a[96:111]
	v_mfma_f32_32x32x16_bf16 a[80:95], v[36:39], v[12:15], a[80:95]
	v_mfma_f32_32x32x16_bf16 a[64:79], v[44:47], v[12:15], a[64:79]
	v_mfma_f32_32x32x16_bf16 a[48:63], v[36:39], v[20:23], a[48:63]
	v_mfma_f32_32x32x16_bf16 a[32:47], v[44:47], v[20:23], a[32:47]
	v_mfma_f32_32x32x16_bf16 a[16:31], v[36:39], v[28:31], a[16:31]
	v_mfma_f32_32x32x16_bf16 a[0:15], v[44:47], v[28:31], a[0:15]
	ds_read_b128 v[142:145], v70 offset:36896
	ds_read_b128 v[146:149], v70 offset:41504
	ds_read_b128 v[150:153], v70 offset:46112
	ds_read_b128 v[154:157], v70 offset:50720
	ds_read_b128 v[158:161], v71 offset:18464
	ds_read_b128 v[162:165], v71 offset:23072
	s_waitcnt lgkmcnt(7)
	v_mfma_f32_32x32x16_bf16 a[112:127], v[134:137], v[52:55], a[112:127]
	global_load_dwordx4 v[4:7], v[102:103], off offset:1664
	s_waitcnt lgkmcnt(6)
	v_mfma_f32_32x32x16_bf16 a[96:111], v[138:141], v[52:55], a[96:111]
	global_load_dwordx4 v[12:15], v[100:101], off offset:1664
	v_mfma_f32_32x32x16_bf16 a[80:95], v[134:137], v[60:63], a[80:95]
	global_load_dwordx4 v[20:23], v[98:99], off offset:1664
	v_mfma_f32_32x32x16_bf16 a[64:79], v[138:141], v[60:63], a[64:79]
	global_load_dwordx4 v[28:31], v[96:97], off offset:1664
	v_mfma_f32_32x32x16_bf16 a[48:63], v[134:137], v[126:129], a[48:63]
	global_load_dwordx4 v[36:39], v[94:95], off offset:1664
	v_mfma_f32_32x32x16_bf16 a[32:47], v[138:141], v[126:129], a[32:47]
	global_load_dwordx4 v[44:47], v[92:93], off offset:1664
	v_mfma_f32_32x32x16_bf16 a[16:31], v[134:137], v[130:133], a[16:31]
	global_load_dwordx4 v[52:55], v[90:91], off offset:1664
	v_mfma_f32_32x32x16_bf16 a[0:15], v[138:141], v[130:133], a[0:15]
	global_load_dwordx4 v[60:63], v[88:89], off offset:1664
	ds_read_b128 v[126:129], v70 offset:36928
	ds_read_b128 v[130:133], v70 offset:41536
	ds_read_b128 v[134:137], v70 offset:46144
	ds_read_b128 v[138:141], v70 offset:50752
	ds_read_b128 v[166:169], v71 offset:18496
	ds_read_b128 v[170:173], v71 offset:23104
	s_waitcnt lgkmcnt(7)
	v_mfma_f32_32x32x16_bf16 a[112:127], v[158:161], v[142:145], a[112:127]
	s_waitcnt vmcnt(19)
	ds_write_b128 v104, v[0:3]
	s_waitcnt vmcnt(18)
	ds_write_b128 v104, v[8:11] offset:4608
	s_waitcnt lgkmcnt(8)
	v_mfma_f32_32x32x16_bf16 a[96:111], v[162:165], v[142:145], a[96:111]
	s_waitcnt vmcnt(17)
	ds_write_b128 v104, v[16:19] offset:9216
	s_waitcnt vmcnt(16)
	ds_write_b128 v104, v[24:27] offset:13824
	v_mfma_f32_32x32x16_bf16 a[80:95], v[158:161], v[146:149], a[80:95]
	s_waitcnt vmcnt(15)
	ds_write_b128 v104, v[32:35] offset:18432
	s_waitcnt vmcnt(14)
	ds_write_b128 v104, v[40:43] offset:23040
	v_mfma_f32_32x32x16_bf16 a[64:79], v[162:165], v[146:149], a[64:79]
	s_waitcnt vmcnt(13)
	ds_write_b128 v104, v[48:51] offset:27648
	s_waitcnt vmcnt(12)
	ds_write_b128 v104, v[56:59] offset:32256
	v_mfma_f32_32x32x16_bf16 a[48:63], v[158:161], v[150:153], a[48:63]
	s_waitcnt vmcnt(11)
	ds_write_b128 v105, v[110:113]
	s_waitcnt vmcnt(10)
	ds_write_b128 v105, v[114:117] offset:4608
	v_mfma_f32_32x32x16_bf16 a[32:47], v[162:165], v[150:153], a[32:47]
	s_waitcnt vmcnt(9)
	ds_write_b128 v105, v[118:121] offset:9216
	s_waitcnt vmcnt(8)
	ds_write_b128 v105, v[122:125] offset:13824
	v_mfma_f32_32x32x16_bf16 a[16:31], v[158:161], v[154:157], a[16:31]
	v_mfma_f32_32x32x16_bf16 a[0:15], v[162:165], v[154:157], a[0:15]
	ds_read_b128 v[0:3], v70 offset:36960
	ds_read_b128 v[8:11], v70 offset:41568
	ds_read_b128 v[16:19], v70 offset:46176
	ds_read_b128 v[24:27], v70 offset:50784
	ds_read_b128 v[32:35], v71 offset:18528
	ds_read_b128 v[40:43], v71 offset:23136
	s_waitcnt lgkmcnt(14)
	v_mfma_f32_32x32x16_bf16 a[112:127], v[166:169], v[126:129], a[112:127]
	global_load_dwordx4 v[110:113], v[86:87], off offset:1664
	v_mfma_f32_32x32x16_bf16 a[96:111], v[170:173], v[126:129], a[96:111]
	global_load_dwordx4 v[114:117], v[84:85], off offset:1664
	v_mfma_f32_32x32x16_bf16 a[80:95], v[166:169], v[130:133], a[80:95]
	global_load_dwordx4 v[118:121], v[82:83], off offset:1664
	v_mfma_f32_32x32x16_bf16 a[64:79], v[170:173], v[130:133], a[64:79]
	global_load_dwordx4 v[122:125], v[80:81], off offset:1664
	v_mfma_f32_32x32x16_bf16 a[48:63], v[166:169], v[134:137], a[48:63]
	v_mfma_f32_32x32x16_bf16 a[32:47], v[170:173], v[134:137], a[32:47]
	v_mfma_f32_32x32x16_bf16 a[16:31], v[166:169], v[138:141], a[16:31]
	v_mfma_f32_32x32x16_bf16 a[0:15], v[170:173], v[138:141], a[0:15]
	s_waitcnt lgkmcnt(0)
	s_barrier
; template <int TJ, bool SWAP, int NK, class Epi>
; DI void gemm_phase(const u16* __restrict__ A, size_t strideAz, int lda, const u16* __restrict__ Bt, size_t strideBz, int ldb,
;                    int Z, int Mt, int Nt, int GM, int K, char* smem, const Epi& epi, int vt) {
;     ...
;     for (int kt = 0; kt < NK; ++kt) {
;       constexpr int dummy = 0; (void)dummy;
;       const int u = kt & 1;
;       const u16* as = As + u * 256 * 72 + (128 * wm + r) * 72 + 8 * h;
;       const u16* bs = Bs + u * BN * 72 + (32 * TJ * wn + r) * 72 + 8 * h;
;       if (kt == 0) {
; #pragma unroll
;         for (int i = 0; i < 4; ++i) af[0][i] = *(const bf16x8*)(as + (32 * i) * 72);
; #pragma unroll
;         for (int j = 0; j < TJ; ++j) bfr[0][j] = *(const bf16x8*)(bs + (32 * j) * 72);
;       }
; #pragma unroll
;       for (int ks = 0; ks < 4; ++ks) {
;         if (ks < 3) {
; #pragma unroll
;           for (int i = 0; i < 4; ++i) af[(ks + 1) & 1][i] = *(const bf16x8*)(as + (32 * i) * 72 + 16 * (ks + 1));
; #pragma unroll
;           for (int j = 0; j < TJ; ++j) bfr[(ks + 1) & 1][j] = *(const bf16x8*)(bs + (32 * j) * 72 + 16 * (ks + 1));
;         } else if (kt + 1 < NK) {
;           const u16* asn = As + (u ^ 1) * 256 * 72 + (128 * wm + r) * 72 + 8 * h;
;           const u16* bsn = Bs + (u ^ 1) * BN * 72 + (32 * TJ * wn + r) * 72 + 8 * h;
; #pragma unroll
;           for (int i = 0; i < 4; ++i) af[0][i] = *(const bf16x8*)(asn + (32 * i) * 72);
; #pragma unroll
;           for (int j = 0; j < TJ; ++j) bfr[0][j] = *(const bf16x8*)(bsn + (32 * j) * 72);
;         }
;         __builtin_amdgcn_sched_barrier(0);
; #pragma unroll
;         for (int i = 0; i < 4; ++i)
; #pragma unroll
;           for (int j = 0; j < TJ; ++j)
;             acc[i][j] = SWAP ? MFMA32(bfr[ks & 1][j], af[ks & 1][i], acc[i][j]) : MFMA32(af[ks & 1][i], bfr[ks & 1][j], acc[i][j]);
;         if (ks == 0 && kt + 2 < NK) {
;           const u16* ag = Ag + (kt + 2) * 64;
; #pragma unroll
;           for (int i = 0; i < 8; ++i) ra[u][i] = *(const u32x4*)(ag + aoff[i]);
; #pragma unroll
;           for (int i = 0; i < 8; ++i) { __builtin_amdgcn_sched_group_barrier(0x008, 1, 0); __builtin_amdgcn_sched_group_barrier(0x020, 1, 0); }
;         }
;         if (ks == 2 && kt + 2 < NK) {
;           const u16* bg = Bg + (kt + 2) * 64;
; #pragma unroll
	ds_read_b128 v[48:51], v70
	ds_read_b128 v[56:59], v70 offset:4608
	ds_read_b128 v[126:129], v70 offset:9216
	ds_read_b128 v[130:133], v70 offset:13824
	ds_read_b128 v[134:137], v71
	ds_read_b128 v[138:141], v71 offset:4608
	v_mfma_f32_32x32x16_bf16 a[112:127], v[32:35], v[0:3], a[112:127]
	v_mfma_f32_32x32x16_bf16 a[96:111], v[40:43], v[0:3], a[96:111]
	v_mfma_f32_32x32x16_bf16 a[80:95], v[32:35], v[8:11], a[80:95]
	v_mfma_f32_32x32x16_bf16 a[64:79], v[40:43], v[8:11], a[64:79]
	v_mfma_f32_32x32x16_bf16 a[48:63], v[32:35], v[16:19], a[48:63]
	v_mfma_f32_32x32x16_bf16 a[32:47], v[40:43], v[16:19], a[32:47]
	v_mfma_f32_32x32x16_bf16 a[16:31], v[32:35], v[24:27], a[16:31]
	v_mfma_f32_32x32x16_bf16 a[0:15], v[40:43], v[24:27], a[0:15]
	ds_read_b128 v[142:145], v70 offset:32
	ds_read_b128 v[146:149], v70 offset:4640
	ds_read_b128 v[150:153], v70 offset:9248
	ds_read_b128 v[154:157], v70 offset:13856
	ds_read_b128 v[158:161], v71 offset:32
	ds_read_b128 v[162:165], v71 offset:4640
	s_waitcnt lgkmcnt(7)
	v_mfma_f32_32x32x16_bf16 a[112:127], v[134:137], v[48:51], a[112:127]
	global_load_dwordx4 v[0:3], v[102:103], off offset:1792
	s_waitcnt lgkmcnt(6)
	v_mfma_f32_32x32x16_bf16 a[96:111], v[138:141], v[48:51], a[96:111]
	global_load_dwordx4 v[8:11], v[100:101], off offset:1792
	v_mfma_f32_32x32x16_bf16 a[80:95], v[134:137], v[56:59], a[80:95]
	global_load_dwordx4 v[16:19], v[98:99], off offset:1792
	v_mfma_f32_32x32x16_bf16 a[64:79], v[138:141], v[56:59], a[64:79]
	global_load_dwordx4 v[24:27], v[96:97], off offset:1792
	v_mfma_f32_32x32x16_bf16 a[48:63], v[134:137], v[126:129], a[48:63]
	global_load_dwordx4 v[32:35], v[94:95], off offset:1792
	v_mfma_f32_32x32x16_bf16 a[32:47], v[138:141], v[126:129], a[32:47]
	global_load_dwordx4 v[40:43], v[92:93], off offset:1792
	v_mfma_f32_32x32x16_bf16 a[16:31], v[134:137], v[130:133], a[16:31]
	global_load_dwordx4 v[48:51], v[90:91], off offset:1792
	v_mfma_f32_32x32x16_bf16 a[0:15], v[138:141], v[130:133], a[0:15]
	global_load_dwordx4 v[56:59], v[88:89], off offset:1792
	ds_read_b128 v[126:129], v70 offset:64
	ds_read_b128 v[130:133], v70 offset:4672
	ds_read_b128 v[134:137], v70 offset:9280
	ds_read_b128 v[138:141], v70 offset:13888
	ds_read_b128 v[166:169], v71 offset:64
	ds_read_b128 v[170:173], v71 offset:4672
	s_waitcnt lgkmcnt(7)
	v_mfma_f32_32x32x16_bf16 a[112:127], v[158:161], v[142:145], a[112:127]
	s_waitcnt vmcnt(19)
	ds_write_b128 v104, v[4:7] offset:36864
	s_waitcnt vmcnt(18)
	ds_write_b128 v104, v[12:15] offset:41472
	s_waitcnt lgkmcnt(8)
	v_mfma_f32_32x32x16_bf16 a[96:111], v[162:165], v[142:145], a[96:111]
	s_waitcnt vmcnt(17)
	ds_write_b128 v104, v[20:23] offset:46080
	s_waitcnt vmcnt(16)
	ds_write_b128 v104, v[28:31] offset:50688
	v_mfma_f32_32x32x16_bf16 a[80:95], v[158:161], v[146:149], a[80:95]
	s_waitcnt vmcnt(15)
	ds_write_b128 v104, v[36:39] offset:55296
	s_waitcnt vmcnt(14)
	ds_write_b128 v104, v[44:47] offset:59904
	v_mfma_f32_32x32x16_bf16 a[64:79], v[162:165], v[146:149], a[64:79]
	s_waitcnt vmcnt(13)
	ds_write_b128 v104, v[52:55] offset:64512
	s_waitcnt vmcnt(12)
	ds_write_b128 v108, v[60:63]
	v_mfma_f32_32x32x16_bf16 a[48:63], v[158:161], v[150:153], a[48:63]
	s_waitcnt vmcnt(11)
	ds_write_b128 v105, v[110:113] offset:18432
	s_waitcnt vmcnt(10)
	ds_write_b128 v105, v[114:117] offset:23040
	v_mfma_f32_32x32x16_bf16 a[32:47], v[162:165], v[150:153], a[32:47]
	s_waitcnt vmcnt(9)
	ds_write_b128 v105, v[118:121] offset:27648
	s_waitcnt vmcnt(8)
	ds_write_b128 v105, v[122:125] offset:32256
	v_mfma_f32_32x32x16_bf16 a[16:31], v[158:161], v[154:157], a[16:31]
	v_mfma_f32_32x32x16_bf16 a[0:15], v[162:165], v[154:157], a[0:15]
	ds_read_b128 v[4:7], v70 offset:96
	ds_read_b128 v[12:15], v70 offset:4704
	ds_read_b128 v[20:23], v70 offset:9312
	ds_read_b128 v[28:31], v70 offset:13920
	ds_read_b128 v[36:39], v71 offset:96
	ds_read_b128 v[44:47], v71 offset:4704
	s_waitcnt lgkmcnt(14)
	v_mfma_f32_32x32x16_bf16 a[112:127], v[166:169], v[126:129], a[112:127]
	global_load_dwordx4 v[52:55], v[86:87], off offset:1792
	v_mfma_f32_32x32x16_bf16 a[96:111], v[170:173], v[126:129], a[96:111]
	global_load_dwordx4 v[60:63], v[84:85], off offset:1792
	v_mfma_f32_32x32x16_bf16 a[80:95], v[166:169], v[130:133], a[80:95]
	global_load_dwordx4 v[110:113], v[82:83], off offset:1792
	v_mfma_f32_32x32x16_bf16 a[64:79], v[170:173], v[130:133], a[64:79]
	global_load_dwordx4 v[114:117], v[80:81], off offset:1792
	v_mfma_f32_32x32x16_bf16 a[48:63], v[166:169], v[134:137], a[48:63]
	v_mfma_f32_32x32x16_bf16 a[32:47], v[170:173], v[134:137], a[32:47]
	v_mfma_f32_32x32x16_bf16 a[16:31], v[166:169], v[138:141], a[16:31]
	v_mfma_f32_32x32x16_bf16 a[0:15], v[170:173], v[138:141], a[0:15]
	s_waitcnt lgkmcnt(0)
	s_barrier
; template <int TJ, bool SWAP, int NK, class Epi>
; DI void gemm_phase(const u16* __restrict__ A, size_t strideAz, int lda, const u16* __restrict__ Bt, size_t strideBz, int ldb,
;                    int Z, int Mt, int Nt, int GM, int K, char* smem, const Epi& epi, int vt) {
;     ...
;     for (int kt = 0; kt < NK; ++kt) {
;       constexpr int dummy = 0; (void)dummy;
;       const int u = kt & 1;
;       const u16* as = As + u * 256 * 72 + (128 * wm + r) * 72 + 8 * h;
;       const u16* bs = Bs + u * BN * 72 + (32 * TJ * wn + r) * 72 + 8 * h;
;       if (kt == 0) {
; #pragma unroll
;         for (int i = 0; i < 4; ++i) af[0][i] = *(const bf16x8*)(as + (32 * i) * 72);
; #pragma unroll
;         for (int j = 0; j < TJ; ++j) bfr[0][j] = *(const bf16x8*)(bs + (32 * j) * 72);
;       }
; #pragma unroll
;       for (int ks = 0; ks < 4; ++ks) {
;         if (ks < 3) {
; #pragma unroll
;           for (int i = 0; i < 4; ++i) af[(ks + 1) & 1][i] = *(const bf16x8*)(as + (32 * i) * 72 + 16 * (ks + 1));
; #pragma unroll
;           for (int j = 0; j < TJ; ++j) bfr[(ks + 1) & 1][j] = *(const bf16x8*)(bs + (32 * j) * 72 + 16 * (ks + 1));
;         } else if (kt + 1 < NK) {
;           const u16* asn = As + (u ^ 1) * 256 * 72 + (128 * wm + r) * 72 + 8 * h;
;           const u16* bsn = Bs + (u ^ 1) * BN * 72 + (32 * TJ * wn + r) * 72 + 8 * h;
; #pragma unroll
;           for (int i = 0; i < 4; ++i) af[0][i] = *(const bf16x8*)(asn + (32 * i) * 72);
; #pragma unroll
;           for (int j = 0; j < TJ; ++j) bfr[0][j] = *(const bf16x8*)(bsn + (32 * j) * 72);
;         }
;         __builtin_amdgcn_sched_barrier(0);
; #pragma unroll
;         for (int i = 0; i < 4; ++i)
; #pragma unroll
;           for (int j = 0; j < TJ; ++j)
;             acc[i][j] = SWAP ? MFMA32(bfr[ks & 1][j], af[ks & 1][i], acc[i][j]) : MFMA32(af[ks & 1][i], bfr[ks & 1][j], acc[i][j]);
;         if (ks == 0 && kt + 2 < NK) {
;           const u16* ag = Ag + (kt + 2) * 64;
; #pragma unroll
;           for (int i = 0; i < 8; ++i) ra[u][i] = *(const u32x4*)(ag + aoff[i]);
; #pragma unroll
;           for (int i = 0; i < 8; ++i) { __builtin_amdgcn_sched_group_barrier(0x008, 1, 0); __builtin_amdgcn_sched_group_barrier(0x020, 1, 0); }
;         }
;         if (ks == 2 && kt + 2 < NK) {
;           const u16* bg = Bg + (kt + 2) * 64;
; #pragma unroll
	ds_read_b128 v[118:121], v70 offset:36864
	ds_read_b128 v[122:125], v70 offset:41472
	ds_read_b128 v[126:129], v70 offset:46080
	ds_read_b128 v[130:133], v70 offset:50688
	ds_read_b128 v[134:137], v71 offset:18432
	ds_read_b128 v[138:141], v71 offset:23040
	v_mfma_f32_32x32x16_bf16 a[112:127], v[36:39], v[4:7], a[112:127]
	v_mfma_f32_32x32x16_bf16 a[96:111], v[44:47], v[4:7], a[96:111]
	v_mfma_f32_32x32x16_bf16 a[80:95], v[36:39], v[12:15], a[80:95]
	v_mfma_f32_32x32x16_bf16 a[64:79], v[44:47], v[12:15], a[64:79]
	v_mfma_f32_32x32x16_bf16 a[48:63], v[36:39], v[20:23], a[48:63]
	v_mfma_f32_32x32x16_bf16 a[32:47], v[44:47], v[20:23], a[32:47]
	v_mfma_f32_32x32x16_bf16 a[16:31], v[36:39], v[28:31], a[16:31]
	v_mfma_f32_32x32x16_bf16 a[0:15], v[44:47], v[28:31], a[0:15]
	ds_read_b128 v[12:15], v70 offset:36896
	ds_read_b128 v[20:23], v70 offset:41504
	ds_read_b128 v[28:31], v70 offset:46112
	ds_read_b128 v[36:39], v70 offset:50720
	ds_read_b128 v[44:47], v71 offset:18464
	ds_read_b128 v[142:145], v71 offset:23072
	s_waitcnt lgkmcnt(7)
	v_mfma_f32_32x32x16_bf16 a[112:127], v[134:137], v[118:121], a[112:127]
	global_load_dwordx4 v[4:7], v[102:103], off offset:1920
	s_waitcnt lgkmcnt(6)
	v_mfma_f32_32x32x16_bf16 a[96:111], v[138:141], v[118:121], a[96:111]
	global_load_dwordx4 v[100:103], v[100:101], off offset:1920
	v_mfma_f32_32x32x16_bf16 a[80:95], v[134:137], v[122:125], a[80:95]
	global_load_dwordx4 v[118:121], v[98:99], off offset:1920
	v_mfma_f32_32x32x16_bf16 a[64:79], v[138:141], v[122:125], a[64:79]
	global_load_dwordx4 v[96:99], v[96:97], off offset:1920
	v_mfma_f32_32x32x16_bf16 a[48:63], v[134:137], v[126:129], a[48:63]
	global_load_dwordx4 v[122:125], v[94:95], off offset:1920
	v_mfma_f32_32x32x16_bf16 a[32:47], v[138:141], v[126:129], a[32:47]
	global_load_dwordx4 v[92:95], v[92:93], off offset:1920
	v_mfma_f32_32x32x16_bf16 a[16:31], v[134:137], v[130:133], a[16:31]
	global_load_dwordx4 v[126:129], v[90:91], off offset:1920
	v_mfma_f32_32x32x16_bf16 a[0:15], v[138:141], v[130:133], a[0:15]
	global_load_dwordx4 v[88:91], v[88:89], off offset:1920
	ds_read_b128 v[130:133], v70 offset:36928
	ds_read_b128 v[134:137], v70 offset:41536
	ds_read_b128 v[138:141], v70 offset:46144
	ds_read_b128 v[146:149], v70 offset:50752
	ds_read_b128 v[150:153], v71 offset:18496
	ds_read_b128 v[154:157], v71 offset:23104
	s_waitcnt lgkmcnt(7)
	v_mfma_f32_32x32x16_bf16 a[112:127], v[44:47], v[12:15], a[112:127]
	s_waitcnt vmcnt(19)
	ds_write_b128 v104, v[0:3]
	s_waitcnt vmcnt(18)
	ds_write_b128 v104, v[8:11] offset:4608
	s_waitcnt lgkmcnt(8)
	v_mfma_f32_32x32x16_bf16 a[96:111], v[142:145], v[12:15], a[96:111]
	s_waitcnt vmcnt(17)
	ds_write_b128 v104, v[16:19] offset:9216
	s_waitcnt vmcnt(16)
	ds_write_b128 v104, v[24:27] offset:13824
	v_mfma_f32_32x32x16_bf16 a[80:95], v[44:47], v[20:23], a[80:95]
	s_waitcnt vmcnt(15)
	ds_write_b128 v104, v[32:35] offset:18432
	s_waitcnt vmcnt(14)
	ds_write_b128 v104, v[40:43] offset:23040
	v_mfma_f32_32x32x16_bf16 a[64:79], v[142:145], v[20:23], a[64:79]
	s_waitcnt vmcnt(13)
	ds_write_b128 v104, v[48:51] offset:27648
	s_waitcnt vmcnt(12)
	ds_write_b128 v104, v[56:59] offset:32256
	v_mfma_f32_32x32x16_bf16 a[48:63], v[44:47], v[28:31], a[48:63]
	s_waitcnt vmcnt(11)
	ds_write_b128 v105, v[52:55]
	s_waitcnt vmcnt(10)
	ds_write_b128 v105, v[60:63] offset:4608
	v_mfma_f32_32x32x16_bf16 a[32:47], v[142:145], v[28:31], a[32:47]
	s_waitcnt vmcnt(9)
	ds_write_b128 v105, v[110:113] offset:9216
	s_waitcnt vmcnt(8)
	ds_write_b128 v105, v[114:117] offset:13824
	v_mfma_f32_32x32x16_bf16 a[16:31], v[44:47], v[36:39], a[16:31]
	v_mfma_f32_32x32x16_bf16 a[0:15], v[142:145], v[36:39], a[0:15]
	ds_read_b128 v[0:3], v70 offset:36960
	ds_read_b128 v[8:11], v70 offset:41568
	ds_read_b128 v[12:15], v70 offset:46176
	ds_read_b128 v[16:19], v70 offset:50784
	ds_read_b128 v[20:23], v71 offset:18528
	ds_read_b128 v[24:27], v71 offset:23136
	s_waitcnt lgkmcnt(14)
	v_mfma_f32_32x32x16_bf16 a[112:127], v[150:153], v[130:133], a[112:127]
	global_load_dwordx4 v[28:31], v[86:87], off offset:1920
	v_mfma_f32_32x32x16_bf16 a[96:111], v[154:157], v[130:133], a[96:111]
	global_load_dwordx4 v[32:35], v[84:85], off offset:1920
	v_mfma_f32_32x32x16_bf16 a[80:95], v[150:153], v[134:137], a[80:95]
	global_load_dwordx4 v[36:39], v[82:83], off offset:1920
	v_mfma_f32_32x32x16_bf16 a[64:79], v[154:157], v[134:137], a[64:79]
	global_load_dwordx4 v[40:43], v[80:81], off offset:1920
	v_mfma_f32_32x32x16_bf16 a[48:63], v[150:153], v[138:141], a[48:63]
	v_mfma_f32_32x32x16_bf16 a[32:47], v[154:157], v[138:141], a[32:47]
	v_mfma_f32_32x32x16_bf16 a[16:31], v[150:153], v[146:149], a[16:31]
	v_mfma_f32_32x32x16_bf16 a[0:15], v[154:157], v[146:149], a[0:15]
	s_waitcnt lgkmcnt(0)
	s_barrier
; template <int TJ, bool SWAP, int NK, class Epi>
; DI void gemm_phase(const u16* __restrict__ A, size_t strideAz, int lda, const u16* __restrict__ Bt, size_t strideBz, int ldb,
;                    int Z, int Mt, int Nt, int GM, int K, char* smem, const Epi& epi, int vt) {
;     ...
;     for (int kt = 0; kt < NK; ++kt) {
;       constexpr int dummy = 0; (void)dummy;
;       const int u = kt & 1;
;       const u16* as = As + u * 256 * 72 + (128 * wm + r) * 72 + 8 * h;
;       const u16* bs = Bs + u * BN * 72 + (32 * TJ * wn + r) * 72 + 8 * h;
;       if (kt == 0) {
; #pragma unroll
;         for (int i = 0; i < 4; ++i) af[0][i] = *(const bf16x8*)(as + (32 * i) * 72);
; #pragma unroll
;         for (int j = 0; j < TJ; ++j) bfr[0][j] = *(const bf16x8*)(bs + (32 * j) * 72);
;       }
; #pragma unroll
;       for (int ks = 0; ks < 4; ++ks) {
;         if (ks < 3) {
; #pragma unroll
;           for (int i = 0; i < 4; ++i) af[(ks + 1) & 1][i] = *(const bf16x8*)(as + (32 * i) * 72 + 16 * (ks + 1));
; #pragma unroll
;           for (int j = 0; j < TJ; ++j) bfr[(ks + 1) & 1][j] = *(const bf16x8*)(bs + (32 * j) * 72 + 16 * (ks + 1));
;         } else if (kt + 1 < NK) {
;           const u16* asn = As + (u ^ 1) * 256 * 72 + (128 * wm + r) * 72 + 8 * h;
;           const u16* bsn = Bs + (u ^ 1) * BN * 72 + (32 * TJ * wn + r) * 72 + 8 * h;
; #pragma unroll
;           for (int i = 0; i < 4; ++i) af[0][i] = *(const bf16x8*)(asn + (32 * i) * 72);
; #pragma unroll
;           for (int j = 0; j < TJ; ++j) bfr[0][j] = *(const bf16x8*)(bsn + (32 * j) * 72);
;         }
;         __builtin_amdgcn_sched_barrier(0);
; #pragma unroll
;         for (int i = 0; i < 4; ++i)
; #pragma unroll
;           for (int j = 0; j < TJ; ++j)
;             acc[i][j] = SWAP ? MFMA32(bfr[ks & 1][j], af[ks & 1][i], acc[i][j]) : MFMA32(af[ks & 1][i], bfr[ks & 1][j], acc[i][j]);
;         if (ks == 0 && kt + 2 < NK) {
;           const u16* ag = Ag + (kt + 2) * 64;
; #pragma unroll
;           for (int i = 0; i < 8; ++i) ra[u][i] = *(const u32x4*)(ag + aoff[i]);
; #pragma unroll
;           for (int i = 0; i < 8; ++i) { __builtin_amdgcn_sched_group_barrier(0x008, 1, 0); __builtin_amdgcn_sched_group_barrier(0x020, 1, 0); }
;         }
;         if (ks == 2 && kt + 2 < NK) {
;           const u16* bg = Bg + (kt + 2) * 64;
; #pragma unroll
	ds_read_b128 v[44:47], v70
	ds_read_b128 v[48:51], v70 offset:4608
	ds_read_b128 v[52:55], v70 offset:9216
	ds_read_b128 v[56:59], v70 offset:13824
	ds_read_b128 v[60:63], v71
	ds_read_b128 v[80:83], v71 offset:4608
	v_mfma_f32_32x32x16_bf16 a[112:127], v[20:23], v[0:3], a[112:127]
	v_mfma_f32_32x32x16_bf16 a[96:111], v[24:27], v[0:3], a[96:111]
	v_mfma_f32_32x32x16_bf16 a[80:95], v[20:23], v[8:11], a[80:95]
	v_mfma_f32_32x32x16_bf16 a[64:79], v[24:27], v[8:11], a[64:79]
	v_mfma_f32_32x32x16_bf16 a[48:63], v[20:23], v[12:15], a[48:63]
	v_mfma_f32_32x32x16_bf16 a[32:47], v[24:27], v[12:15], a[32:47]
	v_mfma_f32_32x32x16_bf16 a[16:31], v[20:23], v[16:19], a[16:31]
	v_mfma_f32_32x32x16_bf16 a[0:15], v[24:27], v[16:19], a[0:15]
	ds_read_b128 v[0:3], v70 offset:32
	ds_read_b128 v[8:11], v70 offset:4640
	ds_read_b128 v[12:15], v70 offset:9248
	ds_read_b128 v[16:19], v70 offset:13856
	ds_read_b128 v[20:23], v71 offset:32
	ds_read_b128 v[24:27], v71 offset:4640
	s_waitcnt lgkmcnt(7)
	v_mfma_f32_32x32x16_bf16 a[112:127], v[60:63], v[44:47], a[112:127]
	s_waitcnt lgkmcnt(6)
	v_mfma_f32_32x32x16_bf16 a[96:111], v[80:83], v[44:47], a[96:111]
	v_mfma_f32_32x32x16_bf16 a[80:95], v[60:63], v[48:51], a[80:95]
	v_mfma_f32_32x32x16_bf16 a[64:79], v[80:83], v[48:51], a[64:79]
	v_mfma_f32_32x32x16_bf16 a[48:63], v[60:63], v[52:55], a[48:63]
	v_mfma_f32_32x32x16_bf16 a[32:47], v[80:83], v[52:55], a[32:47]
	v_mfma_f32_32x32x16_bf16 a[16:31], v[60:63], v[56:59], a[16:31]
	v_mfma_f32_32x32x16_bf16 a[0:15], v[80:83], v[56:59], a[0:15]
	ds_read_b128 v[44:47], v70 offset:64
	ds_read_b128 v[48:51], v70 offset:4672
	ds_read_b128 v[52:55], v70 offset:9280
	ds_read_b128 v[56:59], v70 offset:13888
	ds_read_b128 v[60:63], v71 offset:64
	ds_read_b128 v[80:83], v71 offset:4672
	s_waitcnt lgkmcnt(7)
	v_mfma_f32_32x32x16_bf16 a[112:127], v[20:23], v[0:3], a[112:127]
	s_waitcnt vmcnt(11)
	ds_write_b128 v104, v[4:7] offset:36864
	s_waitcnt vmcnt(10)
	ds_write_b128 v104, v[100:103] offset:41472
	s_waitcnt lgkmcnt(8)
	v_mfma_f32_32x32x16_bf16 a[96:111], v[24:27], v[0:3], a[96:111]
	s_waitcnt vmcnt(9)
	ds_write_b128 v104, v[118:121] offset:46080
	s_waitcnt vmcnt(8)
	ds_write_b128 v104, v[96:99] offset:50688
	v_mfma_f32_32x32x16_bf16 a[80:95], v[20:23], v[8:11], a[80:95]
	s_waitcnt vmcnt(7)
	ds_write_b128 v104, v[122:125] offset:55296
	s_waitcnt vmcnt(6)
	ds_write_b128 v104, v[92:95] offset:59904
	v_mfma_f32_32x32x16_bf16 a[64:79], v[24:27], v[8:11], a[64:79]
	s_waitcnt vmcnt(5)
	ds_write_b128 v104, v[126:129] offset:64512
	s_waitcnt vmcnt(4)
	ds_write_b128 v108, v[88:91]
	v_mfma_f32_32x32x16_bf16 a[48:63], v[20:23], v[12:15], a[48:63]
	s_waitcnt vmcnt(3)
	ds_write_b128 v105, v[28:31] offset:18432
	s_waitcnt vmcnt(2)
	ds_write_b128 v105, v[32:35] offset:23040
	v_mfma_f32_32x32x16_bf16 a[32:47], v[24:27], v[12:15], a[32:47]
	s_waitcnt vmcnt(1)
	ds_write_b128 v105, v[36:39] offset:27648
	s_waitcnt vmcnt(0)
	ds_write_b128 v105, v[40:43] offset:32256
	v_mfma_f32_32x32x16_bf16 a[16:31], v[20:23], v[16:19], a[16:31]
	v_mfma_f32_32x32x16_bf16 a[0:15], v[24:27], v[16:19], a[0:15]
	ds_read_b128 v[0:3], v70 offset:96
	ds_read_b128 v[4:7], v70 offset:4704
	ds_read_b128 v[8:11], v70 offset:9312
	ds_read_b128 v[12:15], v70 offset:13920
	ds_read_b128 v[16:19], v71 offset:96
	ds_read_b128 v[20:23], v71 offset:4704
	s_waitcnt lgkmcnt(14)
	v_mfma_f32_32x32x16_bf16 a[112:127], v[60:63], v[44:47], a[112:127]
	v_mfma_f32_32x32x16_bf16 a[96:111], v[80:83], v[44:47], a[96:111]
	v_mfma_f32_32x32x16_bf16 a[80:95], v[60:63], v[48:51], a[80:95]
	v_mfma_f32_32x32x16_bf16 a[64:79], v[80:83], v[48:51], a[64:79]
	v_mfma_f32_32x32x16_bf16 a[48:63], v[60:63], v[52:55], a[48:63]
	v_mfma_f32_32x32x16_bf16 a[32:47], v[80:83], v[52:55], a[32:47]
	v_mfma_f32_32x32x16_bf16 a[16:31], v[60:63], v[56:59], a[16:31]
	v_mfma_f32_32x32x16_bf16 a[0:15], v[80:83], v[56:59], a[0:15]
	s_waitcnt lgkmcnt(0)
	s_barrier
	ds_read_b128 v[24:27], v70 offset:36864
	ds_read_b128 v[28:31], v70 offset:41472
	ds_read_b128 v[32:35], v70 offset:46080
	ds_read_b128 v[36:39], v70 offset:50688
	ds_read_b128 v[40:43], v71 offset:18432
	ds_read_b128 v[44:47], v71 offset:23040
	v_mfma_f32_32x32x16_bf16 a[112:127], v[16:19], v[0:3], a[112:127]
	v_mfma_f32_32x32x16_bf16 a[96:111], v[20:23], v[0:3], a[96:111]
	v_mfma_f32_32x32x16_bf16 a[80:95], v[16:19], v[4:7], a[80:95]
	v_mfma_f32_32x32x16_bf16 a[64:79], v[20:23], v[4:7], a[64:79]
	v_mfma_f32_32x32x16_bf16 a[48:63], v[16:19], v[8:11], a[48:63]
	v_mfma_f32_32x32x16_bf16 a[32:47], v[20:23], v[8:11], a[32:47]
	v_mfma_f32_32x32x16_bf16 a[16:31], v[16:19], v[12:15], a[16:31]
	v_mfma_f32_32x32x16_bf16 a[0:15], v[20:23], v[12:15], a[0:15]
	ds_read_b128 v[0:3], v70 offset:36896
	ds_read_b128 v[4:7], v70 offset:41504
	ds_read_b128 v[8:11], v70 offset:46112
	ds_read_b128 v[12:15], v70 offset:50720
	ds_read_b128 v[16:19], v71 offset:18464
	ds_read_b128 v[20:23], v71 offset:23072
	s_waitcnt lgkmcnt(7)
	v_mfma_f32_32x32x16_bf16 a[112:127], v[40:43], v[24:27], a[112:127]
	s_waitcnt lgkmcnt(6)
	v_mfma_f32_32x32x16_bf16 a[96:111], v[44:47], v[24:27], a[96:111]
	v_mfma_f32_32x32x16_bf16 a[80:95], v[40:43], v[28:31], a[80:95]
	v_mfma_f32_32x32x16_bf16 a[64:79], v[44:47], v[28:31], a[64:79]
	v_mfma_f32_32x32x16_bf16 a[48:63], v[40:43], v[32:35], a[48:63]
	v_mfma_f32_32x32x16_bf16 a[32:47], v[44:47], v[32:35], a[32:47]
	v_mfma_f32_32x32x16_bf16 a[16:31], v[40:43], v[36:39], a[16:31]
	v_mfma_f32_32x32x16_bf16 a[0:15], v[44:47], v[36:39], a[0:15]
	ds_read_b128 v[24:27], v70 offset:36928
	ds_read_b128 v[28:31], v70 offset:41536
	ds_read_b128 v[32:35], v70 offset:46144
	ds_read_b128 v[36:39], v70 offset:50752
	ds_read_b128 v[40:43], v71 offset:18496
	ds_read_b128 v[44:47], v71 offset:23104
	s_waitcnt lgkmcnt(7)
; template <int TJ, bool SWAP, int NK, class Epi>
; DI void gemm_phase(const u16* __restrict__ A, size_t strideAz, int lda, const u16* __restrict__ Bt, size_t strideBz, int ldb,
;                    int Z, int Mt, int Nt, int GM, int K, char* smem, const Epi& epi, int vt) {
;     ...
;     for (int kt = 0; kt < NK; ++kt) {
;       constexpr int dummy = 0; (void)dummy;
;       const int u = kt & 1;
;       const u16* as = As + u * 256 * 72 + (128 * wm + r) * 72 + 8 * h;
;       const u16* bs = Bs + u * BN * 72 + (32 * TJ * wn + r) * 72 + 8 * h;
;       if (kt == 0) {
; #pragma unroll
;         for (int i = 0; i < 4; ++i) af[0][i] = *(const bf16x8*)(as + (32 * i) * 72);
; #pragma unroll
;         for (int j = 0; j < TJ; ++j) bfr[0][j] = *(const bf16x8*)(bs + (32 * j) * 72);
;       }
; #pragma unroll
;       for (int ks = 0; ks < 4; ++ks) {
;         if (ks < 3) {
; #pragma unroll
;           for (int i = 0; i < 4; ++i) af[(ks + 1) & 1][i] = *(const bf16x8*)(as + (32 * i) * 72 + 16 * (ks + 1));
; #pragma unroll
;           for (int j = 0; j < TJ; ++j) bfr[(ks + 1) & 1][j] = *(const bf16x8*)(bs + (32 * j) * 72 + 16 * (ks + 1));
;         } else if (kt + 1 < NK) {
;           const u16* asn = As + (u ^ 1) * 256 * 72 + (128 * wm + r) * 72 + 8 * h;
;           const u16* bsn = Bs + (u ^ 1) * BN * 72 + (32 * TJ * wn + r) * 72 + 8 * h;
; #pragma unroll
;           for (int i = 0; i < 4; ++i) af[0][i] = *(const bf16x8*)(asn + (32 * i) * 72);
; #pragma unroll
;           for (int j = 0; j < TJ; ++j) bfr[0][j] = *(const bf16x8*)(bsn + (32 * j) * 72);
;         }
;         __builtin_amdgcn_sched_barrier(0);
; #pragma unroll
;         for (int i = 0; i < 4; ++i)
; #pragma unroll
;           for (int j = 0; j < TJ; ++j)
;             acc[i][j] = SWAP ? MFMA32(bfr[ks & 1][j], af[ks & 1][i], acc[i][j]) : MFMA32(af[ks & 1][i], bfr[ks & 1][j], acc[i][j]);
;         if (ks == 0 && kt + 2 < NK) {
;           const u16* ag = Ag + (kt + 2) * 64;
; #pragma unroll
;           for (int i = 0; i < 8; ++i) ra[u][i] = *(const u32x4*)(ag + aoff[i]);
; #pragma unroll
;           for (int i = 0; i < 8; ++i) { __builtin_amdgcn_sched_group_barrier(0x008, 1, 0); __builtin_amdgcn_sched_group_barrier(0x020, 1, 0); }
;         }
;         if (ks == 2 && kt + 2 < NK) {
;           const u16* bg = Bg + (kt + 2) * 64;
; #pragma unroll
	v_mfma_f32_32x32x16_bf16 a[112:127], v[16:19], v[0:3], a[112:127]
	s_waitcnt lgkmcnt(6)
	v_mfma_f32_32x32x16_bf16 a[96:111], v[20:23], v[0:3], a[96:111]
	v_mfma_f32_32x32x16_bf16 a[80:95], v[16:19], v[4:7], a[80:95]
	v_mfma_f32_32x32x16_bf16 a[64:79], v[20:23], v[4:7], a[64:79]
	v_mfma_f32_32x32x16_bf16 a[48:63], v[16:19], v[8:11], a[48:63]
	v_mfma_f32_32x32x16_bf16 a[32:47], v[20:23], v[8:11], a[32:47]
	v_mfma_f32_32x32x16_bf16 a[16:31], v[16:19], v[12:15], a[16:31]
	v_mfma_f32_32x32x16_bf16 a[0:15], v[20:23], v[12:15], a[0:15]
	ds_read_b128 v[0:3], v70 offset:36960
	ds_read_b128 v[4:7], v70 offset:41568
	ds_read_b128 v[8:11], v70 offset:46176
	ds_read_b128 v[12:15], v70 offset:50784
	ds_read_b128 v[16:19], v71 offset:18528
	ds_read_b128 v[20:23], v71 offset:23136
	s_waitcnt lgkmcnt(7)
	v_mfma_f32_32x32x16_bf16 a[112:127], v[40:43], v[24:27], a[112:127]
	s_waitcnt lgkmcnt(6)
	v_mfma_f32_32x32x16_bf16 a[96:111], v[44:47], v[24:27], a[96:111]
	v_mfma_f32_32x32x16_bf16 a[80:95], v[40:43], v[28:31], a[80:95]
	v_mfma_f32_32x32x16_bf16 a[64:79], v[44:47], v[28:31], a[64:79]
	v_mfma_f32_32x32x16_bf16 a[48:63], v[40:43], v[32:35], a[48:63]
	v_mfma_f32_32x32x16_bf16 a[32:47], v[44:47], v[32:35], a[32:47]
	v_mfma_f32_32x32x16_bf16 a[16:31], v[40:43], v[36:39], a[16:31]
	v_mfma_f32_32x32x16_bf16 a[0:15], v[44:47], v[36:39], a[0:15]
	s_waitcnt lgkmcnt(0)
	s_barrier
	v_mfma_f32_32x32x16_bf16 a[112:127], v[16:19], v[0:3], a[112:127]
	v_mfma_f32_32x32x16_bf16 a[96:111], v[20:23], v[0:3], a[96:111]
	v_mfma_f32_32x32x16_bf16 a[80:95], v[16:19], v[4:7], a[80:95]
	v_mfma_f32_32x32x16_bf16 a[64:79], v[20:23], v[4:7], a[64:79]
	v_mfma_f32_32x32x16_bf16 a[48:63], v[16:19], v[8:11], a[48:63]
	v_mfma_f32_32x32x16_bf16 a[32:47], v[20:23], v[8:11], a[32:47]
	v_mfma_f32_32x32x16_bf16 a[16:31], v[16:19], v[12:15], a[16:31]
	v_mfma_f32_32x32x16_bf16 a[0:15], v[20:23], v[12:15], a[0:15]
	v_readlane_b32 s8, v255, 20
	v_readlane_b32 s9, v255, 21
	s_andn2_b64 vcc, exec, s[8:9]
	s_cbranch_vccnz .LBB0_427
	s_nop 0
	v_add_u32_e32 v18, s0, v106
	v_or_b32_e32 v16, s6, v107
	s_movk_i32 s0, 0x1c80
	v_cmp_gt_i32_e32 vcc, s0, v16
	s_cbranch_vccz .Lmy_epi_done_rw
	v_and_b32_e32 v17, 4, v16
	v_add_u32_e32 v16, v16, v17
	v_mov_b32_e32 v17, 0
	v_mov_b64_e32 v[0:1], s[2:3]
	v_mad_i64_i32 v[0:1], s[6:7], v18, s66, v[0:1]
	v_lshl_add_u64 v[0:1], v[16:17], 1, v[0:1]
	s_mov_b32 s0, 0x72000
	s_mov_b32 s1, 0
	v_lshl_add_u64 v[2:3], s[0:1], 0, v[0:1]
	v_lshl_add_u64 v[4:5], s[0:1], 0, v[2:3]
	v_lshl_add_u64 v[6:7], s[0:1], 0, v[4:5]
	v_accvgpr_read_b32 v8, a112
	v_accvgpr_read_b32 v9, a113
	v_accvgpr_read_b32 v10, a114
	v_accvgpr_read_b32 v11, a115
	v_accvgpr_read_b32 v16, a116
	v_accvgpr_read_b32 v17, a117
	v_accvgpr_read_b32 v18, a118
	v_accvgpr_read_b32 v19, a119
	v_cvt_pk_bf16_f32 v12, v8, v9
	v_cvt_pk_bf16_f32 v13, v10, v11
	v_cvt_pk_bf16_f32 v14, v16, v17
	v_cvt_pk_bf16_f32 v15, v18, v19
	s_nop 1
	v_permlane32_swap_b32_e32 v12, v14
	v_permlane32_swap_b32_e32 v13, v15
	global_store_dwordx4 v[0:1], v[12:15], off
	v_accvgpr_read_b32 v8, a120
	v_accvgpr_read_b32 v9, a121
	v_accvgpr_read_b32 v10, a122
	v_accvgpr_read_b32 v11, a123
	v_accvgpr_read_b32 v16, a124
	v_accvgpr_read_b32 v17, a125
	v_accvgpr_read_b32 v18, a126
	v_accvgpr_read_b32 v19, a127
	v_cvt_pk_bf16_f32 v12, v8, v9
	v_cvt_pk_bf16_f32 v13, v10, v11
	v_cvt_pk_bf16_f32 v14, v16, v17
	v_cvt_pk_bf16_f32 v15, v18, v19
	s_nop 1
	v_permlane32_swap_b32_e32 v12, v14
	v_permlane32_swap_b32_e32 v13, v15
	global_store_dwordx4 v[0:1], v[12:15], off offset:32
	v_accvgpr_read_b32 v8, a96
	v_accvgpr_read_b32 v9, a97
	v_accvgpr_read_b32 v10, a98
	v_accvgpr_read_b32 v11, a99
	v_accvgpr_read_b32 v16, a100
	v_accvgpr_read_b32 v17, a101
	v_accvgpr_read_b32 v18, a102
	v_accvgpr_read_b32 v19, a103
	v_cvt_pk_bf16_f32 v12, v8, v9
	v_cvt_pk_bf16_f32 v13, v10, v11
	v_cvt_pk_bf16_f32 v14, v16, v17
	v_cvt_pk_bf16_f32 v15, v18, v19
	s_nop 1
	v_permlane32_swap_b32_e32 v12, v14
	v_permlane32_swap_b32_e32 v13, v15
	global_store_dwordx4 v[0:1], v[12:15], off offset:64
	v_accvgpr_read_b32 v8, a104
	v_accvgpr_read_b32 v9, a105
	v_accvgpr_read_b32 v10, a106
	v_accvgpr_read_b32 v11, a107
	v_accvgpr_read_b32 v16, a108
	v_accvgpr_read_b32 v17, a109
	v_accvgpr_read_b32 v18, a110
	v_accvgpr_read_b32 v19, a111
	v_cvt_pk_bf16_f32 v12, v8, v9
	v_cvt_pk_bf16_f32 v13, v10, v11
	v_cvt_pk_bf16_f32 v14, v16, v17
	v_cvt_pk_bf16_f32 v15, v18, v19
	s_nop 1
	v_permlane32_swap_b32_e32 v12, v14
	v_permlane32_swap_b32_e32 v13, v15
	global_store_dwordx4 v[0:1], v[12:15], off offset:96
	v_accvgpr_read_b32 v8, a80
	v_accvgpr_read_b32 v9, a81
	v_accvgpr_read_b32 v10, a82
	v_accvgpr_read_b32 v11, a83
	v_accvgpr_read_b32 v16, a84
	v_accvgpr_read_b32 v17, a85
	v_accvgpr_read_b32 v18, a86
	v_accvgpr_read_b32 v19, a87
	v_cvt_pk_bf16_f32 v12, v8, v9
	v_cvt_pk_bf16_f32 v13, v10, v11
	v_cvt_pk_bf16_f32 v14, v16, v17
	v_cvt_pk_bf16_f32 v15, v18, v19
	s_nop 1
	v_permlane32_swap_b32_e32 v12, v14
	v_permlane32_swap_b32_e32 v13, v15
	global_store_dwordx4 v[2:3], v[12:15], off
	v_accvgpr_read_b32 v8, a88
	v_accvgpr_read_b32 v9, a89
	v_accvgpr_read_b32 v10, a90
	v_accvgpr_read_b32 v11, a91
	v_accvgpr_read_b32 v16, a92
	v_accvgpr_read_b32 v17, a93
	v_accvgpr_read_b32 v18, a94
	v_accvgpr_read_b32 v19, a95
; DI unsigned pack2(float a, float b) { f2_t v = {a, b}; bf2_t r = __builtin_convertvector(v, bf2_t); return __builtin_bit_cast(unsigned, r); }
; template <int TJ, bool SWAP, int NK, class Epi>
; DI void gemm_phase(const u16* __restrict__ A, size_t strideAz, int lda, const u16* __restrict__ Bt, size_t strideBz, int ldb,
;                    int Z, int Mt, int Nt, int GM, int K, char* smem, const Epi& epi, int vt) {
;     ...
; #pragma unroll
;     for (int i = 0; i < 4; ++i)
; #pragma unroll
;       for (int j = 0; j < TJ; ++j) {
;         if (SWAP) epi(z, mt * 256 + 128 * wm + 32 * i + r, nt * BN + 32 * TJ * wn + 32 * j, h, acc[i][j]);
;         else epi(z, mt * 256 + 128 * wm + 32 * i, nt * BN + 32 * TJ * wn + 32 * j + r, h, acc[i][j]);
;       }
;   }
; }
;   DI void operator()(int z, int row, int colbase, int h, const f32x16& a) const {
;     if (dry) return;
; #pragma unroll
;     for (int g = 0; g < 4; ++g) {
;       const int col = colbase + 8 * g + 4 * h;
;       if (col < ncols) {
;         u32x2 pk = {pack2(a[4 * g], a[4 * g + 1]), pack2(a[4 * g + 2], a[4 * g + 3])};
;         *(u32x2*)(C + (size_t)row * ldc + col) = pk;
;       }
;     }
;   }
	v_cvt_pk_bf16_f32 v12, v8, v9
	v_cvt_pk_bf16_f32 v13, v10, v11
	v_cvt_pk_bf16_f32 v14, v16, v17
	v_cvt_pk_bf16_f32 v15, v18, v19
	s_nop 1
	v_permlane32_swap_b32_e32 v12, v14
	v_permlane32_swap_b32_e32 v13, v15
	global_store_dwordx4 v[2:3], v[12:15], off offset:32
	v_accvgpr_read_b32 v8, a64
	v_accvgpr_read_b32 v9, a65
	v_accvgpr_read_b32 v10, a66
	v_accvgpr_read_b32 v11, a67
	v_accvgpr_read_b32 v16, a68
	v_accvgpr_read_b32 v17, a69
	v_accvgpr_read_b32 v18, a70
	v_accvgpr_read_b32 v19, a71
	v_cvt_pk_bf16_f32 v12, v8, v9
	v_cvt_pk_bf16_f32 v13, v10, v11
	v_cvt_pk_bf16_f32 v14, v16, v17
	v_cvt_pk_bf16_f32 v15, v18, v19
	s_nop 1
	v_permlane32_swap_b32_e32 v12, v14
	v_permlane32_swap_b32_e32 v13, v15
	global_store_dwordx4 v[2:3], v[12:15], off offset:64
	v_accvgpr_read_b32 v8, a72
	v_accvgpr_read_b32 v9, a73
	v_accvgpr_read_b32 v10, a74
	v_accvgpr_read_b32 v11, a75
	v_accvgpr_read_b32 v16, a76
	v_accvgpr_read_b32 v17, a77
	v_accvgpr_read_b32 v18, a78
	v_accvgpr_read_b32 v19, a79
	v_cvt_pk_bf16_f32 v12, v8, v9
	v_cvt_pk_bf16_f32 v13, v10, v11
	v_cvt_pk_bf16_f32 v14, v16, v17
	v_cvt_pk_bf16_f32 v15, v18, v19
	s_nop 1
	v_permlane32_swap_b32_e32 v12, v14
	v_permlane32_swap_b32_e32 v13, v15
	global_store_dwordx4 v[2:3], v[12:15], off offset:96
	v_accvgpr_read_b32 v8, a48
	v_accvgpr_read_b32 v9, a49
	v_accvgpr_read_b32 v10, a50
	v_accvgpr_read_b32 v11, a51
	v_accvgpr_read_b32 v16, a52
	v_accvgpr_read_b32 v17, a53
	v_accvgpr_read_b32 v18, a54
	v_accvgpr_read_b32 v19, a55
	v_cvt_pk_bf16_f32 v12, v8, v9
	v_cvt_pk_bf16_f32 v13, v10, v11
	v_cvt_pk_bf16_f32 v14, v16, v17
	v_cvt_pk_bf16_f32 v15, v18, v19
	s_nop 1
	v_permlane32_swap_b32_e32 v12, v14
	v_permlane32_swap_b32_e32 v13, v15
	global_store_dwordx4 v[4:5], v[12:15], off
	v_accvgpr_read_b32 v8, a56
	v_accvgpr_read_b32 v9, a57
	v_accvgpr_read_b32 v10, a58
	v_accvgpr_read_b32 v11, a59
	v_accvgpr_read_b32 v16, a60
	v_accvgpr_read_b32 v17, a61
	v_accvgpr_read_b32 v18, a62
	v_accvgpr_read_b32 v19, a63
	v_cvt_pk_bf16_f32 v12, v8, v9
	v_cvt_pk_bf16_f32 v13, v10, v11
	v_cvt_pk_bf16_f32 v14, v16, v17
	v_cvt_pk_bf16_f32 v15, v18, v19
	s_nop 1
	v_permlane32_swap_b32_e32 v12, v14
	v_permlane32_swap_b32_e32 v13, v15
	global_store_dwordx4 v[4:5], v[12:15], off offset:32
	v_accvgpr_read_b32 v8, a32
	v_accvgpr_read_b32 v9, a33
	v_accvgpr_read_b32 v10, a34
	v_accvgpr_read_b32 v11, a35
	v_accvgpr_read_b32 v16, a36
	v_accvgpr_read_b32 v17, a37
	v_accvgpr_read_b32 v18, a38
	v_accvgpr_read_b32 v19, a39
	v_cvt_pk_bf16_f32 v12, v8, v9
	v_cvt_pk_bf16_f32 v13, v10, v11
	v_cvt_pk_bf16_f32 v14, v16, v17
	v_cvt_pk_bf16_f32 v15, v18, v19
	s_nop 1
	v_permlane32_swap_b32_e32 v12, v14
	v_permlane32_swap_b32_e32 v13, v15
	global_store_dwordx4 v[4:5], v[12:15], off offset:64
	v_accvgpr_read_b32 v8, a40
	v_accvgpr_read_b32 v9, a41
	v_accvgpr_read_b32 v10, a42
	v_accvgpr_read_b32 v11, a43
	v_accvgpr_read_b32 v16, a44
	v_accvgpr_read_b32 v17, a45
	v_accvgpr_read_b32 v18, a46
	v_accvgpr_read_b32 v19, a47
	v_cvt_pk_bf16_f32 v12, v8, v9
	v_cvt_pk_bf16_f32 v13, v10, v11
	v_cvt_pk_bf16_f32 v14, v16, v17
	v_cvt_pk_bf16_f32 v15, v18, v19
	s_nop 1
	v_permlane32_swap_b32_e32 v12, v14
	v_permlane32_swap_b32_e32 v13, v15
	global_store_dwordx4 v[4:5], v[12:15], off offset:96
	v_accvgpr_read_b32 v8, a16
	v_accvgpr_read_b32 v9, a17
	v_accvgpr_read_b32 v10, a18
	v_accvgpr_read_b32 v11, a19
	v_accvgpr_read_b32 v16, a20
	v_accvgpr_read_b32 v17, a21
	v_accvgpr_read_b32 v18, a22
	v_accvgpr_read_b32 v19, a23
	v_cvt_pk_bf16_f32 v12, v8, v9
	v_cvt_pk_bf16_f32 v13, v10, v11
	v_cvt_pk_bf16_f32 v14, v16, v17
	v_cvt_pk_bf16_f32 v15, v18, v19
	s_nop 1
	v_permlane32_swap_b32_e32 v12, v14
	v_permlane32_swap_b32_e32 v13, v15
	global_store_dwordx4 v[6:7], v[12:15], off
	v_accvgpr_read_b32 v8, a24
	v_accvgpr_read_b32 v9, a25
	v_accvgpr_read_b32 v10, a26
	v_accvgpr_read_b32 v11, a27
	v_accvgpr_read_b32 v16, a28
	v_accvgpr_read_b32 v17, a29
	v_accvgpr_read_b32 v18, a30
	v_accvgpr_read_b32 v19, a31
	v_cvt_pk_bf16_f32 v12, v8, v9
	v_cvt_pk_bf16_f32 v13, v10, v11
	v_cvt_pk_bf16_f32 v14, v16, v17
	v_cvt_pk_bf16_f32 v15, v18, v19
	s_nop 1
	v_permlane32_swap_b32_e32 v12, v14
	v_permlane32_swap_b32_e32 v13, v15
	global_store_dwordx4 v[6:7], v[12:15], off offset:32
	v_accvgpr_read_b32 v8, a0
	v_accvgpr_read_b32 v9, a1
	v_accvgpr_read_b32 v10, a2
	v_accvgpr_read_b32 v11, a3
	v_accvgpr_read_b32 v16, a4
	v_accvgpr_read_b32 v17, a5
	v_accvgpr_read_b32 v18, a6
	v_accvgpr_read_b32 v19, a7
	v_cvt_pk_bf16_f32 v12, v8, v9
	v_cvt_pk_bf16_f32 v13, v10, v11
	v_cvt_pk_bf16_f32 v14, v16, v17
	v_cvt_pk_bf16_f32 v15, v18, v19
	s_nop 1
	v_permlane32_swap_b32_e32 v12, v14
	v_permlane32_swap_b32_e32 v13, v15
	global_store_dwordx4 v[6:7], v[12:15], off offset:64
	v_accvgpr_read_b32 v8, a8
	v_accvgpr_read_b32 v9, a9
	v_accvgpr_read_b32 v10, a10
	v_accvgpr_read_b32 v11, a11
	v_accvgpr_read_b32 v16, a12
	v_accvgpr_read_b32 v17, a13
	v_accvgpr_read_b32 v18, a14
	v_accvgpr_read_b32 v19, a15
	v_cvt_pk_bf16_f32 v12, v8, v9
	v_cvt_pk_bf16_f32 v13, v10, v11
	v_cvt_pk_bf16_f32 v14, v16, v17
	v_cvt_pk_bf16_f32 v15, v18, v19
	s_nop 1
	v_permlane32_swap_b32_e32 v12, v14
	v_permlane32_swap_b32_e32 v13, v15
	global_store_dwordx4 v[6:7], v[12:15], off offset:96
.Lmy_epi_done_rw:
	s_branch .LBB0_427
.LBB0_494:
	s_mov_b64 s[0:1], 0

; template <int TJ, bool SWAP, int NK, class Epi>
; DI void gemm_phase(const u16* __restrict__ A, size_t strideAz, int lda, const u16* __restrict__ Bt, size_t strideBz, int ldb,
;                    int Z, int Mt, int Nt, int GM, int K, char* smem, const Epi& epi, int vt) {
;     ...
;   for (int base = 0; base < total; base += G) {
;     const int q = base + vt;
;     if (q >= total) continue;
;     const int z = q / per, qq = q - z * per;
;     const int grp = qq / (GM * Nt), within = qq - grp * GM * Nt;
;     const int mt = grp * GM + (within % GM), nt = within / GM;
;     const u16* Ag = A + z * strideAz + (size_t)(mt * 256) * lda;
;     const u16* Bg = Bt + z * strideBz + (size_t)(nt * BN) * ldb;
;     u32x4 ra[2][8], rb[2][NB];
;     f32x16 acc[4][TJ];
; #pragma unroll
;     for (int i = 0; i < 4; ++i)
; #pragma unroll
;       for (int j = 0; j < TJ; ++j)
; #pragma unroll
;         for (int e = 0; e < 16; ++e) acc[i][j][e] = 0.f;
;     __syncthreads();
; #pragma unroll
;     for (int i = 0; i < 8; ++i) ra[0][i] = *(const u32x4*)(Ag + aoff[i]);
; #pragma unroll
;     for (int i = 0; i < NB; ++i) rb[0][i] = *(const u32x4*)(Bg + boff[i]);
; #pragma unroll
;     for (int i = 0; i < 8; ++i) ra[1][i] = *(const u32x4*)(Ag + 64 + aoff[i]);
; #pragma unroll
;     for (int i = 0; i < NB; ++i) rb[1][i] = *(const u32x4*)(Bg + 64 + boff[i]);
; #pragma unroll
;     for (int i = 0; i < 8; ++i) *(u32x4*)(As + lds_st + (32 * i) * 72) = ra[0][i];
; #pragma unroll
;     for (int i = 0; i < NB; ++i) *(u32x4*)(Bs + lds_st + (32 * i) * 72) = rb[0][i];
;     __syncthreads();
;     bf16x8 af[2][4], bfr[2][TJ];
; #pragma unroll
;     for (int kt = 0; kt < NK; ++kt) {
;       constexpr int dummy = 0; (void)dummy;
;       const int u = kt & 1;
;       const u16* as = As + u * 256 * 72 + (128 * wm + r) * 72 + 8 * h;
;       const u16* bs = Bs + u * BN * 72 + (32 * TJ * wn + r) * 72 + 8 * h;
;       if (kt == 0) {
; #pragma unroll
;         for (int i = 0; i < 4; ++i) af[0][i] = *(const bf16x8*)(as + (32 * i) * 72);
; #pragma unroll
;         for (int j = 0; j < TJ; ++j) bfr[0][j] = *(const bf16x8*)(bs + (32 * j) * 72);
;       }
; #pragma unroll
;       for (int ks = 0; ks < 4; ++ks) {
;         if (ks < 3) {
; #pragma unroll
;           for (int i = 0; i < 4; ++i) af[(ks + 1) & 1][i] = *(const bf16x8*)(as + (32 * i) * 72 + 16 * (ks + 1));
; #pragma unroll
.LBB0_499:
	s_add_i32 s0, s94, s20
	s_cmpk_gt_i32 s0, 0x67f
	s_cbranch_scc1 .LBB0_498
	s_mul_hi_i32 s1, s0, 0x4ec4ec4f
	s_lshr_b32 s6, s1, 31
	s_ashr_i32 s1, s1, 9
	s_add_i32 s1, s1, s6
	s_mulk_i32 s1, 0x680
	s_sub_i32 s0, s0, s1
	s_mul_i32 s1, s0, 0x4ec5
	s_lshr_b32 s6, s1, 31
	s_ashr_i32 s1, s1, 21
	s_add_i32 s1, s1, s6
	s_sext_i32_i16 s1, s1
	s_mul_i32 s6, s1, 0xff98
	s_add_i32 s0, s6, s0
	s_sext_i32_i16 s6, s0
	s_bfe_u32 s6, s6, 0x2001d
	s_add_i32 s6, s0, s6
	s_sext_i32_i16 s7, s6
	s_and_b32 s6, s6, 0xfffc
	s_sub_i32 s0, s0, s6
	s_sext_i32_i16 s0, s0
	s_lshl_b32 s1, s1, 10
	s_lshl_b32 s0, s0, 8
	s_add_i32 s0, s0, s1
	s_ashr_i32 s1, s0, 31
	s_lshl_b64 s[8:9], s[0:1], 11
	s_lshl_b32 s1, s7, 5
	s_and_b32 s6, s1, 0xffffff80
	s_ashr_i32 s7, s6, 31
	s_lshl_b64 s[10:11], s[6:7], 11
	v_readlane_b32 s12, v252, 54
	v_readlane_b32 s13, v252, 55
	s_add_u32 s8, s12, s8
	s_addc_u32 s9, s13, s9
	v_readlane_b32 s1, v255, 2
	v_lshl_add_u64 v[102:103], s[8:9], 0, v[72:73]
	v_lshl_add_u64 v[100:101], s[8:9], 0, v[74:75]
	v_lshl_add_u64 v[98:99], s[8:9], 0, v[76:77]
	v_lshl_add_u64 v[96:97], s[8:9], 0, v[78:79]
	v_lshl_add_u64 v[94:95], v[198:199], 1, s[8:9]
	v_lshl_add_u64 v[92:93], v[64:65], 1, s[8:9]
	v_lshl_add_u64 v[90:91], v[66:67], 1, s[8:9]
	v_lshl_add_u64 v[88:89], v[68:69], 1, s[8:9]
	s_add_u32 s8, s1, s10
	v_readlane_b32 s1, v255, 3
	s_addc_u32 s9, s1, s11
	v_lshl_add_u64 v[86:87], s[8:9], 0, v[72:73]
	v_lshl_add_u64 v[84:85], s[8:9], 0, v[74:75]
	v_lshl_add_u64 v[82:83], s[8:9], 0, v[76:77]
	v_lshl_add_u64 v[80:81], s[8:9], 0, v[78:79]
	s_barrier
	global_load_dwordx4 v[0:3], v[102:103], off
	global_load_dwordx4 v[4:7], v[100:101], off
	global_load_dwordx4 v[8:11], v[98:99], off
	global_load_dwordx4 v[12:15], v[96:97], off
	global_load_dwordx4 v[16:19], v[94:95], off
	global_load_dwordx4 v[20:23], v[92:93], off
	global_load_dwordx4 v[24:27], v[90:91], off
	global_load_dwordx4 v[28:31], v[88:89], off
	global_load_dwordx4 v[32:35], v[86:87], off
	global_load_dwordx4 v[36:39], v[84:85], off
	global_load_dwordx4 v[40:43], v[82:83], off
	global_load_dwordx4 v[44:47], v[80:81], off
	global_load_dwordx4 v[52:55], v[102:103], off offset:128
	global_load_dwordx4 v[60:63], v[100:101], off offset:128
	global_load_dwordx4 v[110:113], v[98:99], off offset:128
	global_load_dwordx4 v[114:117], v[96:97], off offset:128
	global_load_dwordx4 v[118:121], v[94:95], off offset:128
	global_load_dwordx4 v[122:125], v[92:93], off offset:128
	global_load_dwordx4 v[126:129], v[90:91], off offset:128
	global_load_dwordx4 v[130:133], v[88:89], off offset:128
	global_load_dwordx4 v[134:137], v[86:87], off offset:128
	global_load_dwordx4 v[138:141], v[84:85], off offset:128
	global_load_dwordx4 v[142:145], v[82:83], off offset:128
	global_load_dwordx4 v[146:149], v[80:81], off offset:128
	s_waitcnt vmcnt(23)
	ds_write_b128 v104, v[0:3]
	s_waitcnt vmcnt(22)
	ds_write_b128 v104, v[4:7] offset:4608
	s_waitcnt vmcnt(21)
	ds_write_b128 v104, v[8:11] offset:9216
	s_waitcnt vmcnt(20)
	ds_write_b128 v104, v[12:15] offset:13824
	s_waitcnt vmcnt(19)
	ds_write_b128 v104, v[16:19] offset:18432
	s_waitcnt vmcnt(18)
	ds_write_b128 v104, v[20:23] offset:23040
	s_waitcnt vmcnt(17)
	ds_write_b128 v104, v[24:27] offset:27648
	s_waitcnt vmcnt(16)
	ds_write_b128 v104, v[28:31] offset:32256
	s_waitcnt vmcnt(15)
	ds_write_b128 v105, v[32:35]
	s_waitcnt vmcnt(14)
	ds_write_b128 v105, v[36:39] offset:4608
	s_waitcnt vmcnt(13)
	ds_write_b128 v105, v[40:43] offset:9216
	s_waitcnt vmcnt(12)
	ds_write_b128 v105, v[44:47] offset:13824
	s_waitcnt lgkmcnt(0)
	s_barrier
	ds_read_b128 v[0:3], v70
	ds_read_b128 v[4:7], v70 offset:32
	ds_read_b128 v[8:11], v70 offset:4608
	ds_read_b128 v[12:15], v70 offset:4640
	ds_read_b128 v[16:19], v70 offset:9216
	ds_read_b128 v[20:23], v70 offset:9248
	ds_read_b128 v[24:27], v70 offset:13824
	ds_read_b128 v[28:31], v70 offset:13856
	ds_read_b128 v[32:35], v71
	ds_read_b128 v[36:39], v71 offset:32
	ds_read_b128 v[40:43], v71 offset:4608
	ds_read_b128 v[44:47], v71 offset:4640
	s_waitcnt lgkmcnt(3)
	v_mfma_f32_32x32x16_bf16 a[112:127], v[32:35], v[0:3], 0
	global_load_dwordx4 v[48:51], v[90:91], off offset:256
	s_waitcnt lgkmcnt(1)
	v_mfma_f32_32x32x16_bf16 a[96:111], v[40:43], v[0:3], 0
	global_load_dwordx4 v[0:3], v[102:103], off offset:256
	v_mfma_f32_32x32x16_bf16 a[80:95], v[32:35], v[8:11], 0
	global_load_dwordx4 v[56:59], v[88:89], off offset:256
	v_mfma_f32_32x32x16_bf16 a[64:79], v[40:43], v[8:11], 0
	global_load_dwordx4 v[8:11], v[100:101], off offset:256
	v_mfma_f32_32x32x16_bf16 a[48:63], v[32:35], v[16:19], 0
	v_mfma_f32_32x32x16_bf16 a[32:47], v[40:43], v[16:19], 0
	v_mfma_f32_32x32x16_bf16 a[0:15], v[40:43], v[24:27], 0
	global_load_dwordx4 v[40:43], v[92:93], off offset:256
	global_load_dwordx4 v[16:19], v[98:99], off offset:256
	v_mfma_f32_32x32x16_bf16 a[16:31], v[32:35], v[24:27], 0
	global_load_dwordx4 v[32:35], v[94:95], off offset:256
	global_load_dwordx4 v[24:27], v[96:97], off offset:256
	ds_read_b128 v[150:153], v70 offset:64
	ds_read_b128 v[154:157], v70 offset:4672
	ds_read_b128 v[158:161], v70 offset:9280
	ds_read_b128 v[162:165], v70 offset:13888
	ds_read_b128 v[166:169], v71 offset:64
	ds_read_b128 v[170:173], v71 offset:4672
	v_mfma_f32_32x32x16_bf16 a[112:127], v[36:39], v[4:7], a[112:127]
	s_waitcnt vmcnt(19)
	ds_write_b128 v104, v[52:55] offset:36864
	s_waitcnt vmcnt(18)
	ds_write_b128 v104, v[60:63] offset:41472
	s_waitcnt lgkmcnt(8)
	v_mfma_f32_32x32x16_bf16 a[96:111], v[44:47], v[4:7], a[96:111]
	s_waitcnt vmcnt(17)
	ds_write_b128 v104, v[110:113] offset:46080
	s_waitcnt vmcnt(16)
; template <int TJ, bool SWAP, int NK, class Epi>
; DI void gemm_phase(const u16* __restrict__ A, size_t strideAz, int lda, const u16* __restrict__ Bt, size_t strideBz, int ldb,
;                    int Z, int Mt, int Nt, int GM, int K, char* smem, const Epi& epi, int vt) {
;     ...
;     for (int kt = 0; kt < NK; ++kt) {
;       constexpr int dummy = 0; (void)dummy;
;       const int u = kt & 1;
;       const u16* as = As + u * 256 * 72 + (128 * wm + r) * 72 + 8 * h;
;       const u16* bs = Bs + u * BN * 72 + (32 * TJ * wn + r) * 72 + 8 * h;
;       if (kt == 0) {
; #pragma unroll
;         for (int i = 0; i < 4; ++i) af[0][i] = *(const bf16x8*)(as + (32 * i) * 72);
; #pragma unroll
;         for (int j = 0; j < TJ; ++j) bfr[0][j] = *(const bf16x8*)(bs + (32 * j) * 72);
;       }
; #pragma unroll
;       for (int ks = 0; ks < 4; ++ks) {
;         if (ks < 3) {
; #pragma unroll
;           for (int i = 0; i < 4; ++i) af[(ks + 1) & 1][i] = *(const bf16x8*)(as + (32 * i) * 72 + 16 * (ks + 1));
; #pragma unroll
;           for (int j = 0; j < TJ; ++j) bfr[(ks + 1) & 1][j] = *(const bf16x8*)(bs + (32 * j) * 72 + 16 * (ks + 1));
;         } else if (kt + 1 < NK) {
;           const u16* asn = As + (u ^ 1) * 256 * 72 + (128 * wm + r) * 72 + 8 * h;
;           const u16* bsn = Bs + (u ^ 1) * BN * 72 + (32 * TJ * wn + r) * 72 + 8 * h;
; #pragma unroll
;           for (int i = 0; i < 4; ++i) af[0][i] = *(const bf16x8*)(asn + (32 * i) * 72);
; #pragma unroll
;           for (int j = 0; j < TJ; ++j) bfr[0][j] = *(const bf16x8*)(bsn + (32 * j) * 72);
;         }
;         __builtin_amdgcn_sched_barrier(0);
; #pragma unroll
;         for (int i = 0; i < 4; ++i)
; #pragma unroll
;           for (int j = 0; j < TJ; ++j)
;             acc[i][j] = SWAP ? MFMA32(bfr[ks & 1][j], af[ks & 1][i], acc[i][j]) : MFMA32(af[ks & 1][i], bfr[ks & 1][j], acc[i][j]);
;         if (ks == 0 && kt + 2 < NK) {
;           const u16* ag = Ag + (kt + 2) * 64;
; #pragma unroll
;           for (int i = 0; i < 8; ++i) ra[u][i] = *(const u32x4*)(ag + aoff[i]);
; #pragma unroll
;           for (int i = 0; i < 8; ++i) { __builtin_amdgcn_sched_group_barrier(0x008, 1, 0); __builtin_amdgcn_sched_group_barrier(0x020, 1, 0); }
;         }
;         if (ks == 2 && kt + 2 < NK) {
;           const u16* bg = Bg + (kt + 2) * 64;
; #pragma unroll
	ds_write_b128 v104, v[114:117] offset:50688
	v_mfma_f32_32x32x16_bf16 a[80:95], v[36:39], v[12:15], a[80:95]
	s_waitcnt vmcnt(15)
	ds_write_b128 v104, v[118:121] offset:55296
	s_waitcnt vmcnt(14)
	ds_write_b128 v104, v[122:125] offset:59904
	v_mfma_f32_32x32x16_bf16 a[64:79], v[44:47], v[12:15], a[64:79]
	s_waitcnt vmcnt(13)
	ds_write_b128 v104, v[126:129] offset:64512
	s_waitcnt vmcnt(12)
	ds_write_b128 v108, v[130:133]
	v_mfma_f32_32x32x16_bf16 a[48:63], v[36:39], v[20:23], a[48:63]
	s_waitcnt vmcnt(11)
	ds_write_b128 v105, v[134:137] offset:18432
	s_waitcnt vmcnt(10)
	ds_write_b128 v105, v[138:141] offset:23040
	v_mfma_f32_32x32x16_bf16 a[32:47], v[44:47], v[20:23], a[32:47]
	s_waitcnt vmcnt(9)
	ds_write_b128 v105, v[142:145] offset:27648
	s_waitcnt vmcnt(8)
	ds_write_b128 v105, v[146:149] offset:32256
	v_mfma_f32_32x32x16_bf16 a[16:31], v[36:39], v[28:31], a[16:31]
	v_mfma_f32_32x32x16_bf16 a[0:15], v[44:47], v[28:31], a[0:15]
	ds_read_b128 v[4:7], v70 offset:96
	ds_read_b128 v[12:15], v70 offset:4704
	ds_read_b128 v[20:23], v70 offset:9312
	ds_read_b128 v[28:31], v70 offset:13920
	ds_read_b128 v[36:39], v71 offset:96
	ds_read_b128 v[44:47], v71 offset:4704
	s_waitcnt lgkmcnt(14)
	v_mfma_f32_32x32x16_bf16 a[112:127], v[166:169], v[150:153], a[112:127]
	global_load_dwordx4 v[110:113], v[86:87], off offset:256
	v_mfma_f32_32x32x16_bf16 a[96:111], v[170:173], v[150:153], a[96:111]
	global_load_dwordx4 v[114:117], v[84:85], off offset:256
	v_mfma_f32_32x32x16_bf16 a[80:95], v[166:169], v[154:157], a[80:95]
	global_load_dwordx4 v[118:121], v[82:83], off offset:256
	v_mfma_f32_32x32x16_bf16 a[64:79], v[170:173], v[154:157], a[64:79]
	global_load_dwordx4 v[122:125], v[80:81], off offset:256
	v_mfma_f32_32x32x16_bf16 a[48:63], v[166:169], v[158:161], a[48:63]
	v_mfma_f32_32x32x16_bf16 a[32:47], v[170:173], v[158:161], a[32:47]
	v_mfma_f32_32x32x16_bf16 a[16:31], v[166:169], v[162:165], a[16:31]
	v_mfma_f32_32x32x16_bf16 a[0:15], v[170:173], v[162:165], a[0:15]
	s_waitcnt lgkmcnt(0)
	s_barrier
	ds_read_b128 v[52:55], v70 offset:36864
	ds_read_b128 v[60:63], v70 offset:41472
	ds_read_b128 v[126:129], v70 offset:46080
	ds_read_b128 v[130:133], v70 offset:50688
	ds_read_b128 v[134:137], v71 offset:18432
	ds_read_b128 v[138:141], v71 offset:23040
	v_mfma_f32_32x32x16_bf16 a[112:127], v[36:39], v[4:7], a[112:127]
	v_mfma_f32_32x32x16_bf16 a[96:111], v[44:47], v[4:7], a[96:111]
	v_mfma_f32_32x32x16_bf16 a[80:95], v[36:39], v[12:15], a[80:95]
	v_mfma_f32_32x32x16_bf16 a[64:79], v[44:47], v[12:15], a[64:79]
	v_mfma_f32_32x32x16_bf16 a[48:63], v[36:39], v[20:23], a[48:63]
	v_mfma_f32_32x32x16_bf16 a[32:47], v[44:47], v[20:23], a[32:47]
	v_mfma_f32_32x32x16_bf16 a[16:31], v[36:39], v[28:31], a[16:31]
	v_mfma_f32_32x32x16_bf16 a[0:15], v[44:47], v[28:31], a[0:15]
	ds_read_b128 v[142:145], v70 offset:36896
	ds_read_b128 v[146:149], v70 offset:41504
	ds_read_b128 v[150:153], v70 offset:46112
	ds_read_b128 v[154:157], v70 offset:50720
	ds_read_b128 v[158:161], v71 offset:18464
	ds_read_b128 v[162:165], v71 offset:23072
	s_waitcnt lgkmcnt(7)
	v_mfma_f32_32x32x16_bf16 a[112:127], v[134:137], v[52:55], a[112:127]
	global_load_dwordx4 v[4:7], v[102:103], off offset:384
	s_waitcnt lgkmcnt(6)
	v_mfma_f32_32x32x16_bf16 a[96:111], v[138:141], v[52:55], a[96:111]
	global_load_dwordx4 v[12:15], v[100:101], off offset:384
	v_mfma_f32_32x32x16_bf16 a[80:95], v[134:137], v[60:63], a[80:95]
	global_load_dwordx4 v[20:23], v[98:99], off offset:384
	v_mfma_f32_32x32x16_bf16 a[64:79], v[138:141], v[60:63], a[64:79]
	global_load_dwordx4 v[28:31], v[96:97], off offset:384
	v_mfma_f32_32x32x16_bf16 a[48:63], v[134:137], v[126:129], a[48:63]
	global_load_dwordx4 v[36:39], v[94:95], off offset:384
	v_mfma_f32_32x32x16_bf16 a[32:47], v[138:141], v[126:129], a[32:47]
	global_load_dwordx4 v[44:47], v[92:93], off offset:384
	v_mfma_f32_32x32x16_bf16 a[16:31], v[134:137], v[130:133], a[16:31]
	global_load_dwordx4 v[52:55], v[90:91], off offset:384
	v_mfma_f32_32x32x16_bf16 a[0:15], v[138:141], v[130:133], a[0:15]
	global_load_dwordx4 v[60:63], v[88:89], off offset:384
	ds_read_b128 v[126:129], v70 offset:36928
	ds_read_b128 v[130:133], v70 offset:41536
	ds_read_b128 v[134:137], v70 offset:46144
	ds_read_b128 v[138:141], v70 offset:50752
	ds_read_b128 v[166:169], v71 offset:18496
	ds_read_b128 v[170:173], v71 offset:23104
	s_waitcnt lgkmcnt(7)
	v_mfma_f32_32x32x16_bf16 a[112:127], v[158:161], v[142:145], a[112:127]
	s_waitcnt vmcnt(18)
	ds_write_b128 v104, v[0:3]
	s_waitcnt vmcnt(16)
	ds_write_b128 v104, v[8:11] offset:4608
	s_waitcnt lgkmcnt(8)
	v_mfma_f32_32x32x16_bf16 a[96:111], v[162:165], v[142:145], a[96:111]
	s_waitcnt vmcnt(14)
	ds_write_b128 v104, v[16:19] offset:9216
	s_waitcnt vmcnt(12)
	ds_write_b128 v104, v[24:27] offset:13824
	v_mfma_f32_32x32x16_bf16 a[80:95], v[158:161], v[146:149], a[80:95]
	ds_write_b128 v104, v[32:35] offset:18432
	ds_write_b128 v104, v[40:43] offset:23040
	v_mfma_f32_32x32x16_bf16 a[64:79], v[162:165], v[146:149], a[64:79]
	ds_write_b128 v104, v[48:51] offset:27648
	ds_write_b128 v104, v[56:59] offset:32256
	v_mfma_f32_32x32x16_bf16 a[48:63], v[158:161], v[150:153], a[48:63]
	s_waitcnt vmcnt(11)
	ds_write_b128 v105, v[110:113]
	s_waitcnt vmcnt(10)
	ds_write_b128 v105, v[114:117] offset:4608
	v_mfma_f32_32x32x16_bf16 a[32:47], v[162:165], v[150:153], a[32:47]
	s_waitcnt vmcnt(9)
	ds_write_b128 v105, v[118:121] offset:9216
	s_waitcnt vmcnt(8)
	ds_write_b128 v105, v[122:125] offset:13824
	v_mfma_f32_32x32x16_bf16 a[16:31], v[158:161], v[154:157], a[16:31]
	v_mfma_f32_32x32x16_bf16 a[0:15], v[162:165], v[154:157], a[0:15]
	ds_read_b128 v[0:3], v70 offset:36960
	ds_read_b128 v[8:11], v70 offset:41568
	ds_read_b128 v[16:19], v70 offset:46176
	ds_read_b128 v[24:27], v70 offset:50784
	ds_read_b128 v[32:35], v71 offset:18528
	ds_read_b128 v[40:43], v71 offset:23136
	s_waitcnt lgkmcnt(14)
	v_mfma_f32_32x32x16_bf16 a[112:127], v[166:169], v[126:129], a[112:127]
	global_load_dwordx4 v[110:113], v[86:87], off offset:384
	v_mfma_f32_32x32x16_bf16 a[96:111], v[170:173], v[126:129], a[96:111]
	global_load_dwordx4 v[114:117], v[84:85], off offset:384
	v_mfma_f32_32x32x16_bf16 a[80:95], v[166:169], v[130:133], a[80:95]
	global_load_dwordx4 v[118:121], v[82:83], off offset:384
	v_mfma_f32_32x32x16_bf16 a[64:79], v[170:173], v[130:133], a[64:79]
	global_load_dwordx4 v[122:125], v[80:81], off offset:384
	v_mfma_f32_32x32x16_bf16 a[48:63], v[166:169], v[134:137], a[48:63]
	v_mfma_f32_32x32x16_bf16 a[32:47], v[170:173], v[134:137], a[32:47]
	v_mfma_f32_32x32x16_bf16 a[16:31], v[166:169], v[138:141], a[16:31]
	v_mfma_f32_32x32x16_bf16 a[0:15], v[170:173], v[138:141], a[0:15]
	s_waitcnt lgkmcnt(0)
	s_barrier
; template <int TJ, bool SWAP, int NK, class Epi>
; DI void gemm_phase(const u16* __restrict__ A, size_t strideAz, int lda, const u16* __restrict__ Bt, size_t strideBz, int ldb,
;                    int Z, int Mt, int Nt, int GM, int K, char* smem, const Epi& epi, int vt) {
;     ...
;     for (int kt = 0; kt < NK; ++kt) {
;       constexpr int dummy = 0; (void)dummy;
;       const int u = kt & 1;
;       const u16* as = As + u * 256 * 72 + (128 * wm + r) * 72 + 8 * h;
;       const u16* bs = Bs + u * BN * 72 + (32 * TJ * wn + r) * 72 + 8 * h;
;       if (kt == 0) {
; #pragma unroll
;         for (int i = 0; i < 4; ++i) af[0][i] = *(const bf16x8*)(as + (32 * i) * 72);
; #pragma unroll
;         for (int j = 0; j < TJ; ++j) bfr[0][j] = *(const bf16x8*)(bs + (32 * j) * 72);
;       }
; #pragma unroll
;       for (int ks = 0; ks < 4; ++ks) {
;         if (ks < 3) {
; #pragma unroll
;           for (int i = 0; i < 4; ++i) af[(ks + 1) & 1][i] = *(const bf16x8*)(as + (32 * i) * 72 + 16 * (ks + 1));
; #pragma unroll
;           for (int j = 0; j < TJ; ++j) bfr[(ks + 1) & 1][j] = *(const bf16x8*)(bs + (32 * j) * 72 + 16 * (ks + 1));
;         } else if (kt + 1 < NK) {
;           const u16* asn = As + (u ^ 1) * 256 * 72 + (128 * wm + r) * 72 + 8 * h;
;           const u16* bsn = Bs + (u ^ 1) * BN * 72 + (32 * TJ * wn + r) * 72 + 8 * h;
; #pragma unroll
;           for (int i = 0; i < 4; ++i) af[0][i] = *(const bf16x8*)(asn + (32 * i) * 72);
; #pragma unroll
;           for (int j = 0; j < TJ; ++j) bfr[0][j] = *(const bf16x8*)(bsn + (32 * j) * 72);
;         }
;         __builtin_amdgcn_sched_barrier(0);
; #pragma unroll
;         for (int i = 0; i < 4; ++i)
; #pragma unroll
;           for (int j = 0; j < TJ; ++j)
;             acc[i][j] = SWAP ? MFMA32(bfr[ks & 1][j], af[ks & 1][i], acc[i][j]) : MFMA32(af[ks & 1][i], bfr[ks & 1][j], acc[i][j]);
;         if (ks == 0 && kt + 2 < NK) {
;           const u16* ag = Ag + (kt + 2) * 64;
; #pragma unroll
;           for (int i = 0; i < 8; ++i) ra[u][i] = *(const u32x4*)(ag + aoff[i]);
; #pragma unroll
;           for (int i = 0; i < 8; ++i) { __builtin_amdgcn_sched_group_barrier(0x008, 1, 0); __builtin_amdgcn_sched_group_barrier(0x020, 1, 0); }
;         }
;         if (ks == 2 && kt + 2 < NK) {
;           const u16* bg = Bg + (kt + 2) * 64;
; #pragma unroll
	ds_read_b128 v[48:51], v70
	ds_read_b128 v[56:59], v70 offset:4608
	ds_read_b128 v[126:129], v70 offset:9216
	ds_read_b128 v[130:133], v70 offset:13824
	ds_read_b128 v[134:137], v71
	ds_read_b128 v[138:141], v71 offset:4608
	v_mfma_f32_32x32x16_bf16 a[112:127], v[32:35], v[0:3], a[112:127]
	v_mfma_f32_32x32x16_bf16 a[96:111], v[40:43], v[0:3], a[96:111]
	v_mfma_f32_32x32x16_bf16 a[80:95], v[32:35], v[8:11], a[80:95]
	v_mfma_f32_32x32x16_bf16 a[64:79], v[40:43], v[8:11], a[64:79]
	v_mfma_f32_32x32x16_bf16 a[48:63], v[32:35], v[16:19], a[48:63]
	v_mfma_f32_32x32x16_bf16 a[32:47], v[40:43], v[16:19], a[32:47]
	v_mfma_f32_32x32x16_bf16 a[16:31], v[32:35], v[24:27], a[16:31]
	v_mfma_f32_32x32x16_bf16 a[0:15], v[40:43], v[24:27], a[0:15]
	ds_read_b128 v[142:145], v70 offset:32
	ds_read_b128 v[146:149], v70 offset:4640
	ds_read_b128 v[150:153], v70 offset:9248
	ds_read_b128 v[154:157], v70 offset:13856
	ds_read_b128 v[158:161], v71 offset:32
	ds_read_b128 v[162:165], v71 offset:4640
	s_waitcnt lgkmcnt(7)
	v_mfma_f32_32x32x16_bf16 a[112:127], v[134:137], v[48:51], a[112:127]
	global_load_dwordx4 v[0:3], v[102:103], off offset:512
	s_waitcnt lgkmcnt(6)
	v_mfma_f32_32x32x16_bf16 a[96:111], v[138:141], v[48:51], a[96:111]
	global_load_dwordx4 v[8:11], v[100:101], off offset:512
	v_mfma_f32_32x32x16_bf16 a[80:95], v[134:137], v[56:59], a[80:95]
	global_load_dwordx4 v[16:19], v[98:99], off offset:512
	v_mfma_f32_32x32x16_bf16 a[64:79], v[138:141], v[56:59], a[64:79]
	global_load_dwordx4 v[24:27], v[96:97], off offset:512
	v_mfma_f32_32x32x16_bf16 a[48:63], v[134:137], v[126:129], a[48:63]
	global_load_dwordx4 v[32:35], v[94:95], off offset:512
	v_mfma_f32_32x32x16_bf16 a[32:47], v[138:141], v[126:129], a[32:47]
	global_load_dwordx4 v[40:43], v[92:93], off offset:512
	v_mfma_f32_32x32x16_bf16 a[16:31], v[134:137], v[130:133], a[16:31]
	global_load_dwordx4 v[48:51], v[90:91], off offset:512
	v_mfma_f32_32x32x16_bf16 a[0:15], v[138:141], v[130:133], a[0:15]
	global_load_dwordx4 v[56:59], v[88:89], off offset:512
	ds_read_b128 v[126:129], v70 offset:64
	ds_read_b128 v[130:133], v70 offset:4672
	ds_read_b128 v[134:137], v70 offset:9280
	ds_read_b128 v[138:141], v70 offset:13888
	ds_read_b128 v[166:169], v71 offset:64
	ds_read_b128 v[170:173], v71 offset:4672
	s_waitcnt lgkmcnt(7)
	v_mfma_f32_32x32x16_bf16 a[112:127], v[158:161], v[142:145], a[112:127]
	s_waitcnt vmcnt(19)
	ds_write_b128 v104, v[4:7] offset:36864
	s_waitcnt vmcnt(18)
	ds_write_b128 v104, v[12:15] offset:41472
	s_waitcnt lgkmcnt(8)
	v_mfma_f32_32x32x16_bf16 a[96:111], v[162:165], v[142:145], a[96:111]
	s_waitcnt vmcnt(17)
	ds_write_b128 v104, v[20:23] offset:46080
	s_waitcnt vmcnt(16)
	ds_write_b128 v104, v[28:31] offset:50688
	v_mfma_f32_32x32x16_bf16 a[80:95], v[158:161], v[146:149], a[80:95]
	s_waitcnt vmcnt(15)
	ds_write_b128 v104, v[36:39] offset:55296
	s_waitcnt vmcnt(14)
	ds_write_b128 v104, v[44:47] offset:59904
	v_mfma_f32_32x32x16_bf16 a[64:79], v[162:165], v[146:149], a[64:79]
	s_waitcnt vmcnt(13)
	ds_write_b128 v104, v[52:55] offset:64512
	s_waitcnt vmcnt(12)
	ds_write_b128 v108, v[60:63]
	v_mfma_f32_32x32x16_bf16 a[48:63], v[158:161], v[150:153], a[48:63]
	s_waitcnt vmcnt(11)
	ds_write_b128 v105, v[110:113] offset:18432
	s_waitcnt vmcnt(10)
	ds_write_b128 v105, v[114:117] offset:23040
	v_mfma_f32_32x32x16_bf16 a[32:47], v[162:165], v[150:153], a[32:47]
	s_waitcnt vmcnt(9)
	ds_write_b128 v105, v[118:121] offset:27648
	s_waitcnt vmcnt(8)
	ds_write_b128 v105, v[122:125] offset:32256
	v_mfma_f32_32x32x16_bf16 a[16:31], v[158:161], v[154:157], a[16:31]
	v_mfma_f32_32x32x16_bf16 a[0:15], v[162:165], v[154:157], a[0:15]
	ds_read_b128 v[4:7], v70 offset:96
	ds_read_b128 v[12:15], v70 offset:4704
	ds_read_b128 v[20:23], v70 offset:9312
	ds_read_b128 v[28:31], v70 offset:13920
	ds_read_b128 v[36:39], v71 offset:96
	ds_read_b128 v[44:47], v71 offset:4704
	s_waitcnt lgkmcnt(14)
	v_mfma_f32_32x32x16_bf16 a[112:127], v[166:169], v[126:129], a[112:127]
	global_load_dwordx4 v[110:113], v[86:87], off offset:512
	v_mfma_f32_32x32x16_bf16 a[96:111], v[170:173], v[126:129], a[96:111]
	global_load_dwordx4 v[114:117], v[84:85], off offset:512
	v_mfma_f32_32x32x16_bf16 a[80:95], v[166:169], v[130:133], a[80:95]
	global_load_dwordx4 v[118:121], v[82:83], off offset:512
	v_mfma_f32_32x32x16_bf16 a[64:79], v[170:173], v[130:133], a[64:79]
	global_load_dwordx4 v[122:125], v[80:81], off offset:512
	v_mfma_f32_32x32x16_bf16 a[48:63], v[166:169], v[134:137], a[48:63]
	v_mfma_f32_32x32x16_bf16 a[32:47], v[170:173], v[134:137], a[32:47]
	v_mfma_f32_32x32x16_bf16 a[16:31], v[166:169], v[138:141], a[16:31]
	v_mfma_f32_32x32x16_bf16 a[0:15], v[170:173], v[138:141], a[0:15]
	s_waitcnt lgkmcnt(0)
	s_barrier
; template <int TJ, bool SWAP, int NK, class Epi>
; DI void gemm_phase(const u16* __restrict__ A, size_t strideAz, int lda, const u16* __restrict__ Bt, size_t strideBz, int ldb,
;                    int Z, int Mt, int Nt, int GM, int K, char* smem, const Epi& epi, int vt) {
;     ...
;     for (int kt = 0; kt < NK; ++kt) {
;       constexpr int dummy = 0; (void)dummy;
;       const int u = kt & 1;
;       const u16* as = As + u * 256 * 72 + (128 * wm + r) * 72 + 8 * h;
;       const u16* bs = Bs + u * BN * 72 + (32 * TJ * wn + r) * 72 + 8 * h;
;       if (kt == 0) {
; #pragma unroll
;         for (int i = 0; i < 4; ++i) af[0][i] = *(const bf16x8*)(as + (32 * i) * 72);
; #pragma unroll
;         for (int j = 0; j < TJ; ++j) bfr[0][j] = *(const bf16x8*)(bs + (32 * j) * 72);
;       }
; #pragma unroll
;       for (int ks = 0; ks < 4; ++ks) {
;         if (ks < 3) {
; #pragma unroll
;           for (int i = 0; i < 4; ++i) af[(ks + 1) & 1][i] = *(const bf16x8*)(as + (32 * i) * 72 + 16 * (ks + 1));
; #pragma unroll
;           for (int j = 0; j < TJ; ++j) bfr[(ks + 1) & 1][j] = *(const bf16x8*)(bs + (32 * j) * 72 + 16 * (ks + 1));
;         } else if (kt + 1 < NK) {
;           const u16* asn = As + (u ^ 1) * 256 * 72 + (128 * wm + r) * 72 + 8 * h;
;           const u16* bsn = Bs + (u ^ 1) * BN * 72 + (32 * TJ * wn + r) * 72 + 8 * h;
; #pragma unroll
;           for (int i = 0; i < 4; ++i) af[0][i] = *(const bf16x8*)(asn + (32 * i) * 72);
; #pragma unroll
;           for (int j = 0; j < TJ; ++j) bfr[0][j] = *(const bf16x8*)(bsn + (32 * j) * 72);
;         }
;         __builtin_amdgcn_sched_barrier(0);
; #pragma unroll
;         for (int i = 0; i < 4; ++i)
; #pragma unroll
;           for (int j = 0; j < TJ; ++j)
;             acc[i][j] = SWAP ? MFMA32(bfr[ks & 1][j], af[ks & 1][i], acc[i][j]) : MFMA32(af[ks & 1][i], bfr[ks & 1][j], acc[i][j]);
;         if (ks == 0 && kt + 2 < NK) {
;           const u16* ag = Ag + (kt + 2) * 64;
; #pragma unroll
;           for (int i = 0; i < 8; ++i) ra[u][i] = *(const u32x4*)(ag + aoff[i]);
; #pragma unroll
;           for (int i = 0; i < 8; ++i) { __builtin_amdgcn_sched_group_barrier(0x008, 1, 0); __builtin_amdgcn_sched_group_barrier(0x020, 1, 0); }
;         }
;         if (ks == 2 && kt + 2 < NK) {
;           const u16* bg = Bg + (kt + 2) * 64;
; #pragma unroll
	ds_read_b128 v[52:55], v70 offset:36864
	ds_read_b128 v[60:63], v70 offset:41472
	ds_read_b128 v[126:129], v70 offset:46080
	ds_read_b128 v[130:133], v70 offset:50688
	ds_read_b128 v[134:137], v71 offset:18432
	ds_read_b128 v[138:141], v71 offset:23040
	v_mfma_f32_32x32x16_bf16 a[112:127], v[36:39], v[4:7], a[112:127]
	v_mfma_f32_32x32x16_bf16 a[96:111], v[44:47], v[4:7], a[96:111]
	v_mfma_f32_32x32x16_bf16 a[80:95], v[36:39], v[12:15], a[80:95]
	v_mfma_f32_32x32x16_bf16 a[64:79], v[44:47], v[12:15], a[64:79]
	v_mfma_f32_32x32x16_bf16 a[48:63], v[36:39], v[20:23], a[48:63]
	v_mfma_f32_32x32x16_bf16 a[32:47], v[44:47], v[20:23], a[32:47]
	v_mfma_f32_32x32x16_bf16 a[16:31], v[36:39], v[28:31], a[16:31]
	v_mfma_f32_32x32x16_bf16 a[0:15], v[44:47], v[28:31], a[0:15]
	ds_read_b128 v[142:145], v70 offset:36896
	ds_read_b128 v[146:149], v70 offset:41504
	ds_read_b128 v[150:153], v70 offset:46112
	ds_read_b128 v[154:157], v70 offset:50720
	ds_read_b128 v[158:161], v71 offset:18464
	ds_read_b128 v[162:165], v71 offset:23072
	s_waitcnt lgkmcnt(7)
	v_mfma_f32_32x32x16_bf16 a[112:127], v[134:137], v[52:55], a[112:127]
	global_load_dwordx4 v[4:7], v[102:103], off offset:640
	s_waitcnt lgkmcnt(6)
	v_mfma_f32_32x32x16_bf16 a[96:111], v[138:141], v[52:55], a[96:111]
	global_load_dwordx4 v[12:15], v[100:101], off offset:640
	v_mfma_f32_32x32x16_bf16 a[80:95], v[134:137], v[60:63], a[80:95]
	global_load_dwordx4 v[20:23], v[98:99], off offset:640
	v_mfma_f32_32x32x16_bf16 a[64:79], v[138:141], v[60:63], a[64:79]
	global_load_dwordx4 v[28:31], v[96:97], off offset:640
	v_mfma_f32_32x32x16_bf16 a[48:63], v[134:137], v[126:129], a[48:63]
	global_load_dwordx4 v[36:39], v[94:95], off offset:640
	v_mfma_f32_32x32x16_bf16 a[32:47], v[138:141], v[126:129], a[32:47]
	global_load_dwordx4 v[44:47], v[92:93], off offset:640
	v_mfma_f32_32x32x16_bf16 a[16:31], v[134:137], v[130:133], a[16:31]
	global_load_dwordx4 v[52:55], v[90:91], off offset:640
	v_mfma_f32_32x32x16_bf16 a[0:15], v[138:141], v[130:133], a[0:15]
	global_load_dwordx4 v[60:63], v[88:89], off offset:640
	ds_read_b128 v[126:129], v70 offset:36928
	ds_read_b128 v[130:133], v70 offset:41536
	ds_read_b128 v[134:137], v70 offset:46144
	ds_read_b128 v[138:141], v70 offset:50752
	ds_read_b128 v[166:169], v71 offset:18496
	ds_read_b128 v[170:173], v71 offset:23104
	s_waitcnt lgkmcnt(7)
	v_mfma_f32_32x32x16_bf16 a[112:127], v[158:161], v[142:145], a[112:127]
	s_waitcnt vmcnt(19)
	ds_write_b128 v104, v[0:3]
	s_waitcnt vmcnt(18)
	ds_write_b128 v104, v[8:11] offset:4608
	s_waitcnt lgkmcnt(8)
	v_mfma_f32_32x32x16_bf16 a[96:111], v[162:165], v[142:145], a[96:111]
	s_waitcnt vmcnt(17)
	ds_write_b128 v104, v[16:19] offset:9216
	s_waitcnt vmcnt(16)
	ds_write_b128 v104, v[24:27] offset:13824
	v_mfma_f32_32x32x16_bf16 a[80:95], v[158:161], v[146:149], a[80:95]
	s_waitcnt vmcnt(15)
	ds_write_b128 v104, v[32:35] offset:18432
	s_waitcnt vmcnt(14)
	ds_write_b128 v104, v[40:43] offset:23040
	v_mfma_f32_32x32x16_bf16 a[64:79], v[162:165], v[146:149], a[64:79]
	s_waitcnt vmcnt(13)
	ds_write_b128 v104, v[48:51] offset:27648
	s_waitcnt vmcnt(12)
	ds_write_b128 v104, v[56:59] offset:32256
	v_mfma_f32_32x32x16_bf16 a[48:63], v[158:161], v[150:153], a[48:63]
	s_waitcnt vmcnt(11)
	ds_write_b128 v105, v[110:113]
	s_waitcnt vmcnt(10)
	ds_write_b128 v105, v[114:117] offset:4608
	v_mfma_f32_32x32x16_bf16 a[32:47], v[162:165], v[150:153], a[32:47]
	s_waitcnt vmcnt(9)
	ds_write_b128 v105, v[118:121] offset:9216
	s_waitcnt vmcnt(8)
	ds_write_b128 v105, v[122:125] offset:13824
	v_mfma_f32_32x32x16_bf16 a[16:31], v[158:161], v[154:157], a[16:31]
	v_mfma_f32_32x32x16_bf16 a[0:15], v[162:165], v[154:157], a[0:15]
	ds_read_b128 v[0:3], v70 offset:36960
	ds_read_b128 v[8:11], v70 offset:41568
	ds_read_b128 v[16:19], v70 offset:46176
	ds_read_b128 v[24:27], v70 offset:50784
	ds_read_b128 v[32:35], v71 offset:18528
	ds_read_b128 v[40:43], v71 offset:23136
	s_waitcnt lgkmcnt(14)
	v_mfma_f32_32x32x16_bf16 a[112:127], v[166:169], v[126:129], a[112:127]
	global_load_dwordx4 v[110:113], v[86:87], off offset:640
	v_mfma_f32_32x32x16_bf16 a[96:111], v[170:173], v[126:129], a[96:111]
	global_load_dwordx4 v[114:117], v[84:85], off offset:640
	v_mfma_f32_32x32x16_bf16 a[80:95], v[166:169], v[130:133], a[80:95]
	global_load_dwordx4 v[118:121], v[82:83], off offset:640
	v_mfma_f32_32x32x16_bf16 a[64:79], v[170:173], v[130:133], a[64:79]
	global_load_dwordx4 v[122:125], v[80:81], off offset:640
	v_mfma_f32_32x32x16_bf16 a[48:63], v[166:169], v[134:137], a[48:63]
	v_mfma_f32_32x32x16_bf16 a[32:47], v[170:173], v[134:137], a[32:47]
	v_mfma_f32_32x32x16_bf16 a[16:31], v[166:169], v[138:141], a[16:31]
	v_mfma_f32_32x32x16_bf16 a[0:15], v[170:173], v[138:141], a[0:15]
	s_waitcnt lgkmcnt(0)
	s_barrier
; template <int TJ, bool SWAP, int NK, class Epi>
; DI void gemm_phase(const u16* __restrict__ A, size_t strideAz, int lda, const u16* __restrict__ Bt, size_t strideBz, int ldb,
;                    int Z, int Mt, int Nt, int GM, int K, char* smem, const Epi& epi, int vt) {
;     ...
;     for (int kt = 0; kt < NK; ++kt) {
;       constexpr int dummy = 0; (void)dummy;
;       const int u = kt & 1;
;       const u16* as = As + u * 256 * 72 + (128 * wm + r) * 72 + 8 * h;
;       const u16* bs = Bs + u * BN * 72 + (32 * TJ * wn + r) * 72 + 8 * h;
;       if (kt == 0) {
; #pragma unroll
;         for (int i = 0; i < 4; ++i) af[0][i] = *(const bf16x8*)(as + (32 * i) * 72);
; #pragma unroll
;         for (int j = 0; j < TJ; ++j) bfr[0][j] = *(const bf16x8*)(bs + (32 * j) * 72);
;       }
; #pragma unroll
;       for (int ks = 0; ks < 4; ++ks) {
;         if (ks < 3) {
; #pragma unroll
;           for (int i = 0; i < 4; ++i) af[(ks + 1) & 1][i] = *(const bf16x8*)(as + (32 * i) * 72 + 16 * (ks + 1));
; #pragma unroll
;           for (int j = 0; j < TJ; ++j) bfr[(ks + 1) & 1][j] = *(const bf16x8*)(bs + (32 * j) * 72 + 16 * (ks + 1));
;         } else if (kt + 1 < NK) {
;           const u16* asn = As + (u ^ 1) * 256 * 72 + (128 * wm + r) * 72 + 8 * h;
;           const u16* bsn = Bs + (u ^ 1) * BN * 72 + (32 * TJ * wn + r) * 72 + 8 * h;
; #pragma unroll
;           for (int i = 0; i < 4; ++i) af[0][i] = *(const bf16x8*)(asn + (32 * i) * 72);
; #pragma unroll
;           for (int j = 0; j < TJ; ++j) bfr[0][j] = *(const bf16x8*)(bsn + (32 * j) * 72);
;         }
;         __builtin_amdgcn_sched_barrier(0);
; #pragma unroll
;         for (int i = 0; i < 4; ++i)
; #pragma unroll
;           for (int j = 0; j < TJ; ++j)
;             acc[i][j] = SWAP ? MFMA32(bfr[ks & 1][j], af[ks & 1][i], acc[i][j]) : MFMA32(af[ks & 1][i], bfr[ks & 1][j], acc[i][j]);
;         if (ks == 0 && kt + 2 < NK) {
;           const u16* ag = Ag + (kt + 2) * 64;
; #pragma unroll
;           for (int i = 0; i < 8; ++i) ra[u][i] = *(const u32x4*)(ag + aoff[i]);
; #pragma unroll
;           for (int i = 0; i < 8; ++i) { __builtin_amdgcn_sched_group_barrier(0x008, 1, 0); __builtin_amdgcn_sched_group_barrier(0x020, 1, 0); }
;         }
;         if (ks == 2 && kt + 2 < NK) {
;           const u16* bg = Bg + (kt + 2) * 64;
; #pragma unroll
	ds_read_b128 v[48:51], v70
	ds_read_b128 v[56:59], v70 offset:4608
	ds_read_b128 v[126:129], v70 offset:9216
	ds_read_b128 v[130:133], v70 offset:13824
	ds_read_b128 v[134:137], v71
	ds_read_b128 v[138:141], v71 offset:4608
	v_mfma_f32_32x32x16_bf16 a[112:127], v[32:35], v[0:3], a[112:127]
	v_mfma_f32_32x32x16_bf16 a[96:111], v[40:43], v[0:3], a[96:111]
	v_mfma_f32_32x32x16_bf16 a[80:95], v[32:35], v[8:11], a[80:95]
	v_mfma_f32_32x32x16_bf16 a[64:79], v[40:43], v[8:11], a[64:79]
	v_mfma_f32_32x32x16_bf16 a[48:63], v[32:35], v[16:19], a[48:63]
	v_mfma_f32_32x32x16_bf16 a[32:47], v[40:43], v[16:19], a[32:47]
	v_mfma_f32_32x32x16_bf16 a[16:31], v[32:35], v[24:27], a[16:31]
	v_mfma_f32_32x32x16_bf16 a[0:15], v[40:43], v[24:27], a[0:15]
	ds_read_b128 v[142:145], v70 offset:32
	ds_read_b128 v[146:149], v70 offset:4640
	ds_read_b128 v[150:153], v70 offset:9248
	ds_read_b128 v[154:157], v70 offset:13856
	ds_read_b128 v[158:161], v71 offset:32
	ds_read_b128 v[162:165], v71 offset:4640
	s_waitcnt lgkmcnt(7)
	v_mfma_f32_32x32x16_bf16 a[112:127], v[134:137], v[48:51], a[112:127]
	global_load_dwordx4 v[0:3], v[102:103], off offset:768
	s_waitcnt lgkmcnt(6)
	v_mfma_f32_32x32x16_bf16 a[96:111], v[138:141], v[48:51], a[96:111]
	global_load_dwordx4 v[8:11], v[100:101], off offset:768
	v_mfma_f32_32x32x16_bf16 a[80:95], v[134:137], v[56:59], a[80:95]
	global_load_dwordx4 v[16:19], v[98:99], off offset:768
	v_mfma_f32_32x32x16_bf16 a[64:79], v[138:141], v[56:59], a[64:79]
	global_load_dwordx4 v[24:27], v[96:97], off offset:768
	v_mfma_f32_32x32x16_bf16 a[48:63], v[134:137], v[126:129], a[48:63]
	global_load_dwordx4 v[32:35], v[94:95], off offset:768
	v_mfma_f32_32x32x16_bf16 a[32:47], v[138:141], v[126:129], a[32:47]
	global_load_dwordx4 v[40:43], v[92:93], off offset:768
	v_mfma_f32_32x32x16_bf16 a[16:31], v[134:137], v[130:133], a[16:31]
	global_load_dwordx4 v[48:51], v[90:91], off offset:768
	v_mfma_f32_32x32x16_bf16 a[0:15], v[138:141], v[130:133], a[0:15]
	global_load_dwordx4 v[56:59], v[88:89], off offset:768
	ds_read_b128 v[126:129], v70 offset:64
	ds_read_b128 v[130:133], v70 offset:4672
	ds_read_b128 v[134:137], v70 offset:9280
	ds_read_b128 v[138:141], v70 offset:13888
	ds_read_b128 v[166:169], v71 offset:64
	ds_read_b128 v[170:173], v71 offset:4672
	s_waitcnt lgkmcnt(7)
	v_mfma_f32_32x32x16_bf16 a[112:127], v[158:161], v[142:145], a[112:127]
	s_waitcnt vmcnt(19)
	ds_write_b128 v104, v[4:7] offset:36864
	s_waitcnt vmcnt(18)
	ds_write_b128 v104, v[12:15] offset:41472
	s_waitcnt lgkmcnt(8)
	v_mfma_f32_32x32x16_bf16 a[96:111], v[162:165], v[142:145], a[96:111]
	s_waitcnt vmcnt(17)
	ds_write_b128 v104, v[20:23] offset:46080
	s_waitcnt vmcnt(16)
	ds_write_b128 v104, v[28:31] offset:50688
	v_mfma_f32_32x32x16_bf16 a[80:95], v[158:161], v[146:149], a[80:95]
	s_waitcnt vmcnt(15)
	ds_write_b128 v104, v[36:39] offset:55296
	s_waitcnt vmcnt(14)
	ds_write_b128 v104, v[44:47] offset:59904
	v_mfma_f32_32x32x16_bf16 a[64:79], v[162:165], v[146:149], a[64:79]
	s_waitcnt vmcnt(13)
	ds_write_b128 v104, v[52:55] offset:64512
	s_waitcnt vmcnt(12)
	ds_write_b128 v108, v[60:63]
	v_mfma_f32_32x32x16_bf16 a[48:63], v[158:161], v[150:153], a[48:63]
	s_waitcnt vmcnt(11)
	ds_write_b128 v105, v[110:113] offset:18432
	s_waitcnt vmcnt(10)
	ds_write_b128 v105, v[114:117] offset:23040
	v_mfma_f32_32x32x16_bf16 a[32:47], v[162:165], v[150:153], a[32:47]
	s_waitcnt vmcnt(9)
	ds_write_b128 v105, v[118:121] offset:27648
	s_waitcnt vmcnt(8)
	ds_write_b128 v105, v[122:125] offset:32256
	v_mfma_f32_32x32x16_bf16 a[16:31], v[158:161], v[154:157], a[16:31]
	v_mfma_f32_32x32x16_bf16 a[0:15], v[162:165], v[154:157], a[0:15]
	ds_read_b128 v[4:7], v70 offset:96
	ds_read_b128 v[12:15], v70 offset:4704
	ds_read_b128 v[20:23], v70 offset:9312
	ds_read_b128 v[28:31], v70 offset:13920
	ds_read_b128 v[36:39], v71 offset:96
	ds_read_b128 v[44:47], v71 offset:4704
	s_waitcnt lgkmcnt(14)
	v_mfma_f32_32x32x16_bf16 a[112:127], v[166:169], v[126:129], a[112:127]
	global_load_dwordx4 v[110:113], v[86:87], off offset:768
	v_mfma_f32_32x32x16_bf16 a[96:111], v[170:173], v[126:129], a[96:111]
	global_load_dwordx4 v[114:117], v[84:85], off offset:768
	v_mfma_f32_32x32x16_bf16 a[80:95], v[166:169], v[130:133], a[80:95]
	global_load_dwordx4 v[118:121], v[82:83], off offset:768
	v_mfma_f32_32x32x16_bf16 a[64:79], v[170:173], v[130:133], a[64:79]
	global_load_dwordx4 v[122:125], v[80:81], off offset:768
	v_mfma_f32_32x32x16_bf16 a[48:63], v[166:169], v[134:137], a[48:63]
	v_mfma_f32_32x32x16_bf16 a[32:47], v[170:173], v[134:137], a[32:47]
	v_mfma_f32_32x32x16_bf16 a[16:31], v[166:169], v[138:141], a[16:31]
	v_mfma_f32_32x32x16_bf16 a[0:15], v[170:173], v[138:141], a[0:15]
	s_waitcnt lgkmcnt(0)
	s_barrier
; template <int TJ, bool SWAP, int NK, class Epi>
; DI void gemm_phase(const u16* __restrict__ A, size_t strideAz, int lda, const u16* __restrict__ Bt, size_t strideBz, int ldb,
;                    int Z, int Mt, int Nt, int GM, int K, char* smem, const Epi& epi, int vt) {
;     ...
;     for (int kt = 0; kt < NK; ++kt) {
;       constexpr int dummy = 0; (void)dummy;
;       const int u = kt & 1;
;       const u16* as = As + u * 256 * 72 + (128 * wm + r) * 72 + 8 * h;
;       const u16* bs = Bs + u * BN * 72 + (32 * TJ * wn + r) * 72 + 8 * h;
;       if (kt == 0) {
; #pragma unroll
;         for (int i = 0; i < 4; ++i) af[0][i] = *(const bf16x8*)(as + (32 * i) * 72);
; #pragma unroll
;         for (int j = 0; j < TJ; ++j) bfr[0][j] = *(const bf16x8*)(bs + (32 * j) * 72);
;       }
; #pragma unroll
;       for (int ks = 0; ks < 4; ++ks) {
;         if (ks < 3) {
; #pragma unroll
;           for (int i = 0; i < 4; ++i) af[(ks + 1) & 1][i] = *(const bf16x8*)(as + (32 * i) * 72 + 16 * (ks + 1));
; #pragma unroll
;           for (int j = 0; j < TJ; ++j) bfr[(ks + 1) & 1][j] = *(const bf16x8*)(bs + (32 * j) * 72 + 16 * (ks + 1));
;         } else if (kt + 1 < NK) {
;           const u16* asn = As + (u ^ 1) * 256 * 72 + (128 * wm + r) * 72 + 8 * h;
;           const u16* bsn = Bs + (u ^ 1) * BN * 72 + (32 * TJ * wn + r) * 72 + 8 * h;
; #pragma unroll
;           for (int i = 0; i < 4; ++i) af[0][i] = *(const bf16x8*)(asn + (32 * i) * 72);
; #pragma unroll
;           for (int j = 0; j < TJ; ++j) bfr[0][j] = *(const bf16x8*)(bsn + (32 * j) * 72);
;         }
;         __builtin_amdgcn_sched_barrier(0);
; #pragma unroll
;         for (int i = 0; i < 4; ++i)
; #pragma unroll
;           for (int j = 0; j < TJ; ++j)
;             acc[i][j] = SWAP ? MFMA32(bfr[ks & 1][j], af[ks & 1][i], acc[i][j]) : MFMA32(af[ks & 1][i], bfr[ks & 1][j], acc[i][j]);
;         if (ks == 0 && kt + 2 < NK) {
;           const u16* ag = Ag + (kt + 2) * 64;
; #pragma unroll
;           for (int i = 0; i < 8; ++i) ra[u][i] = *(const u32x4*)(ag + aoff[i]);
; #pragma unroll
;           for (int i = 0; i < 8; ++i) { __builtin_amdgcn_sched_group_barrier(0x008, 1, 0); __builtin_amdgcn_sched_group_barrier(0x020, 1, 0); }
;         }
;         if (ks == 2 && kt + 2 < NK) {
;           const u16* bg = Bg + (kt + 2) * 64;
; #pragma unroll
	ds_read_b128 v[52:55], v70 offset:36864
	ds_read_b128 v[60:63], v70 offset:41472
	ds_read_b128 v[126:129], v70 offset:46080
	ds_read_b128 v[130:133], v70 offset:50688
	ds_read_b128 v[134:137], v71 offset:18432
	ds_read_b128 v[138:141], v71 offset:23040
	v_mfma_f32_32x32x16_bf16 a[112:127], v[36:39], v[4:7], a[112:127]
	v_mfma_f32_32x32x16_bf16 a[96:111], v[44:47], v[4:7], a[96:111]
	v_mfma_f32_32x32x16_bf16 a[80:95], v[36:39], v[12:15], a[80:95]
	v_mfma_f32_32x32x16_bf16 a[64:79], v[44:47], v[12:15], a[64:79]
	v_mfma_f32_32x32x16_bf16 a[48:63], v[36:39], v[20:23], a[48:63]
	v_mfma_f32_32x32x16_bf16 a[32:47], v[44:47], v[20:23], a[32:47]
	v_mfma_f32_32x32x16_bf16 a[16:31], v[36:39], v[28:31], a[16:31]
	v_mfma_f32_32x32x16_bf16 a[0:15], v[44:47], v[28:31], a[0:15]
	ds_read_b128 v[142:145], v70 offset:36896
	ds_read_b128 v[146:149], v70 offset:41504
	ds_read_b128 v[150:153], v70 offset:46112
	ds_read_b128 v[154:157], v70 offset:50720
	ds_read_b128 v[158:161], v71 offset:18464
	ds_read_b128 v[162:165], v71 offset:23072
	s_waitcnt lgkmcnt(7)
	v_mfma_f32_32x32x16_bf16 a[112:127], v[134:137], v[52:55], a[112:127]
	global_load_dwordx4 v[4:7], v[102:103], off offset:896
	s_waitcnt lgkmcnt(6)
	v_mfma_f32_32x32x16_bf16 a[96:111], v[138:141], v[52:55], a[96:111]
	global_load_dwordx4 v[12:15], v[100:101], off offset:896
	v_mfma_f32_32x32x16_bf16 a[80:95], v[134:137], v[60:63], a[80:95]
	global_load_dwordx4 v[20:23], v[98:99], off offset:896
	v_mfma_f32_32x32x16_bf16 a[64:79], v[138:141], v[60:63], a[64:79]
	global_load_dwordx4 v[28:31], v[96:97], off offset:896
	v_mfma_f32_32x32x16_bf16 a[48:63], v[134:137], v[126:129], a[48:63]
	global_load_dwordx4 v[36:39], v[94:95], off offset:896
	v_mfma_f32_32x32x16_bf16 a[32:47], v[138:141], v[126:129], a[32:47]
	global_load_dwordx4 v[44:47], v[92:93], off offset:896
	v_mfma_f32_32x32x16_bf16 a[16:31], v[134:137], v[130:133], a[16:31]
	global_load_dwordx4 v[52:55], v[90:91], off offset:896
	v_mfma_f32_32x32x16_bf16 a[0:15], v[138:141], v[130:133], a[0:15]
	global_load_dwordx4 v[60:63], v[88:89], off offset:896
	ds_read_b128 v[126:129], v70 offset:36928
	ds_read_b128 v[130:133], v70 offset:41536
	ds_read_b128 v[134:137], v70 offset:46144
	ds_read_b128 v[138:141], v70 offset:50752
	ds_read_b128 v[166:169], v71 offset:18496
	ds_read_b128 v[170:173], v71 offset:23104
	s_waitcnt lgkmcnt(7)
	v_mfma_f32_32x32x16_bf16 a[112:127], v[158:161], v[142:145], a[112:127]
	s_waitcnt vmcnt(19)
	ds_write_b128 v104, v[0:3]
	s_waitcnt vmcnt(18)
	ds_write_b128 v104, v[8:11] offset:4608
	s_waitcnt lgkmcnt(8)
	v_mfma_f32_32x32x16_bf16 a[96:111], v[162:165], v[142:145], a[96:111]
	s_waitcnt vmcnt(17)
	ds_write_b128 v104, v[16:19] offset:9216
	s_waitcnt vmcnt(16)
	ds_write_b128 v104, v[24:27] offset:13824
	v_mfma_f32_32x32x16_bf16 a[80:95], v[158:161], v[146:149], a[80:95]
	s_waitcnt vmcnt(15)
	ds_write_b128 v104, v[32:35] offset:18432
	s_waitcnt vmcnt(14)
	ds_write_b128 v104, v[40:43] offset:23040
	v_mfma_f32_32x32x16_bf16 a[64:79], v[162:165], v[146:149], a[64:79]
	s_waitcnt vmcnt(13)
	ds_write_b128 v104, v[48:51] offset:27648
	s_waitcnt vmcnt(12)
	ds_write_b128 v104, v[56:59] offset:32256
	v_mfma_f32_32x32x16_bf16 a[48:63], v[158:161], v[150:153], a[48:63]
	s_waitcnt vmcnt(11)
	ds_write_b128 v105, v[110:113]
	s_waitcnt vmcnt(10)
	ds_write_b128 v105, v[114:117] offset:4608
	v_mfma_f32_32x32x16_bf16 a[32:47], v[162:165], v[150:153], a[32:47]
	s_waitcnt vmcnt(9)
	ds_write_b128 v105, v[118:121] offset:9216
	s_waitcnt vmcnt(8)
	ds_write_b128 v105, v[122:125] offset:13824
	v_mfma_f32_32x32x16_bf16 a[16:31], v[158:161], v[154:157], a[16:31]
	v_mfma_f32_32x32x16_bf16 a[0:15], v[162:165], v[154:157], a[0:15]
	ds_read_b128 v[0:3], v70 offset:36960
	ds_read_b128 v[8:11], v70 offset:41568
	ds_read_b128 v[16:19], v70 offset:46176
	ds_read_b128 v[24:27], v70 offset:50784
	ds_read_b128 v[32:35], v71 offset:18528
	ds_read_b128 v[40:43], v71 offset:23136
	s_waitcnt lgkmcnt(14)
	v_mfma_f32_32x32x16_bf16 a[112:127], v[166:169], v[126:129], a[112:127]
	global_load_dwordx4 v[110:113], v[86:87], off offset:896
	v_mfma_f32_32x32x16_bf16 a[96:111], v[170:173], v[126:129], a[96:111]
	global_load_dwordx4 v[114:117], v[84:85], off offset:896
	v_mfma_f32_32x32x16_bf16 a[80:95], v[166:169], v[130:133], a[80:95]
	global_load_dwordx4 v[118:121], v[82:83], off offset:896
	v_mfma_f32_32x32x16_bf16 a[64:79], v[170:173], v[130:133], a[64:79]
	global_load_dwordx4 v[122:125], v[80:81], off offset:896
	v_mfma_f32_32x32x16_bf16 a[48:63], v[166:169], v[134:137], a[48:63]
	v_mfma_f32_32x32x16_bf16 a[32:47], v[170:173], v[134:137], a[32:47]
	v_mfma_f32_32x32x16_bf16 a[16:31], v[166:169], v[138:141], a[16:31]
	v_mfma_f32_32x32x16_bf16 a[0:15], v[170:173], v[138:141], a[0:15]
	s_waitcnt lgkmcnt(0)
	s_barrier
; template <int TJ, bool SWAP, int NK, class Epi>
; DI void gemm_phase(const u16* __restrict__ A, size_t strideAz, int lda, const u16* __restrict__ Bt, size_t strideBz, int ldb,
;                    int Z, int Mt, int Nt, int GM, int K, char* smem, const Epi& epi, int vt) {
;     ...
;     for (int kt = 0; kt < NK; ++kt) {
;       constexpr int dummy = 0; (void)dummy;
;       const int u = kt & 1;
;       const u16* as = As + u * 256 * 72 + (128 * wm + r) * 72 + 8 * h;
;       const u16* bs = Bs + u * BN * 72 + (32 * TJ * wn + r) * 72 + 8 * h;
;       if (kt == 0) {
; #pragma unroll
;         for (int i = 0; i < 4; ++i) af[0][i] = *(const bf16x8*)(as + (32 * i) * 72);
; #pragma unroll
;         for (int j = 0; j < TJ; ++j) bfr[0][j] = *(const bf16x8*)(bs + (32 * j) * 72);
;       }
; #pragma unroll
;       for (int ks = 0; ks < 4; ++ks) {
;         if (ks < 3) {
; #pragma unroll
;           for (int i = 0; i < 4; ++i) af[(ks + 1) & 1][i] = *(const bf16x8*)(as + (32 * i) * 72 + 16 * (ks + 1));
; #pragma unroll
;           for (int j = 0; j < TJ; ++j) bfr[(ks + 1) & 1][j] = *(const bf16x8*)(bs + (32 * j) * 72 + 16 * (ks + 1));
;         } else if (kt + 1 < NK) {
;           const u16* asn = As + (u ^ 1) * 256 * 72 + (128 * wm + r) * 72 + 8 * h;
;           const u16* bsn = Bs + (u ^ 1) * BN * 72 + (32 * TJ * wn + r) * 72 + 8 * h;
; #pragma unroll
;           for (int i = 0; i < 4; ++i) af[0][i] = *(const bf16x8*)(asn + (32 * i) * 72);
; #pragma unroll
;           for (int j = 0; j < TJ; ++j) bfr[0][j] = *(const bf16x8*)(bsn + (32 * j) * 72);
;         }
;         __builtin_amdgcn_sched_barrier(0);
; #pragma unroll
;         for (int i = 0; i < 4; ++i)
; #pragma unroll
;           for (int j = 0; j < TJ; ++j)
;             acc[i][j] = SWAP ? MFMA32(bfr[ks & 1][j], af[ks & 1][i], acc[i][j]) : MFMA32(af[ks & 1][i], bfr[ks & 1][j], acc[i][j]);
;         if (ks == 0 && kt + 2 < NK) {
;           const u16* ag = Ag + (kt + 2) * 64;
; #pragma unroll
;           for (int i = 0; i < 8; ++i) ra[u][i] = *(const u32x4*)(ag + aoff[i]);
; #pragma unroll
;           for (int i = 0; i < 8; ++i) { __builtin_amdgcn_sched_group_barrier(0x008, 1, 0); __builtin_amdgcn_sched_group_barrier(0x020, 1, 0); }
;         }
;         if (ks == 2 && kt + 2 < NK) {
;           const u16* bg = Bg + (kt + 2) * 64;
; #pragma unroll
	ds_read_b128 v[48:51], v70
	ds_read_b128 v[56:59], v70 offset:4608
	ds_read_b128 v[126:129], v70 offset:9216
	ds_read_b128 v[130:133], v70 offset:13824
	ds_read_b128 v[134:137], v71
	ds_read_b128 v[138:141], v71 offset:4608
	v_mfma_f32_32x32x16_bf16 a[112:127], v[32:35], v[0:3], a[112:127]
	v_mfma_f32_32x32x16_bf16 a[96:111], v[40:43], v[0:3], a[96:111]
	v_mfma_f32_32x32x16_bf16 a[80:95], v[32:35], v[8:11], a[80:95]
	v_mfma_f32_32x32x16_bf16 a[64:79], v[40:43], v[8:11], a[64:79]
	v_mfma_f32_32x32x16_bf16 a[48:63], v[32:35], v[16:19], a[48:63]
	v_mfma_f32_32x32x16_bf16 a[32:47], v[40:43], v[16:19], a[32:47]
	v_mfma_f32_32x32x16_bf16 a[16:31], v[32:35], v[24:27], a[16:31]
	v_mfma_f32_32x32x16_bf16 a[0:15], v[40:43], v[24:27], a[0:15]
	ds_read_b128 v[142:145], v70 offset:32
	ds_read_b128 v[146:149], v70 offset:4640
	ds_read_b128 v[150:153], v70 offset:9248
	ds_read_b128 v[154:157], v70 offset:13856
	ds_read_b128 v[158:161], v71 offset:32
	ds_read_b128 v[162:165], v71 offset:4640
	s_waitcnt lgkmcnt(7)
	v_mfma_f32_32x32x16_bf16 a[112:127], v[134:137], v[48:51], a[112:127]
	global_load_dwordx4 v[0:3], v[102:103], off offset:1024
	s_waitcnt lgkmcnt(6)
	v_mfma_f32_32x32x16_bf16 a[96:111], v[138:141], v[48:51], a[96:111]
	global_load_dwordx4 v[8:11], v[100:101], off offset:1024
	v_mfma_f32_32x32x16_bf16 a[80:95], v[134:137], v[56:59], a[80:95]
	global_load_dwordx4 v[16:19], v[98:99], off offset:1024
	v_mfma_f32_32x32x16_bf16 a[64:79], v[138:141], v[56:59], a[64:79]
	global_load_dwordx4 v[24:27], v[96:97], off offset:1024
	v_mfma_f32_32x32x16_bf16 a[48:63], v[134:137], v[126:129], a[48:63]
	global_load_dwordx4 v[32:35], v[94:95], off offset:1024
	v_mfma_f32_32x32x16_bf16 a[32:47], v[138:141], v[126:129], a[32:47]
	global_load_dwordx4 v[40:43], v[92:93], off offset:1024
	v_mfma_f32_32x32x16_bf16 a[16:31], v[134:137], v[130:133], a[16:31]
	global_load_dwordx4 v[48:51], v[90:91], off offset:1024
	v_mfma_f32_32x32x16_bf16 a[0:15], v[138:141], v[130:133], a[0:15]
	global_load_dwordx4 v[56:59], v[88:89], off offset:1024
	ds_read_b128 v[126:129], v70 offset:64
	ds_read_b128 v[130:133], v70 offset:4672
	ds_read_b128 v[134:137], v70 offset:9280
	ds_read_b128 v[138:141], v70 offset:13888
	ds_read_b128 v[166:169], v71 offset:64
	ds_read_b128 v[170:173], v71 offset:4672
	s_waitcnt lgkmcnt(7)
	v_mfma_f32_32x32x16_bf16 a[112:127], v[158:161], v[142:145], a[112:127]
	s_waitcnt vmcnt(19)
	ds_write_b128 v104, v[4:7] offset:36864
	s_waitcnt vmcnt(18)
	ds_write_b128 v104, v[12:15] offset:41472
	s_waitcnt lgkmcnt(8)
	v_mfma_f32_32x32x16_bf16 a[96:111], v[162:165], v[142:145], a[96:111]
	s_waitcnt vmcnt(17)
	ds_write_b128 v104, v[20:23] offset:46080
	s_waitcnt vmcnt(16)
	ds_write_b128 v104, v[28:31] offset:50688
	v_mfma_f32_32x32x16_bf16 a[80:95], v[158:161], v[146:149], a[80:95]
	s_waitcnt vmcnt(15)
	ds_write_b128 v104, v[36:39] offset:55296
	s_waitcnt vmcnt(14)
	ds_write_b128 v104, v[44:47] offset:59904
	v_mfma_f32_32x32x16_bf16 a[64:79], v[162:165], v[146:149], a[64:79]
	s_waitcnt vmcnt(13)
	ds_write_b128 v104, v[52:55] offset:64512
	s_waitcnt vmcnt(12)
	ds_write_b128 v108, v[60:63]
	v_mfma_f32_32x32x16_bf16 a[48:63], v[158:161], v[150:153], a[48:63]
	s_waitcnt vmcnt(11)
	ds_write_b128 v105, v[110:113] offset:18432
	s_waitcnt vmcnt(10)
	ds_write_b128 v105, v[114:117] offset:23040
	v_mfma_f32_32x32x16_bf16 a[32:47], v[162:165], v[150:153], a[32:47]
	s_waitcnt vmcnt(9)
	ds_write_b128 v105, v[118:121] offset:27648
	s_waitcnt vmcnt(8)
	ds_write_b128 v105, v[122:125] offset:32256
	v_mfma_f32_32x32x16_bf16 a[16:31], v[158:161], v[154:157], a[16:31]
	v_mfma_f32_32x32x16_bf16 a[0:15], v[162:165], v[154:157], a[0:15]
	ds_read_b128 v[4:7], v70 offset:96
	ds_read_b128 v[12:15], v70 offset:4704
	ds_read_b128 v[20:23], v70 offset:9312
	ds_read_b128 v[28:31], v70 offset:13920
	ds_read_b128 v[36:39], v71 offset:96
	ds_read_b128 v[44:47], v71 offset:4704
	s_waitcnt lgkmcnt(14)
	v_mfma_f32_32x32x16_bf16 a[112:127], v[166:169], v[126:129], a[112:127]
	global_load_dwordx4 v[110:113], v[86:87], off offset:1024
	v_mfma_f32_32x32x16_bf16 a[96:111], v[170:173], v[126:129], a[96:111]
	global_load_dwordx4 v[114:117], v[84:85], off offset:1024
	v_mfma_f32_32x32x16_bf16 a[80:95], v[166:169], v[130:133], a[80:95]
	global_load_dwordx4 v[118:121], v[82:83], off offset:1024
	v_mfma_f32_32x32x16_bf16 a[64:79], v[170:173], v[130:133], a[64:79]
	global_load_dwordx4 v[122:125], v[80:81], off offset:1024
	v_mfma_f32_32x32x16_bf16 a[48:63], v[166:169], v[134:137], a[48:63]
	v_mfma_f32_32x32x16_bf16 a[32:47], v[170:173], v[134:137], a[32:47]
	v_mfma_f32_32x32x16_bf16 a[16:31], v[166:169], v[138:141], a[16:31]
	v_mfma_f32_32x32x16_bf16 a[0:15], v[170:173], v[138:141], a[0:15]
	s_waitcnt lgkmcnt(0)
	s_barrier
; template <int TJ, bool SWAP, int NK, class Epi>
; DI void gemm_phase(const u16* __restrict__ A, size_t strideAz, int lda, const u16* __restrict__ Bt, size_t strideBz, int ldb,
;                    int Z, int Mt, int Nt, int GM, int K, char* smem, const Epi& epi, int vt) {
;     ...
;     for (int kt = 0; kt < NK; ++kt) {
;       constexpr int dummy = 0; (void)dummy;
;       const int u = kt & 1;
;       const u16* as = As + u * 256 * 72 + (128 * wm + r) * 72 + 8 * h;
;       const u16* bs = Bs + u * BN * 72 + (32 * TJ * wn + r) * 72 + 8 * h;
;       if (kt == 0) {
; #pragma unroll
;         for (int i = 0; i < 4; ++i) af[0][i] = *(const bf16x8*)(as + (32 * i) * 72);
; #pragma unroll
;         for (int j = 0; j < TJ; ++j) bfr[0][j] = *(const bf16x8*)(bs + (32 * j) * 72);
;       }
; #pragma unroll
;       for (int ks = 0; ks < 4; ++ks) {
;         if (ks < 3) {
; #pragma unroll
;           for (int i = 0; i < 4; ++i) af[(ks + 1) & 1][i] = *(const bf16x8*)(as + (32 * i) * 72 + 16 * (ks + 1));
; #pragma unroll
;           for (int j = 0; j < TJ; ++j) bfr[(ks + 1) & 1][j] = *(const bf16x8*)(bs + (32 * j) * 72 + 16 * (ks + 1));
;         } else if (kt + 1 < NK) {
;           const u16* asn = As + (u ^ 1) * 256 * 72 + (128 * wm + r) * 72 + 8 * h;
;           const u16* bsn = Bs + (u ^ 1) * BN * 72 + (32 * TJ * wn + r) * 72 + 8 * h;
; #pragma unroll
;           for (int i = 0; i < 4; ++i) af[0][i] = *(const bf16x8*)(asn + (32 * i) * 72);
; #pragma unroll
;           for (int j = 0; j < TJ; ++j) bfr[0][j] = *(const bf16x8*)(bsn + (32 * j) * 72);
;         }
;         __builtin_amdgcn_sched_barrier(0);
; #pragma unroll
;         for (int i = 0; i < 4; ++i)
; #pragma unroll
;           for (int j = 0; j < TJ; ++j)
;             acc[i][j] = SWAP ? MFMA32(bfr[ks & 1][j], af[ks & 1][i], acc[i][j]) : MFMA32(af[ks & 1][i], bfr[ks & 1][j], acc[i][j]);
;         if (ks == 0 && kt + 2 < NK) {
;           const u16* ag = Ag + (kt + 2) * 64;
; #pragma unroll
;           for (int i = 0; i < 8; ++i) ra[u][i] = *(const u32x4*)(ag + aoff[i]);
; #pragma unroll
;           for (int i = 0; i < 8; ++i) { __builtin_amdgcn_sched_group_barrier(0x008, 1, 0); __builtin_amdgcn_sched_group_barrier(0x020, 1, 0); }
;         }
;         if (ks == 2 && kt + 2 < NK) {
;           const u16* bg = Bg + (kt + 2) * 64;
; #pragma unroll
	ds_read_b128 v[52:55], v70 offset:36864
	ds_read_b128 v[60:63], v70 offset:41472
	ds_read_b128 v[126:129], v70 offset:46080
	ds_read_b128 v[130:133], v70 offset:50688
	ds_read_b128 v[134:137], v71 offset:18432
	ds_read_b128 v[138:141], v71 offset:23040
	v_mfma_f32_32x32x16_bf16 a[112:127], v[36:39], v[4:7], a[112:127]
	v_mfma_f32_32x32x16_bf16 a[96:111], v[44:47], v[4:7], a[96:111]
	v_mfma_f32_32x32x16_bf16 a[80:95], v[36:39], v[12:15], a[80:95]
	v_mfma_f32_32x32x16_bf16 a[64:79], v[44:47], v[12:15], a[64:79]
	v_mfma_f32_32x32x16_bf16 a[48:63], v[36:39], v[20:23], a[48:63]
	v_mfma_f32_32x32x16_bf16 a[32:47], v[44:47], v[20:23], a[32:47]
	v_mfma_f32_32x32x16_bf16 a[16:31], v[36:39], v[28:31], a[16:31]
	v_mfma_f32_32x32x16_bf16 a[0:15], v[44:47], v[28:31], a[0:15]
	ds_read_b128 v[142:145], v70 offset:36896
	ds_read_b128 v[146:149], v70 offset:41504
	ds_read_b128 v[150:153], v70 offset:46112
	ds_read_b128 v[154:157], v70 offset:50720
	ds_read_b128 v[158:161], v71 offset:18464
	ds_read_b128 v[162:165], v71 offset:23072
	s_waitcnt lgkmcnt(7)
	v_mfma_f32_32x32x16_bf16 a[112:127], v[134:137], v[52:55], a[112:127]
	global_load_dwordx4 v[4:7], v[102:103], off offset:1152
	s_waitcnt lgkmcnt(6)
	v_mfma_f32_32x32x16_bf16 a[96:111], v[138:141], v[52:55], a[96:111]
	global_load_dwordx4 v[12:15], v[100:101], off offset:1152
	v_mfma_f32_32x32x16_bf16 a[80:95], v[134:137], v[60:63], a[80:95]
	global_load_dwordx4 v[20:23], v[98:99], off offset:1152
	v_mfma_f32_32x32x16_bf16 a[64:79], v[138:141], v[60:63], a[64:79]
	global_load_dwordx4 v[28:31], v[96:97], off offset:1152
	v_mfma_f32_32x32x16_bf16 a[48:63], v[134:137], v[126:129], a[48:63]
	global_load_dwordx4 v[36:39], v[94:95], off offset:1152
	v_mfma_f32_32x32x16_bf16 a[32:47], v[138:141], v[126:129], a[32:47]
	global_load_dwordx4 v[44:47], v[92:93], off offset:1152
	v_mfma_f32_32x32x16_bf16 a[16:31], v[134:137], v[130:133], a[16:31]
	global_load_dwordx4 v[52:55], v[90:91], off offset:1152
	v_mfma_f32_32x32x16_bf16 a[0:15], v[138:141], v[130:133], a[0:15]
	global_load_dwordx4 v[60:63], v[88:89], off offset:1152
	ds_read_b128 v[126:129], v70 offset:36928
	ds_read_b128 v[130:133], v70 offset:41536
	ds_read_b128 v[134:137], v70 offset:46144
	ds_read_b128 v[138:141], v70 offset:50752
	ds_read_b128 v[166:169], v71 offset:18496
	ds_read_b128 v[170:173], v71 offset:23104
	s_waitcnt lgkmcnt(7)
	v_mfma_f32_32x32x16_bf16 a[112:127], v[158:161], v[142:145], a[112:127]
	s_waitcnt vmcnt(19)
	ds_write_b128 v104, v[0:3]
	s_waitcnt vmcnt(18)
	ds_write_b128 v104, v[8:11] offset:4608
	s_waitcnt lgkmcnt(8)
	v_mfma_f32_32x32x16_bf16 a[96:111], v[162:165], v[142:145], a[96:111]
	s_waitcnt vmcnt(17)
	ds_write_b128 v104, v[16:19] offset:9216
	s_waitcnt vmcnt(16)
	ds_write_b128 v104, v[24:27] offset:13824
	v_mfma_f32_32x32x16_bf16 a[80:95], v[158:161], v[146:149], a[80:95]
	s_waitcnt vmcnt(15)
	ds_write_b128 v104, v[32:35] offset:18432
	s_waitcnt vmcnt(14)
	ds_write_b128 v104, v[40:43] offset:23040
	v_mfma_f32_32x32x16_bf16 a[64:79], v[162:165], v[146:149], a[64:79]
	s_waitcnt vmcnt(13)
	ds_write_b128 v104, v[48:51] offset:27648
	s_waitcnt vmcnt(12)
	ds_write_b128 v104, v[56:59] offset:32256
	v_mfma_f32_32x32x16_bf16 a[48:63], v[158:161], v[150:153], a[48:63]
	s_waitcnt vmcnt(11)
	ds_write_b128 v105, v[110:113]
	s_waitcnt vmcnt(10)
	ds_write_b128 v105, v[114:117] offset:4608
	v_mfma_f32_32x32x16_bf16 a[32:47], v[162:165], v[150:153], a[32:47]
	s_waitcnt vmcnt(9)
	ds_write_b128 v105, v[118:121] offset:9216
	s_waitcnt vmcnt(8)
	ds_write_b128 v105, v[122:125] offset:13824
	v_mfma_f32_32x32x16_bf16 a[16:31], v[158:161], v[154:157], a[16:31]
	v_mfma_f32_32x32x16_bf16 a[0:15], v[162:165], v[154:157], a[0:15]
	ds_read_b128 v[0:3], v70 offset:36960
	ds_read_b128 v[8:11], v70 offset:41568
	ds_read_b128 v[16:19], v70 offset:46176
	ds_read_b128 v[24:27], v70 offset:50784
	ds_read_b128 v[32:35], v71 offset:18528
	ds_read_b128 v[40:43], v71 offset:23136
	s_waitcnt lgkmcnt(14)
	v_mfma_f32_32x32x16_bf16 a[112:127], v[166:169], v[126:129], a[112:127]
	global_load_dwordx4 v[110:113], v[86:87], off offset:1152
	v_mfma_f32_32x32x16_bf16 a[96:111], v[170:173], v[126:129], a[96:111]
	global_load_dwordx4 v[114:117], v[84:85], off offset:1152
	v_mfma_f32_32x32x16_bf16 a[80:95], v[166:169], v[130:133], a[80:95]
	global_load_dwordx4 v[118:121], v[82:83], off offset:1152
	v_mfma_f32_32x32x16_bf16 a[64:79], v[170:173], v[130:133], a[64:79]
	global_load_dwordx4 v[122:125], v[80:81], off offset:1152
	v_mfma_f32_32x32x16_bf16 a[48:63], v[166:169], v[134:137], a[48:63]
	v_mfma_f32_32x32x16_bf16 a[32:47], v[170:173], v[134:137], a[32:47]
	v_mfma_f32_32x32x16_bf16 a[16:31], v[166:169], v[138:141], a[16:31]
	v_mfma_f32_32x32x16_bf16 a[0:15], v[170:173], v[138:141], a[0:15]
	s_waitcnt lgkmcnt(0)
	s_barrier
; template <int TJ, bool SWAP, int NK, class Epi>
; DI void gemm_phase(const u16* __restrict__ A, size_t strideAz, int lda, const u16* __restrict__ Bt, size_t strideBz, int ldb,
;                    int Z, int Mt, int Nt, int GM, int K, char* smem, const Epi& epi, int vt) {
;     ...
;     for (int kt = 0; kt < NK; ++kt) {
;       constexpr int dummy = 0; (void)dummy;
;       const int u = kt & 1;
;       const u16* as = As + u * 256 * 72 + (128 * wm + r) * 72 + 8 * h;
;       const u16* bs = Bs + u * BN * 72 + (32 * TJ * wn + r) * 72 + 8 * h;
;       if (kt == 0) {
; #pragma unroll
;         for (int i = 0; i < 4; ++i) af[0][i] = *(const bf16x8*)(as + (32 * i) * 72);
; #pragma unroll
;         for (int j = 0; j < TJ; ++j) bfr[0][j] = *(const bf16x8*)(bs + (32 * j) * 72);
;       }
; #pragma unroll
;       for (int ks = 0; ks < 4; ++ks) {
;         if (ks < 3) {
; #pragma unroll
;           for (int i = 0; i < 4; ++i) af[(ks + 1) & 1][i] = *(const bf16x8*)(as + (32 * i) * 72 + 16 * (ks + 1));
; #pragma unroll
;           for (int j = 0; j < TJ; ++j) bfr[(ks + 1) & 1][j] = *(const bf16x8*)(bs + (32 * j) * 72 + 16 * (ks + 1));
;         } else if (kt + 1 < NK) {
;           const u16* asn = As + (u ^ 1) * 256 * 72 + (128 * wm + r) * 72 + 8 * h;
;           const u16* bsn = Bs + (u ^ 1) * BN * 72 + (32 * TJ * wn + r) * 72 + 8 * h;
; #pragma unroll
;           for (int i = 0; i < 4; ++i) af[0][i] = *(const bf16x8*)(asn + (32 * i) * 72);
; #pragma unroll
;           for (int j = 0; j < TJ; ++j) bfr[0][j] = *(const bf16x8*)(bsn + (32 * j) * 72);
;         }
;         __builtin_amdgcn_sched_barrier(0);
; #pragma unroll
;         for (int i = 0; i < 4; ++i)
; #pragma unroll
;           for (int j = 0; j < TJ; ++j)
;             acc[i][j] = SWAP ? MFMA32(bfr[ks & 1][j], af[ks & 1][i], acc[i][j]) : MFMA32(af[ks & 1][i], bfr[ks & 1][j], acc[i][j]);
;         if (ks == 0 && kt + 2 < NK) {
;           const u16* ag = Ag + (kt + 2) * 64;
; #pragma unroll
;           for (int i = 0; i < 8; ++i) ra[u][i] = *(const u32x4*)(ag + aoff[i]);
; #pragma unroll
;           for (int i = 0; i < 8; ++i) { __builtin_amdgcn_sched_group_barrier(0x008, 1, 0); __builtin_amdgcn_sched_group_barrier(0x020, 1, 0); }
;         }
;         if (ks == 2 && kt + 2 < NK) {
;           const u16* bg = Bg + (kt + 2) * 64;
; #pragma unroll
	ds_read_b128 v[48:51], v70
	ds_read_b128 v[56:59], v70 offset:4608
	ds_read_b128 v[126:129], v70 offset:9216
	ds_read_b128 v[130:133], v70 offset:13824
	ds_read_b128 v[134:137], v71
	ds_read_b128 v[138:141], v71 offset:4608
	v_mfma_f32_32x32x16_bf16 a[112:127], v[32:35], v[0:3], a[112:127]
	v_mfma_f32_32x32x16_bf16 a[96:111], v[40:43], v[0:3], a[96:111]
	v_mfma_f32_32x32x16_bf16 a[80:95], v[32:35], v[8:11], a[80:95]
	v_mfma_f32_32x32x16_bf16 a[64:79], v[40:43], v[8:11], a[64:79]
	v_mfma_f32_32x32x16_bf16 a[48:63], v[32:35], v[16:19], a[48:63]
	v_mfma_f32_32x32x16_bf16 a[32:47], v[40:43], v[16:19], a[32:47]
	v_mfma_f32_32x32x16_bf16 a[16:31], v[32:35], v[24:27], a[16:31]
	v_mfma_f32_32x32x16_bf16 a[0:15], v[40:43], v[24:27], a[0:15]
	ds_read_b128 v[142:145], v70 offset:32
	ds_read_b128 v[146:149], v70 offset:4640
	ds_read_b128 v[150:153], v70 offset:9248
	ds_read_b128 v[154:157], v70 offset:13856
	ds_read_b128 v[158:161], v71 offset:32
	ds_read_b128 v[162:165], v71 offset:4640
	s_waitcnt lgkmcnt(7)
	v_mfma_f32_32x32x16_bf16 a[112:127], v[134:137], v[48:51], a[112:127]
	global_load_dwordx4 v[0:3], v[102:103], off offset:1280
	s_waitcnt lgkmcnt(6)
	v_mfma_f32_32x32x16_bf16 a[96:111], v[138:141], v[48:51], a[96:111]
	global_load_dwordx4 v[8:11], v[100:101], off offset:1280
	v_mfma_f32_32x32x16_bf16 a[80:95], v[134:137], v[56:59], a[80:95]
	global_load_dwordx4 v[16:19], v[98:99], off offset:1280
	v_mfma_f32_32x32x16_bf16 a[64:79], v[138:141], v[56:59], a[64:79]
	global_load_dwordx4 v[24:27], v[96:97], off offset:1280
	v_mfma_f32_32x32x16_bf16 a[48:63], v[134:137], v[126:129], a[48:63]
	global_load_dwordx4 v[32:35], v[94:95], off offset:1280
	v_mfma_f32_32x32x16_bf16 a[32:47], v[138:141], v[126:129], a[32:47]
	global_load_dwordx4 v[40:43], v[92:93], off offset:1280
	v_mfma_f32_32x32x16_bf16 a[16:31], v[134:137], v[130:133], a[16:31]
	global_load_dwordx4 v[48:51], v[90:91], off offset:1280
	v_mfma_f32_32x32x16_bf16 a[0:15], v[138:141], v[130:133], a[0:15]
	global_load_dwordx4 v[56:59], v[88:89], off offset:1280
	ds_read_b128 v[126:129], v70 offset:64
	ds_read_b128 v[130:133], v70 offset:4672
	ds_read_b128 v[134:137], v70 offset:9280
	ds_read_b128 v[138:141], v70 offset:13888
	ds_read_b128 v[166:169], v71 offset:64
	ds_read_b128 v[170:173], v71 offset:4672
	s_waitcnt lgkmcnt(7)
	v_mfma_f32_32x32x16_bf16 a[112:127], v[158:161], v[142:145], a[112:127]
	s_waitcnt vmcnt(19)
	ds_write_b128 v104, v[4:7] offset:36864
	s_waitcnt vmcnt(18)
	ds_write_b128 v104, v[12:15] offset:41472
	s_waitcnt lgkmcnt(8)
	v_mfma_f32_32x32x16_bf16 a[96:111], v[162:165], v[142:145], a[96:111]
	s_waitcnt vmcnt(17)
	ds_write_b128 v104, v[20:23] offset:46080
	s_waitcnt vmcnt(16)
	ds_write_b128 v104, v[28:31] offset:50688
	v_mfma_f32_32x32x16_bf16 a[80:95], v[158:161], v[146:149], a[80:95]
	s_waitcnt vmcnt(15)
	ds_write_b128 v104, v[36:39] offset:55296
	s_waitcnt vmcnt(14)
	ds_write_b128 v104, v[44:47] offset:59904
	v_mfma_f32_32x32x16_bf16 a[64:79], v[162:165], v[146:149], a[64:79]
	s_waitcnt vmcnt(13)
	ds_write_b128 v104, v[52:55] offset:64512
	s_waitcnt vmcnt(12)
	ds_write_b128 v108, v[60:63]
	v_mfma_f32_32x32x16_bf16 a[48:63], v[158:161], v[150:153], a[48:63]
	s_waitcnt vmcnt(11)
	ds_write_b128 v105, v[110:113] offset:18432
	s_waitcnt vmcnt(10)
	ds_write_b128 v105, v[114:117] offset:23040
	v_mfma_f32_32x32x16_bf16 a[32:47], v[162:165], v[150:153], a[32:47]
	s_waitcnt vmcnt(9)
	ds_write_b128 v105, v[118:121] offset:27648
	s_waitcnt vmcnt(8)
	ds_write_b128 v105, v[122:125] offset:32256
	v_mfma_f32_32x32x16_bf16 a[16:31], v[158:161], v[154:157], a[16:31]
	v_mfma_f32_32x32x16_bf16 a[0:15], v[162:165], v[154:157], a[0:15]
	ds_read_b128 v[4:7], v70 offset:96
	ds_read_b128 v[12:15], v70 offset:4704
	ds_read_b128 v[20:23], v70 offset:9312
	ds_read_b128 v[28:31], v70 offset:13920
	ds_read_b128 v[36:39], v71 offset:96
	ds_read_b128 v[44:47], v71 offset:4704
	s_waitcnt lgkmcnt(14)
	v_mfma_f32_32x32x16_bf16 a[112:127], v[166:169], v[126:129], a[112:127]
	global_load_dwordx4 v[110:113], v[86:87], off offset:1280
	v_mfma_f32_32x32x16_bf16 a[96:111], v[170:173], v[126:129], a[96:111]
	global_load_dwordx4 v[114:117], v[84:85], off offset:1280
	v_mfma_f32_32x32x16_bf16 a[80:95], v[166:169], v[130:133], a[80:95]
	global_load_dwordx4 v[118:121], v[82:83], off offset:1280
	v_mfma_f32_32x32x16_bf16 a[64:79], v[170:173], v[130:133], a[64:79]
	global_load_dwordx4 v[122:125], v[80:81], off offset:1280
	v_mfma_f32_32x32x16_bf16 a[48:63], v[166:169], v[134:137], a[48:63]
	v_mfma_f32_32x32x16_bf16 a[32:47], v[170:173], v[134:137], a[32:47]
	v_mfma_f32_32x32x16_bf16 a[16:31], v[166:169], v[138:141], a[16:31]
	v_mfma_f32_32x32x16_bf16 a[0:15], v[170:173], v[138:141], a[0:15]
	s_waitcnt lgkmcnt(0)
	s_barrier
; template <int TJ, bool SWAP, int NK, class Epi>
; DI void gemm_phase(const u16* __restrict__ A, size_t strideAz, int lda, const u16* __restrict__ Bt, size_t strideBz, int ldb,
;                    int Z, int Mt, int Nt, int GM, int K, char* smem, const Epi& epi, int vt) {
;     ...
;     for (int kt = 0; kt < NK; ++kt) {
;       constexpr int dummy = 0; (void)dummy;
;       const int u = kt & 1;
;       const u16* as = As + u * 256 * 72 + (128 * wm + r) * 72 + 8 * h;
;       const u16* bs = Bs + u * BN * 72 + (32 * TJ * wn + r) * 72 + 8 * h;
;       if (kt == 0) {
; #pragma unroll
;         for (int i = 0; i < 4; ++i) af[0][i] = *(const bf16x8*)(as + (32 * i) * 72);
; #pragma unroll
;         for (int j = 0; j < TJ; ++j) bfr[0][j] = *(const bf16x8*)(bs + (32 * j) * 72);
;       }
; #pragma unroll
;       for (int ks = 0; ks < 4; ++ks) {
;         if (ks < 3) {
; #pragma unroll
;           for (int i = 0; i < 4; ++i) af[(ks + 1) & 1][i] = *(const bf16x8*)(as + (32 * i) * 72 + 16 * (ks + 1));
; #pragma unroll
;           for (int j = 0; j < TJ; ++j) bfr[(ks + 1) & 1][j] = *(const bf16x8*)(bs + (32 * j) * 72 + 16 * (ks + 1));
;         } else if (kt + 1 < NK) {
;           const u16* asn = As + (u ^ 1) * 256 * 72 + (128 * wm + r) * 72 + 8 * h;
;           const u16* bsn = Bs + (u ^ 1) * BN * 72 + (32 * TJ * wn + r) * 72 + 8 * h;
; #pragma unroll
;           for (int i = 0; i < 4; ++i) af[0][i] = *(const bf16x8*)(asn + (32 * i) * 72);
; #pragma unroll
;           for (int j = 0; j < TJ; ++j) bfr[0][j] = *(const bf16x8*)(bsn + (32 * j) * 72);
;         }
;         __builtin_amdgcn_sched_barrier(0);
; #pragma unroll
;         for (int i = 0; i < 4; ++i)
; #pragma unroll
;           for (int j = 0; j < TJ; ++j)
;             acc[i][j] = SWAP ? MFMA32(bfr[ks & 1][j], af[ks & 1][i], acc[i][j]) : MFMA32(af[ks & 1][i], bfr[ks & 1][j], acc[i][j]);
;         if (ks == 0 && kt + 2 < NK) {
;           const u16* ag = Ag + (kt + 2) * 64;
; #pragma unroll
;           for (int i = 0; i < 8; ++i) ra[u][i] = *(const u32x4*)(ag + aoff[i]);
; #pragma unroll
;           for (int i = 0; i < 8; ++i) { __builtin_amdgcn_sched_group_barrier(0x008, 1, 0); __builtin_amdgcn_sched_group_barrier(0x020, 1, 0); }
;         }
;         if (ks == 2 && kt + 2 < NK) {
;           const u16* bg = Bg + (kt + 2) * 64;
; #pragma unroll
	ds_read_b128 v[52:55], v70 offset:36864
	ds_read_b128 v[60:63], v70 offset:41472
	ds_read_b128 v[126:129], v70 offset:46080
	ds_read_b128 v[130:133], v70 offset:50688
	ds_read_b128 v[134:137], v71 offset:18432
	ds_read_b128 v[138:141], v71 offset:23040
	v_mfma_f32_32x32x16_bf16 a[112:127], v[36:39], v[4:7], a[112:127]
	v_mfma_f32_32x32x16_bf16 a[96:111], v[44:47], v[4:7], a[96:111]
	v_mfma_f32_32x32x16_bf16 a[80:95], v[36:39], v[12:15], a[80:95]
	v_mfma_f32_32x32x16_bf16 a[64:79], v[44:47], v[12:15], a[64:79]
	v_mfma_f32_32x32x16_bf16 a[48:63], v[36:39], v[20:23], a[48:63]
	v_mfma_f32_32x32x16_bf16 a[32:47], v[44:47], v[20:23], a[32:47]
	v_mfma_f32_32x32x16_bf16 a[16:31], v[36:39], v[28:31], a[16:31]
	v_mfma_f32_32x32x16_bf16 a[0:15], v[44:47], v[28:31], a[0:15]
	ds_read_b128 v[142:145], v70 offset:36896
	ds_read_b128 v[146:149], v70 offset:41504
	ds_read_b128 v[150:153], v70 offset:46112
	ds_read_b128 v[154:157], v70 offset:50720
	ds_read_b128 v[158:161], v71 offset:18464
	ds_read_b128 v[162:165], v71 offset:23072
	s_waitcnt lgkmcnt(7)
	v_mfma_f32_32x32x16_bf16 a[112:127], v[134:137], v[52:55], a[112:127]
	global_load_dwordx4 v[4:7], v[102:103], off offset:1408
	s_waitcnt lgkmcnt(6)
	v_mfma_f32_32x32x16_bf16 a[96:111], v[138:141], v[52:55], a[96:111]
	global_load_dwordx4 v[12:15], v[100:101], off offset:1408
	v_mfma_f32_32x32x16_bf16 a[80:95], v[134:137], v[60:63], a[80:95]
	global_load_dwordx4 v[20:23], v[98:99], off offset:1408
	v_mfma_f32_32x32x16_bf16 a[64:79], v[138:141], v[60:63], a[64:79]
	global_load_dwordx4 v[28:31], v[96:97], off offset:1408
	v_mfma_f32_32x32x16_bf16 a[48:63], v[134:137], v[126:129], a[48:63]
	global_load_dwordx4 v[36:39], v[94:95], off offset:1408
	v_mfma_f32_32x32x16_bf16 a[32:47], v[138:141], v[126:129], a[32:47]
	global_load_dwordx4 v[44:47], v[92:93], off offset:1408
	v_mfma_f32_32x32x16_bf16 a[16:31], v[134:137], v[130:133], a[16:31]
	global_load_dwordx4 v[52:55], v[90:91], off offset:1408
	v_mfma_f32_32x32x16_bf16 a[0:15], v[138:141], v[130:133], a[0:15]
	global_load_dwordx4 v[60:63], v[88:89], off offset:1408
	ds_read_b128 v[126:129], v70 offset:36928
	ds_read_b128 v[130:133], v70 offset:41536
	ds_read_b128 v[134:137], v70 offset:46144
	ds_read_b128 v[138:141], v70 offset:50752
	ds_read_b128 v[166:169], v71 offset:18496
	ds_read_b128 v[170:173], v71 offset:23104
	s_waitcnt lgkmcnt(7)
	v_mfma_f32_32x32x16_bf16 a[112:127], v[158:161], v[142:145], a[112:127]
	s_waitcnt vmcnt(19)
	ds_write_b128 v104, v[0:3]
	s_waitcnt vmcnt(18)
	ds_write_b128 v104, v[8:11] offset:4608
	s_waitcnt lgkmcnt(8)
	v_mfma_f32_32x32x16_bf16 a[96:111], v[162:165], v[142:145], a[96:111]
	s_waitcnt vmcnt(17)
	ds_write_b128 v104, v[16:19] offset:9216
	s_waitcnt vmcnt(16)
	ds_write_b128 v104, v[24:27] offset:13824
	v_mfma_f32_32x32x16_bf16 a[80:95], v[158:161], v[146:149], a[80:95]
	s_waitcnt vmcnt(15)
	ds_write_b128 v104, v[32:35] offset:18432
	s_waitcnt vmcnt(14)
	ds_write_b128 v104, v[40:43] offset:23040
	v_mfma_f32_32x32x16_bf16 a[64:79], v[162:165], v[146:149], a[64:79]
	s_waitcnt vmcnt(13)
	ds_write_b128 v104, v[48:51] offset:27648
	s_waitcnt vmcnt(12)
	ds_write_b128 v104, v[56:59] offset:32256
	v_mfma_f32_32x32x16_bf16 a[48:63], v[158:161], v[150:153], a[48:63]
	s_waitcnt vmcnt(11)
	ds_write_b128 v105, v[110:113]
	s_waitcnt vmcnt(10)
	ds_write_b128 v105, v[114:117] offset:4608
	v_mfma_f32_32x32x16_bf16 a[32:47], v[162:165], v[150:153], a[32:47]
	s_waitcnt vmcnt(9)
	ds_write_b128 v105, v[118:121] offset:9216
	s_waitcnt vmcnt(8)
	ds_write_b128 v105, v[122:125] offset:13824
	v_mfma_f32_32x32x16_bf16 a[16:31], v[158:161], v[154:157], a[16:31]
	v_mfma_f32_32x32x16_bf16 a[0:15], v[162:165], v[154:157], a[0:15]
	ds_read_b128 v[0:3], v70 offset:36960
	ds_read_b128 v[8:11], v70 offset:41568
	ds_read_b128 v[16:19], v70 offset:46176
	ds_read_b128 v[24:27], v70 offset:50784
	ds_read_b128 v[32:35], v71 offset:18528
	ds_read_b128 v[40:43], v71 offset:23136
	s_waitcnt lgkmcnt(14)
	v_mfma_f32_32x32x16_bf16 a[112:127], v[166:169], v[126:129], a[112:127]
	global_load_dwordx4 v[110:113], v[86:87], off offset:1408
	v_mfma_f32_32x32x16_bf16 a[96:111], v[170:173], v[126:129], a[96:111]
	global_load_dwordx4 v[114:117], v[84:85], off offset:1408
	v_mfma_f32_32x32x16_bf16 a[80:95], v[166:169], v[130:133], a[80:95]
	global_load_dwordx4 v[118:121], v[82:83], off offset:1408
	v_mfma_f32_32x32x16_bf16 a[64:79], v[170:173], v[130:133], a[64:79]
	global_load_dwordx4 v[122:125], v[80:81], off offset:1408
	v_mfma_f32_32x32x16_bf16 a[48:63], v[166:169], v[134:137], a[48:63]
	v_mfma_f32_32x32x16_bf16 a[32:47], v[170:173], v[134:137], a[32:47]
	v_mfma_f32_32x32x16_bf16 a[16:31], v[166:169], v[138:141], a[16:31]
	v_mfma_f32_32x32x16_bf16 a[0:15], v[170:173], v[138:141], a[0:15]
	s_waitcnt lgkmcnt(0)
	s_barrier
; template <int TJ, bool SWAP, int NK, class Epi>
; DI void gemm_phase(const u16* __restrict__ A, size_t strideAz, int lda, const u16* __restrict__ Bt, size_t strideBz, int ldb,
;                    int Z, int Mt, int Nt, int GM, int K, char* smem, const Epi& epi, int vt) {
;     ...
;     for (int kt = 0; kt < NK; ++kt) {
;       constexpr int dummy = 0; (void)dummy;
;       const int u = kt & 1;
;       const u16* as = As + u * 256 * 72 + (128 * wm + r) * 72 + 8 * h;
;       const u16* bs = Bs + u * BN * 72 + (32 * TJ * wn + r) * 72 + 8 * h;
;       if (kt == 0) {
; #pragma unroll
;         for (int i = 0; i < 4; ++i) af[0][i] = *(const bf16x8*)(as + (32 * i) * 72);
; #pragma unroll
;         for (int j = 0; j < TJ; ++j) bfr[0][j] = *(const bf16x8*)(bs + (32 * j) * 72);
;       }
; #pragma unroll
;       for (int ks = 0; ks < 4; ++ks) {
;         if (ks < 3) {
; #pragma unroll
;           for (int i = 0; i < 4; ++i) af[(ks + 1) & 1][i] = *(const bf16x8*)(as + (32 * i) * 72 + 16 * (ks + 1));
; #pragma unroll
;           for (int j = 0; j < TJ; ++j) bfr[(ks + 1) & 1][j] = *(const bf16x8*)(bs + (32 * j) * 72 + 16 * (ks + 1));
;         } else if (kt + 1 < NK) {
;           const u16* asn = As + (u ^ 1) * 256 * 72 + (128 * wm + r) * 72 + 8 * h;
;           const u16* bsn = Bs + (u ^ 1) * BN * 72 + (32 * TJ * wn + r) * 72 + 8 * h;
; #pragma unroll
;           for (int i = 0; i < 4; ++i) af[0][i] = *(const bf16x8*)(asn + (32 * i) * 72);
; #pragma unroll
;           for (int j = 0; j < TJ; ++j) bfr[0][j] = *(const bf16x8*)(bsn + (32 * j) * 72);
;         }
;         __builtin_amdgcn_sched_barrier(0);
; #pragma unroll
;         for (int i = 0; i < 4; ++i)
; #pragma unroll
;           for (int j = 0; j < TJ; ++j)
;             acc[i][j] = SWAP ? MFMA32(bfr[ks & 1][j], af[ks & 1][i], acc[i][j]) : MFMA32(af[ks & 1][i], bfr[ks & 1][j], acc[i][j]);
;         if (ks == 0 && kt + 2 < NK) {
;           const u16* ag = Ag + (kt + 2) * 64;
; #pragma unroll
;           for (int i = 0; i < 8; ++i) ra[u][i] = *(const u32x4*)(ag + aoff[i]);
; #pragma unroll
;           for (int i = 0; i < 8; ++i) { __builtin_amdgcn_sched_group_barrier(0x008, 1, 0); __builtin_amdgcn_sched_group_barrier(0x020, 1, 0); }
;         }
;         if (ks == 2 && kt + 2 < NK) {
;           const u16* bg = Bg + (kt + 2) * 64;
; #pragma unroll
	ds_read_b128 v[48:51], v70
	ds_read_b128 v[56:59], v70 offset:4608
	ds_read_b128 v[126:129], v70 offset:9216
	ds_read_b128 v[130:133], v70 offset:13824
	ds_read_b128 v[134:137], v71
	ds_read_b128 v[138:141], v71 offset:4608
	v_mfma_f32_32x32x16_bf16 a[112:127], v[32:35], v[0:3], a[112:127]
	v_mfma_f32_32x32x16_bf16 a[96:111], v[40:43], v[0:3], a[96:111]
	v_mfma_f32_32x32x16_bf16 a[80:95], v[32:35], v[8:11], a[80:95]
	v_mfma_f32_32x32x16_bf16 a[64:79], v[40:43], v[8:11], a[64:79]
	v_mfma_f32_32x32x16_bf16 a[48:63], v[32:35], v[16:19], a[48:63]
	v_mfma_f32_32x32x16_bf16 a[32:47], v[40:43], v[16:19], a[32:47]
	v_mfma_f32_32x32x16_bf16 a[16:31], v[32:35], v[24:27], a[16:31]
	v_mfma_f32_32x32x16_bf16 a[0:15], v[40:43], v[24:27], a[0:15]
	ds_read_b128 v[142:145], v70 offset:32
	ds_read_b128 v[146:149], v70 offset:4640
	ds_read_b128 v[150:153], v70 offset:9248
	ds_read_b128 v[154:157], v70 offset:13856
	ds_read_b128 v[158:161], v71 offset:32
	ds_read_b128 v[162:165], v71 offset:4640
	s_waitcnt lgkmcnt(7)
	v_mfma_f32_32x32x16_bf16 a[112:127], v[134:137], v[48:51], a[112:127]
	global_load_dwordx4 v[0:3], v[102:103], off offset:1536
	s_waitcnt lgkmcnt(6)
	v_mfma_f32_32x32x16_bf16 a[96:111], v[138:141], v[48:51], a[96:111]
	global_load_dwordx4 v[8:11], v[100:101], off offset:1536
	v_mfma_f32_32x32x16_bf16 a[80:95], v[134:137], v[56:59], a[80:95]
	global_load_dwordx4 v[16:19], v[98:99], off offset:1536
	v_mfma_f32_32x32x16_bf16 a[64:79], v[138:141], v[56:59], a[64:79]
	global_load_dwordx4 v[24:27], v[96:97], off offset:1536
	v_mfma_f32_32x32x16_bf16 a[48:63], v[134:137], v[126:129], a[48:63]
	global_load_dwordx4 v[32:35], v[94:95], off offset:1536
	v_mfma_f32_32x32x16_bf16 a[32:47], v[138:141], v[126:129], a[32:47]
	global_load_dwordx4 v[40:43], v[92:93], off offset:1536
	v_mfma_f32_32x32x16_bf16 a[16:31], v[134:137], v[130:133], a[16:31]
	global_load_dwordx4 v[48:51], v[90:91], off offset:1536
	v_mfma_f32_32x32x16_bf16 a[0:15], v[138:141], v[130:133], a[0:15]
	global_load_dwordx4 v[56:59], v[88:89], off offset:1536
	ds_read_b128 v[126:129], v70 offset:64
	ds_read_b128 v[130:133], v70 offset:4672
	ds_read_b128 v[134:137], v70 offset:9280
	ds_read_b128 v[138:141], v70 offset:13888
	ds_read_b128 v[166:169], v71 offset:64
	ds_read_b128 v[170:173], v71 offset:4672
	s_waitcnt lgkmcnt(7)
	v_mfma_f32_32x32x16_bf16 a[112:127], v[158:161], v[142:145], a[112:127]
	s_waitcnt vmcnt(19)
	ds_write_b128 v104, v[4:7] offset:36864
	s_waitcnt vmcnt(18)
	ds_write_b128 v104, v[12:15] offset:41472
	s_waitcnt lgkmcnt(8)
	v_mfma_f32_32x32x16_bf16 a[96:111], v[162:165], v[142:145], a[96:111]
	s_waitcnt vmcnt(17)
	ds_write_b128 v104, v[20:23] offset:46080
	s_waitcnt vmcnt(16)
	ds_write_b128 v104, v[28:31] offset:50688
	v_mfma_f32_32x32x16_bf16 a[80:95], v[158:161], v[146:149], a[80:95]
	s_waitcnt vmcnt(15)
	ds_write_b128 v104, v[36:39] offset:55296
	s_waitcnt vmcnt(14)
	ds_write_b128 v104, v[44:47] offset:59904
	v_mfma_f32_32x32x16_bf16 a[64:79], v[162:165], v[146:149], a[64:79]
	s_waitcnt vmcnt(13)
	ds_write_b128 v104, v[52:55] offset:64512
	s_waitcnt vmcnt(12)
	ds_write_b128 v108, v[60:63]
	v_mfma_f32_32x32x16_bf16 a[48:63], v[158:161], v[150:153], a[48:63]
	s_waitcnt vmcnt(11)
	ds_write_b128 v105, v[110:113] offset:18432
	s_waitcnt vmcnt(10)
	ds_write_b128 v105, v[114:117] offset:23040
	v_mfma_f32_32x32x16_bf16 a[32:47], v[162:165], v[150:153], a[32:47]
	s_waitcnt vmcnt(9)
	ds_write_b128 v105, v[118:121] offset:27648
	s_waitcnt vmcnt(8)
	ds_write_b128 v105, v[122:125] offset:32256
	v_mfma_f32_32x32x16_bf16 a[16:31], v[158:161], v[154:157], a[16:31]
	v_mfma_f32_32x32x16_bf16 a[0:15], v[162:165], v[154:157], a[0:15]
	ds_read_b128 v[4:7], v70 offset:96
	ds_read_b128 v[12:15], v70 offset:4704
	ds_read_b128 v[20:23], v70 offset:9312
	ds_read_b128 v[28:31], v70 offset:13920
	ds_read_b128 v[36:39], v71 offset:96
	ds_read_b128 v[44:47], v71 offset:4704
	s_waitcnt lgkmcnt(14)
	v_mfma_f32_32x32x16_bf16 a[112:127], v[166:169], v[126:129], a[112:127]
	global_load_dwordx4 v[110:113], v[86:87], off offset:1536
	v_mfma_f32_32x32x16_bf16 a[96:111], v[170:173], v[126:129], a[96:111]
	global_load_dwordx4 v[114:117], v[84:85], off offset:1536
	v_mfma_f32_32x32x16_bf16 a[80:95], v[166:169], v[130:133], a[80:95]
	global_load_dwordx4 v[118:121], v[82:83], off offset:1536
	v_mfma_f32_32x32x16_bf16 a[64:79], v[170:173], v[130:133], a[64:79]
	global_load_dwordx4 v[122:125], v[80:81], off offset:1536
	v_mfma_f32_32x32x16_bf16 a[48:63], v[166:169], v[134:137], a[48:63]
	v_mfma_f32_32x32x16_bf16 a[32:47], v[170:173], v[134:137], a[32:47]
	v_mfma_f32_32x32x16_bf16 a[16:31], v[166:169], v[138:141], a[16:31]
	v_mfma_f32_32x32x16_bf16 a[0:15], v[170:173], v[138:141], a[0:15]
	s_waitcnt lgkmcnt(0)
	s_barrier
; template <int TJ, bool SWAP, int NK, class Epi>
; DI void gemm_phase(const u16* __restrict__ A, size_t strideAz, int lda, const u16* __restrict__ Bt, size_t strideBz, int ldb,
;                    int Z, int Mt, int Nt, int GM, int K, char* smem, const Epi& epi, int vt) {
;     ...
;     for (int kt = 0; kt < NK; ++kt) {
;       constexpr int dummy = 0; (void)dummy;
;       const int u = kt & 1;
;       const u16* as = As + u * 256 * 72 + (128 * wm + r) * 72 + 8 * h;
;       const u16* bs = Bs + u * BN * 72 + (32 * TJ * wn + r) * 72 + 8 * h;
;       if (kt == 0) {
; #pragma unroll
;         for (int i = 0; i < 4; ++i) af[0][i] = *(const bf16x8*)(as + (32 * i) * 72);
; #pragma unroll
;         for (int j = 0; j < TJ; ++j) bfr[0][j] = *(const bf16x8*)(bs + (32 * j) * 72);
;       }
; #pragma unroll
;       for (int ks = 0; ks < 4; ++ks) {
;         if (ks < 3) {
; #pragma unroll
;           for (int i = 0; i < 4; ++i) af[(ks + 1) & 1][i] = *(const bf16x8*)(as + (32 * i) * 72 + 16 * (ks + 1));
; #pragma unroll
;           for (int j = 0; j < TJ; ++j) bfr[(ks + 1) & 1][j] = *(const bf16x8*)(bs + (32 * j) * 72 + 16 * (ks + 1));
;         } else if (kt + 1 < NK) {
;           const u16* asn = As + (u ^ 1) * 256 * 72 + (128 * wm + r) * 72 + 8 * h;
;           const u16* bsn = Bs + (u ^ 1) * BN * 72 + (32 * TJ * wn + r) * 72 + 8 * h;
; #pragma unroll
;           for (int i = 0; i < 4; ++i) af[0][i] = *(const bf16x8*)(asn + (32 * i) * 72);
; #pragma unroll
;           for (int j = 0; j < TJ; ++j) bfr[0][j] = *(const bf16x8*)(bsn + (32 * j) * 72);
;         }
;         __builtin_amdgcn_sched_barrier(0);
; #pragma unroll
;         for (int i = 0; i < 4; ++i)
; #pragma unroll
;           for (int j = 0; j < TJ; ++j)
;             acc[i][j] = SWAP ? MFMA32(bfr[ks & 1][j], af[ks & 1][i], acc[i][j]) : MFMA32(af[ks & 1][i], bfr[ks & 1][j], acc[i][j]);
;         if (ks == 0 && kt + 2 < NK) {
;           const u16* ag = Ag + (kt + 2) * 64;
; #pragma unroll
;           for (int i = 0; i < 8; ++i) ra[u][i] = *(const u32x4*)(ag + aoff[i]);
; #pragma unroll
;           for (int i = 0; i < 8; ++i) { __builtin_amdgcn_sched_group_barrier(0x008, 1, 0); __builtin_amdgcn_sched_group_barrier(0x020, 1, 0); }
;         }
;         if (ks == 2 && kt + 2 < NK) {
;           const u16* bg = Bg + (kt + 2) * 64;
; #pragma unroll
	ds_read_b128 v[52:55], v70 offset:36864
	ds_read_b128 v[60:63], v70 offset:41472
	ds_read_b128 v[126:129], v70 offset:46080
	ds_read_b128 v[130:133], v70 offset:50688
	ds_read_b128 v[134:137], v71 offset:18432
	ds_read_b128 v[138:141], v71 offset:23040
	v_mfma_f32_32x32x16_bf16 a[112:127], v[36:39], v[4:7], a[112:127]
	v_mfma_f32_32x32x16_bf16 a[96:111], v[44:47], v[4:7], a[96:111]
	v_mfma_f32_32x32x16_bf16 a[80:95], v[36:39], v[12:15], a[80:95]
	v_mfma_f32_32x32x16_bf16 a[64:79], v[44:47], v[12:15], a[64:79]
	v_mfma_f32_32x32x16_bf16 a[48:63], v[36:39], v[20:23], a[48:63]
	v_mfma_f32_32x32x16_bf16 a[32:47], v[44:47], v[20:23], a[32:47]
	v_mfma_f32_32x32x16_bf16 a[16:31], v[36:39], v[28:31], a[16:31]
	v_mfma_f32_32x32x16_bf16 a[0:15], v[44:47], v[28:31], a[0:15]
	ds_read_b128 v[142:145], v70 offset:36896
	ds_read_b128 v[146:149], v70 offset:41504
	ds_read_b128 v[150:153], v70 offset:46112
	ds_read_b128 v[154:157], v70 offset:50720
	ds_read_b128 v[158:161], v71 offset:18464
	ds_read_b128 v[162:165], v71 offset:23072
	s_waitcnt lgkmcnt(7)
	v_mfma_f32_32x32x16_bf16 a[112:127], v[134:137], v[52:55], a[112:127]
	global_load_dwordx4 v[4:7], v[102:103], off offset:1664
	s_waitcnt lgkmcnt(6)
	v_mfma_f32_32x32x16_bf16 a[96:111], v[138:141], v[52:55], a[96:111]
	global_load_dwordx4 v[12:15], v[100:101], off offset:1664
	v_mfma_f32_32x32x16_bf16 a[80:95], v[134:137], v[60:63], a[80:95]
	global_load_dwordx4 v[20:23], v[98:99], off offset:1664
	v_mfma_f32_32x32x16_bf16 a[64:79], v[138:141], v[60:63], a[64:79]
	global_load_dwordx4 v[28:31], v[96:97], off offset:1664
	v_mfma_f32_32x32x16_bf16 a[48:63], v[134:137], v[126:129], a[48:63]
	global_load_dwordx4 v[36:39], v[94:95], off offset:1664
	v_mfma_f32_32x32x16_bf16 a[32:47], v[138:141], v[126:129], a[32:47]
	global_load_dwordx4 v[44:47], v[92:93], off offset:1664
	v_mfma_f32_32x32x16_bf16 a[16:31], v[134:137], v[130:133], a[16:31]
	global_load_dwordx4 v[52:55], v[90:91], off offset:1664
	v_mfma_f32_32x32x16_bf16 a[0:15], v[138:141], v[130:133], a[0:15]
	global_load_dwordx4 v[60:63], v[88:89], off offset:1664
	ds_read_b128 v[126:129], v70 offset:36928
	ds_read_b128 v[130:133], v70 offset:41536
	ds_read_b128 v[134:137], v70 offset:46144
	ds_read_b128 v[138:141], v70 offset:50752
	ds_read_b128 v[166:169], v71 offset:18496
	ds_read_b128 v[170:173], v71 offset:23104
	s_waitcnt lgkmcnt(7)
	v_mfma_f32_32x32x16_bf16 a[112:127], v[158:161], v[142:145], a[112:127]
	s_waitcnt vmcnt(19)
	ds_write_b128 v104, v[0:3]
	s_waitcnt vmcnt(18)
	ds_write_b128 v104, v[8:11] offset:4608
	s_waitcnt lgkmcnt(8)
	v_mfma_f32_32x32x16_bf16 a[96:111], v[162:165], v[142:145], a[96:111]
	s_waitcnt vmcnt(17)
	ds_write_b128 v104, v[16:19] offset:9216
	s_waitcnt vmcnt(16)
	ds_write_b128 v104, v[24:27] offset:13824
	v_mfma_f32_32x32x16_bf16 a[80:95], v[158:161], v[146:149], a[80:95]
	s_waitcnt vmcnt(15)
	ds_write_b128 v104, v[32:35] offset:18432
	s_waitcnt vmcnt(14)
	ds_write_b128 v104, v[40:43] offset:23040
	v_mfma_f32_32x32x16_bf16 a[64:79], v[162:165], v[146:149], a[64:79]
	s_waitcnt vmcnt(13)
	ds_write_b128 v104, v[48:51] offset:27648
	s_waitcnt vmcnt(12)
	ds_write_b128 v104, v[56:59] offset:32256
	v_mfma_f32_32x32x16_bf16 a[48:63], v[158:161], v[150:153], a[48:63]
	s_waitcnt vmcnt(11)
	ds_write_b128 v105, v[110:113]
	s_waitcnt vmcnt(10)
	ds_write_b128 v105, v[114:117] offset:4608
	v_mfma_f32_32x32x16_bf16 a[32:47], v[162:165], v[150:153], a[32:47]
	s_waitcnt vmcnt(9)
	ds_write_b128 v105, v[118:121] offset:9216
	s_waitcnt vmcnt(8)
	ds_write_b128 v105, v[122:125] offset:13824
	v_mfma_f32_32x32x16_bf16 a[16:31], v[158:161], v[154:157], a[16:31]
	v_mfma_f32_32x32x16_bf16 a[0:15], v[162:165], v[154:157], a[0:15]
	ds_read_b128 v[0:3], v70 offset:36960
	ds_read_b128 v[8:11], v70 offset:41568
	ds_read_b128 v[16:19], v70 offset:46176
	ds_read_b128 v[24:27], v70 offset:50784
	ds_read_b128 v[32:35], v71 offset:18528
	ds_read_b128 v[40:43], v71 offset:23136
	s_waitcnt lgkmcnt(14)
	v_mfma_f32_32x32x16_bf16 a[112:127], v[166:169], v[126:129], a[112:127]
	global_load_dwordx4 v[110:113], v[86:87], off offset:1664
	v_mfma_f32_32x32x16_bf16 a[96:111], v[170:173], v[126:129], a[96:111]
	global_load_dwordx4 v[114:117], v[84:85], off offset:1664
	v_mfma_f32_32x32x16_bf16 a[80:95], v[166:169], v[130:133], a[80:95]
	global_load_dwordx4 v[118:121], v[82:83], off offset:1664
	v_mfma_f32_32x32x16_bf16 a[64:79], v[170:173], v[130:133], a[64:79]
	global_load_dwordx4 v[122:125], v[80:81], off offset:1664
	v_mfma_f32_32x32x16_bf16 a[48:63], v[166:169], v[134:137], a[48:63]
	v_mfma_f32_32x32x16_bf16 a[32:47], v[170:173], v[134:137], a[32:47]
	v_mfma_f32_32x32x16_bf16 a[16:31], v[166:169], v[138:141], a[16:31]
	v_mfma_f32_32x32x16_bf16 a[0:15], v[170:173], v[138:141], a[0:15]
	s_waitcnt lgkmcnt(0)
	s_barrier
; template <int TJ, bool SWAP, int NK, class Epi>
; DI void gemm_phase(const u16* __restrict__ A, size_t strideAz, int lda, const u16* __restrict__ Bt, size_t strideBz, int ldb,
;                    int Z, int Mt, int Nt, int GM, int K, char* smem, const Epi& epi, int vt) {
;     ...
;     for (int kt = 0; kt < NK; ++kt) {
;       constexpr int dummy = 0; (void)dummy;
;       const int u = kt & 1;
;       const u16* as = As + u * 256 * 72 + (128 * wm + r) * 72 + 8 * h;
;       const u16* bs = Bs + u * BN * 72 + (32 * TJ * wn + r) * 72 + 8 * h;
;       if (kt == 0) {
; #pragma unroll
;         for (int i = 0; i < 4; ++i) af[0][i] = *(const bf16x8*)(as + (32 * i) * 72);
; #pragma unroll
;         for (int j = 0; j < TJ; ++j) bfr[0][j] = *(const bf16x8*)(bs + (32 * j) * 72);
;       }
; #pragma unroll
;       for (int ks = 0; ks < 4; ++ks) {
;         if (ks < 3) {
; #pragma unroll
;           for (int i = 0; i < 4; ++i) af[(ks + 1) & 1][i] = *(const bf16x8*)(as + (32 * i) * 72 + 16 * (ks + 1));
; #pragma unroll
;           for (int j = 0; j < TJ; ++j) bfr[(ks + 1) & 1][j] = *(const bf16x8*)(bs + (32 * j) * 72 + 16 * (ks + 1));
;         } else if (kt + 1 < NK) {
;           const u16* asn = As + (u ^ 1) * 256 * 72 + (128 * wm + r) * 72 + 8 * h;
;           const u16* bsn = Bs + (u ^ 1) * BN * 72 + (32 * TJ * wn + r) * 72 + 8 * h;
; #pragma unroll
;           for (int i = 0; i < 4; ++i) af[0][i] = *(const bf16x8*)(asn + (32 * i) * 72);
; #pragma unroll
;           for (int j = 0; j < TJ; ++j) bfr[0][j] = *(const bf16x8*)(bsn + (32 * j) * 72);
;         }
;         __builtin_amdgcn_sched_barrier(0);
; #pragma unroll
;         for (int i = 0; i < 4; ++i)
; #pragma unroll
;           for (int j = 0; j < TJ; ++j)
;             acc[i][j] = SWAP ? MFMA32(bfr[ks & 1][j], af[ks & 1][i], acc[i][j]) : MFMA32(af[ks & 1][i], bfr[ks & 1][j], acc[i][j]);
;         if (ks == 0 && kt + 2 < NK) {
;           const u16* ag = Ag + (kt + 2) * 64;
; #pragma unroll
;           for (int i = 0; i < 8; ++i) ra[u][i] = *(const u32x4*)(ag + aoff[i]);
; #pragma unroll
;           for (int i = 0; i < 8; ++i) { __builtin_amdgcn_sched_group_barrier(0x008, 1, 0); __builtin_amdgcn_sched_group_barrier(0x020, 1, 0); }
;         }
;         if (ks == 2 && kt + 2 < NK) {
;           const u16* bg = Bg + (kt + 2) * 64;
; #pragma unroll
	ds_read_b128 v[48:51], v70
	ds_read_b128 v[56:59], v70 offset:4608
	ds_read_b128 v[126:129], v70 offset:9216
	ds_read_b128 v[130:133], v70 offset:13824
	ds_read_b128 v[134:137], v71
	ds_read_b128 v[138:141], v71 offset:4608
	v_mfma_f32_32x32x16_bf16 a[112:127], v[32:35], v[0:3], a[112:127]
	v_mfma_f32_32x32x16_bf16 a[96:111], v[40:43], v[0:3], a[96:111]
	v_mfma_f32_32x32x16_bf16 a[80:95], v[32:35], v[8:11], a[80:95]
	v_mfma_f32_32x32x16_bf16 a[64:79], v[40:43], v[8:11], a[64:79]
	v_mfma_f32_32x32x16_bf16 a[48:63], v[32:35], v[16:19], a[48:63]
	v_mfma_f32_32x32x16_bf16 a[32:47], v[40:43], v[16:19], a[32:47]
	v_mfma_f32_32x32x16_bf16 a[16:31], v[32:35], v[24:27], a[16:31]
	v_mfma_f32_32x32x16_bf16 a[0:15], v[40:43], v[24:27], a[0:15]
	ds_read_b128 v[142:145], v70 offset:32
	ds_read_b128 v[146:149], v70 offset:4640
	ds_read_b128 v[150:153], v70 offset:9248
	ds_read_b128 v[154:157], v70 offset:13856
	ds_read_b128 v[158:161], v71 offset:32
	ds_read_b128 v[162:165], v71 offset:4640
	s_waitcnt lgkmcnt(7)
	v_mfma_f32_32x32x16_bf16 a[112:127], v[134:137], v[48:51], a[112:127]
	global_load_dwordx4 v[0:3], v[102:103], off offset:1792
	s_waitcnt lgkmcnt(6)
	v_mfma_f32_32x32x16_bf16 a[96:111], v[138:141], v[48:51], a[96:111]
	global_load_dwordx4 v[8:11], v[100:101], off offset:1792
	v_mfma_f32_32x32x16_bf16 a[80:95], v[134:137], v[56:59], a[80:95]
	global_load_dwordx4 v[16:19], v[98:99], off offset:1792
	v_mfma_f32_32x32x16_bf16 a[64:79], v[138:141], v[56:59], a[64:79]
	global_load_dwordx4 v[24:27], v[96:97], off offset:1792
	v_mfma_f32_32x32x16_bf16 a[48:63], v[134:137], v[126:129], a[48:63]
	global_load_dwordx4 v[32:35], v[94:95], off offset:1792
	v_mfma_f32_32x32x16_bf16 a[32:47], v[138:141], v[126:129], a[32:47]
	global_load_dwordx4 v[40:43], v[92:93], off offset:1792
	v_mfma_f32_32x32x16_bf16 a[16:31], v[134:137], v[130:133], a[16:31]
	global_load_dwordx4 v[48:51], v[90:91], off offset:1792
	v_mfma_f32_32x32x16_bf16 a[0:15], v[138:141], v[130:133], a[0:15]
	global_load_dwordx4 v[56:59], v[88:89], off offset:1792
	ds_read_b128 v[126:129], v70 offset:64
	ds_read_b128 v[130:133], v70 offset:4672
	ds_read_b128 v[134:137], v70 offset:9280
	ds_read_b128 v[138:141], v70 offset:13888
	ds_read_b128 v[166:169], v71 offset:64
	ds_read_b128 v[170:173], v71 offset:4672
	s_waitcnt lgkmcnt(7)
	v_mfma_f32_32x32x16_bf16 a[112:127], v[158:161], v[142:145], a[112:127]
	s_waitcnt vmcnt(19)
	ds_write_b128 v104, v[4:7] offset:36864
	s_waitcnt vmcnt(18)
	ds_write_b128 v104, v[12:15] offset:41472
	s_waitcnt lgkmcnt(8)
	v_mfma_f32_32x32x16_bf16 a[96:111], v[162:165], v[142:145], a[96:111]
	s_waitcnt vmcnt(17)
	ds_write_b128 v104, v[20:23] offset:46080
	s_waitcnt vmcnt(16)
	ds_write_b128 v104, v[28:31] offset:50688
	v_mfma_f32_32x32x16_bf16 a[80:95], v[158:161], v[146:149], a[80:95]
	s_waitcnt vmcnt(15)
	ds_write_b128 v104, v[36:39] offset:55296
	s_waitcnt vmcnt(14)
	ds_write_b128 v104, v[44:47] offset:59904
	v_mfma_f32_32x32x16_bf16 a[64:79], v[162:165], v[146:149], a[64:79]
	s_waitcnt vmcnt(13)
	ds_write_b128 v104, v[52:55] offset:64512
	s_waitcnt vmcnt(12)
	ds_write_b128 v108, v[60:63]
	v_mfma_f32_32x32x16_bf16 a[48:63], v[158:161], v[150:153], a[48:63]
	s_waitcnt vmcnt(11)
	ds_write_b128 v105, v[110:113] offset:18432
	s_waitcnt vmcnt(10)
	ds_write_b128 v105, v[114:117] offset:23040
	v_mfma_f32_32x32x16_bf16 a[32:47], v[162:165], v[150:153], a[32:47]
	s_waitcnt vmcnt(9)
	ds_write_b128 v105, v[118:121] offset:27648
	s_waitcnt vmcnt(8)
	ds_write_b128 v105, v[122:125] offset:32256
	v_mfma_f32_32x32x16_bf16 a[16:31], v[158:161], v[154:157], a[16:31]
	v_mfma_f32_32x32x16_bf16 a[0:15], v[162:165], v[154:157], a[0:15]
	ds_read_b128 v[4:7], v70 offset:96
	ds_read_b128 v[12:15], v70 offset:4704
	ds_read_b128 v[20:23], v70 offset:9312
	ds_read_b128 v[28:31], v70 offset:13920
	ds_read_b128 v[36:39], v71 offset:96
	ds_read_b128 v[44:47], v71 offset:4704
	s_waitcnt lgkmcnt(14)
	v_mfma_f32_32x32x16_bf16 a[112:127], v[166:169], v[126:129], a[112:127]
	global_load_dwordx4 v[52:55], v[86:87], off offset:1792
	v_mfma_f32_32x32x16_bf16 a[96:111], v[170:173], v[126:129], a[96:111]
	global_load_dwordx4 v[60:63], v[84:85], off offset:1792
	v_mfma_f32_32x32x16_bf16 a[80:95], v[166:169], v[130:133], a[80:95]
	global_load_dwordx4 v[110:113], v[82:83], off offset:1792
	v_mfma_f32_32x32x16_bf16 a[64:79], v[170:173], v[130:133], a[64:79]
	global_load_dwordx4 v[114:117], v[80:81], off offset:1792
	v_mfma_f32_32x32x16_bf16 a[48:63], v[166:169], v[134:137], a[48:63]
	v_mfma_f32_32x32x16_bf16 a[32:47], v[170:173], v[134:137], a[32:47]
	v_mfma_f32_32x32x16_bf16 a[16:31], v[166:169], v[138:141], a[16:31]
	v_mfma_f32_32x32x16_bf16 a[0:15], v[170:173], v[138:141], a[0:15]
	s_waitcnt lgkmcnt(0)
	s_barrier
; template <int TJ, bool SWAP, int NK, class Epi>
; DI void gemm_phase(const u16* __restrict__ A, size_t strideAz, int lda, const u16* __restrict__ Bt, size_t strideBz, int ldb,
;                    int Z, int Mt, int Nt, int GM, int K, char* smem, const Epi& epi, int vt) {
;     ...
;     for (int kt = 0; kt < NK; ++kt) {
;       constexpr int dummy = 0; (void)dummy;
;       const int u = kt & 1;
;       const u16* as = As + u * 256 * 72 + (128 * wm + r) * 72 + 8 * h;
;       const u16* bs = Bs + u * BN * 72 + (32 * TJ * wn + r) * 72 + 8 * h;
;       if (kt == 0) {
; #pragma unroll
;         for (int i = 0; i < 4; ++i) af[0][i] = *(const bf16x8*)(as + (32 * i) * 72);
; #pragma unroll
;         for (int j = 0; j < TJ; ++j) bfr[0][j] = *(const bf16x8*)(bs + (32 * j) * 72);
;       }
; #pragma unroll
;       for (int ks = 0; ks < 4; ++ks) {
;         if (ks < 3) {
; #pragma unroll
;           for (int i = 0; i < 4; ++i) af[(ks + 1) & 1][i] = *(const bf16x8*)(as + (32 * i) * 72 + 16 * (ks + 1));
; #pragma unroll
;           for (int j = 0; j < TJ; ++j) bfr[(ks + 1) & 1][j] = *(const bf16x8*)(bs + (32 * j) * 72 + 16 * (ks + 1));
;         } else if (kt + 1 < NK) {
;           const u16* asn = As + (u ^ 1) * 256 * 72 + (128 * wm + r) * 72 + 8 * h;
;           const u16* bsn = Bs + (u ^ 1) * BN * 72 + (32 * TJ * wn + r) * 72 + 8 * h;
; #pragma unroll
;           for (int i = 0; i < 4; ++i) af[0][i] = *(const bf16x8*)(asn + (32 * i) * 72);
; #pragma unroll
;           for (int j = 0; j < TJ; ++j) bfr[0][j] = *(const bf16x8*)(bsn + (32 * j) * 72);
;         }
;         __builtin_amdgcn_sched_barrier(0);
; #pragma unroll
;         for (int i = 0; i < 4; ++i)
; #pragma unroll
;           for (int j = 0; j < TJ; ++j)
;             acc[i][j] = SWAP ? MFMA32(bfr[ks & 1][j], af[ks & 1][i], acc[i][j]) : MFMA32(af[ks & 1][i], bfr[ks & 1][j], acc[i][j]);
;         if (ks == 0 && kt + 2 < NK) {
;           const u16* ag = Ag + (kt + 2) * 64;
; #pragma unroll
;           for (int i = 0; i < 8; ++i) ra[u][i] = *(const u32x4*)(ag + aoff[i]);
; #pragma unroll
;           for (int i = 0; i < 8; ++i) { __builtin_amdgcn_sched_group_barrier(0x008, 1, 0); __builtin_amdgcn_sched_group_barrier(0x020, 1, 0); }
;         }
;         if (ks == 2 && kt + 2 < NK) {
;           const u16* bg = Bg + (kt + 2) * 64;
; #pragma unroll
	ds_read_b128 v[118:121], v70 offset:36864
	ds_read_b128 v[122:125], v70 offset:41472
	ds_read_b128 v[126:129], v70 offset:46080
	ds_read_b128 v[130:133], v70 offset:50688
	ds_read_b128 v[134:137], v71 offset:18432
	ds_read_b128 v[138:141], v71 offset:23040
	v_mfma_f32_32x32x16_bf16 a[112:127], v[36:39], v[4:7], a[112:127]
	v_mfma_f32_32x32x16_bf16 a[96:111], v[44:47], v[4:7], a[96:111]
	v_mfma_f32_32x32x16_bf16 a[80:95], v[36:39], v[12:15], a[80:95]
	v_mfma_f32_32x32x16_bf16 a[64:79], v[44:47], v[12:15], a[64:79]
	v_mfma_f32_32x32x16_bf16 a[48:63], v[36:39], v[20:23], a[48:63]
	v_mfma_f32_32x32x16_bf16 a[32:47], v[44:47], v[20:23], a[32:47]
	v_mfma_f32_32x32x16_bf16 a[16:31], v[36:39], v[28:31], a[16:31]
	v_mfma_f32_32x32x16_bf16 a[0:15], v[44:47], v[28:31], a[0:15]
	ds_read_b128 v[12:15], v70 offset:36896
	ds_read_b128 v[20:23], v70 offset:41504
	ds_read_b128 v[28:31], v70 offset:46112
	ds_read_b128 v[36:39], v70 offset:50720
	ds_read_b128 v[44:47], v71 offset:18464
	ds_read_b128 v[142:145], v71 offset:23072
	s_waitcnt lgkmcnt(7)
	v_mfma_f32_32x32x16_bf16 a[112:127], v[134:137], v[118:121], a[112:127]
	global_load_dwordx4 v[4:7], v[102:103], off offset:1920
	s_waitcnt lgkmcnt(6)
	v_mfma_f32_32x32x16_bf16 a[96:111], v[138:141], v[118:121], a[96:111]
	global_load_dwordx4 v[100:103], v[100:101], off offset:1920
	v_mfma_f32_32x32x16_bf16 a[80:95], v[134:137], v[122:125], a[80:95]
	global_load_dwordx4 v[118:121], v[98:99], off offset:1920
	v_mfma_f32_32x32x16_bf16 a[64:79], v[138:141], v[122:125], a[64:79]
	global_load_dwordx4 v[96:99], v[96:97], off offset:1920
	v_mfma_f32_32x32x16_bf16 a[48:63], v[134:137], v[126:129], a[48:63]
	global_load_dwordx4 v[122:125], v[94:95], off offset:1920
	v_mfma_f32_32x32x16_bf16 a[32:47], v[138:141], v[126:129], a[32:47]
	global_load_dwordx4 v[92:95], v[92:93], off offset:1920
	v_mfma_f32_32x32x16_bf16 a[16:31], v[134:137], v[130:133], a[16:31]
	global_load_dwordx4 v[126:129], v[90:91], off offset:1920
	v_mfma_f32_32x32x16_bf16 a[0:15], v[138:141], v[130:133], a[0:15]
	global_load_dwordx4 v[88:91], v[88:89], off offset:1920
	ds_read_b128 v[130:133], v70 offset:36928
	ds_read_b128 v[134:137], v70 offset:41536
	ds_read_b128 v[138:141], v70 offset:46144
	ds_read_b128 v[146:149], v70 offset:50752
	ds_read_b128 v[150:153], v71 offset:18496
	ds_read_b128 v[154:157], v71 offset:23104
	s_waitcnt lgkmcnt(7)
	v_mfma_f32_32x32x16_bf16 a[112:127], v[44:47], v[12:15], a[112:127]
	s_waitcnt vmcnt(19)
	ds_write_b128 v104, v[0:3]
	s_waitcnt vmcnt(18)
	ds_write_b128 v104, v[8:11] offset:4608
	s_waitcnt lgkmcnt(8)
	v_mfma_f32_32x32x16_bf16 a[96:111], v[142:145], v[12:15], a[96:111]
	s_waitcnt vmcnt(17)
	ds_write_b128 v104, v[16:19] offset:9216
	s_waitcnt vmcnt(16)
	ds_write_b128 v104, v[24:27] offset:13824
	v_mfma_f32_32x32x16_bf16 a[80:95], v[44:47], v[20:23], a[80:95]
	s_waitcnt vmcnt(15)
	ds_write_b128 v104, v[32:35] offset:18432
	s_waitcnt vmcnt(14)
	ds_write_b128 v104, v[40:43] offset:23040
	v_mfma_f32_32x32x16_bf16 a[64:79], v[142:145], v[20:23], a[64:79]
	s_waitcnt vmcnt(13)
	ds_write_b128 v104, v[48:51] offset:27648
	s_waitcnt vmcnt(12)
	ds_write_b128 v104, v[56:59] offset:32256
	v_mfma_f32_32x32x16_bf16 a[48:63], v[44:47], v[28:31], a[48:63]
	s_waitcnt vmcnt(11)
	ds_write_b128 v105, v[52:55]
	s_waitcnt vmcnt(10)
	ds_write_b128 v105, v[60:63] offset:4608
	v_mfma_f32_32x32x16_bf16 a[32:47], v[142:145], v[28:31], a[32:47]
	s_waitcnt vmcnt(9)
	ds_write_b128 v105, v[110:113] offset:9216
	s_waitcnt vmcnt(8)
	ds_write_b128 v105, v[114:117] offset:13824
	v_mfma_f32_32x32x16_bf16 a[16:31], v[44:47], v[36:39], a[16:31]
	v_mfma_f32_32x32x16_bf16 a[0:15], v[142:145], v[36:39], a[0:15]
	ds_read_b128 v[0:3], v70 offset:36960
	ds_read_b128 v[8:11], v70 offset:41568
	ds_read_b128 v[12:15], v70 offset:46176
	ds_read_b128 v[16:19], v70 offset:50784
	ds_read_b128 v[20:23], v71 offset:18528
	ds_read_b128 v[24:27], v71 offset:23136
	s_waitcnt lgkmcnt(14)
	v_mfma_f32_32x32x16_bf16 a[112:127], v[150:153], v[130:133], a[112:127]
	global_load_dwordx4 v[28:31], v[86:87], off offset:1920
	v_mfma_f32_32x32x16_bf16 a[96:111], v[154:157], v[130:133], a[96:111]
	global_load_dwordx4 v[32:35], v[84:85], off offset:1920
	v_mfma_f32_32x32x16_bf16 a[80:95], v[150:153], v[134:137], a[80:95]
	global_load_dwordx4 v[36:39], v[82:83], off offset:1920
	v_mfma_f32_32x32x16_bf16 a[64:79], v[154:157], v[134:137], a[64:79]
	global_load_dwordx4 v[40:43], v[80:81], off offset:1920
	v_mfma_f32_32x32x16_bf16 a[48:63], v[150:153], v[138:141], a[48:63]
	v_mfma_f32_32x32x16_bf16 a[32:47], v[154:157], v[138:141], a[32:47]
	v_mfma_f32_32x32x16_bf16 a[16:31], v[150:153], v[146:149], a[16:31]
	v_mfma_f32_32x32x16_bf16 a[0:15], v[154:157], v[146:149], a[0:15]
	s_waitcnt lgkmcnt(0)
	s_barrier
; template <int TJ, bool SWAP, int NK, class Epi>
; DI void gemm_phase(const u16* __restrict__ A, size_t strideAz, int lda, const u16* __restrict__ Bt, size_t strideBz, int ldb,
;                    int Z, int Mt, int Nt, int GM, int K, char* smem, const Epi& epi, int vt) {
;     ...
;     for (int kt = 0; kt < NK; ++kt) {
;       constexpr int dummy = 0; (void)dummy;
;       const int u = kt & 1;
;       const u16* as = As + u * 256 * 72 + (128 * wm + r) * 72 + 8 * h;
;       const u16* bs = Bs + u * BN * 72 + (32 * TJ * wn + r) * 72 + 8 * h;
;       if (kt == 0) {
; #pragma unroll
;         for (int i = 0; i < 4; ++i) af[0][i] = *(const bf16x8*)(as + (32 * i) * 72);
; #pragma unroll
;         for (int j = 0; j < TJ; ++j) bfr[0][j] = *(const bf16x8*)(bs + (32 * j) * 72);
;       }
; #pragma unroll
;       for (int ks = 0; ks < 4; ++ks) {
;         if (ks < 3) {
; #pragma unroll
;           for (int i = 0; i < 4; ++i) af[(ks + 1) & 1][i] = *(const bf16x8*)(as + (32 * i) * 72 + 16 * (ks + 1));
; #pragma unroll
;           for (int j = 0; j < TJ; ++j) bfr[(ks + 1) & 1][j] = *(const bf16x8*)(bs + (32 * j) * 72 + 16 * (ks + 1));
;         } else if (kt + 1 < NK) {
;           const u16* asn = As + (u ^ 1) * 256 * 72 + (128 * wm + r) * 72 + 8 * h;
;           const u16* bsn = Bs + (u ^ 1) * BN * 72 + (32 * TJ * wn + r) * 72 + 8 * h;
; #pragma unroll
;           for (int i = 0; i < 4; ++i) af[0][i] = *(const bf16x8*)(asn + (32 * i) * 72);
; #pragma unroll
;           for (int j = 0; j < TJ; ++j) bfr[0][j] = *(const bf16x8*)(bsn + (32 * j) * 72);
;         }
;         __builtin_amdgcn_sched_barrier(0);
; #pragma unroll
;         for (int i = 0; i < 4; ++i)
; #pragma unroll
;           for (int j = 0; j < TJ; ++j)
;             acc[i][j] = SWAP ? MFMA32(bfr[ks & 1][j], af[ks & 1][i], acc[i][j]) : MFMA32(af[ks & 1][i], bfr[ks & 1][j], acc[i][j]);
;         if (ks == 0 && kt + 2 < NK) {
;           const u16* ag = Ag + (kt + 2) * 64;
; #pragma unroll
;           for (int i = 0; i < 8; ++i) ra[u][i] = *(const u32x4*)(ag + aoff[i]);
; #pragma unroll
;           for (int i = 0; i < 8; ++i) { __builtin_amdgcn_sched_group_barrier(0x008, 1, 0); __builtin_amdgcn_sched_group_barrier(0x020, 1, 0); }
;         }
;         if (ks == 2 && kt + 2 < NK) {
;           const u16* bg = Bg + (kt + 2) * 64;
; #pragma unroll
	ds_read_b128 v[44:47], v70
	ds_read_b128 v[48:51], v70 offset:4608
	ds_read_b128 v[52:55], v70 offset:9216
	ds_read_b128 v[56:59], v70 offset:13824
	ds_read_b128 v[60:63], v71
	ds_read_b128 v[80:83], v71 offset:4608
	v_mfma_f32_32x32x16_bf16 a[112:127], v[20:23], v[0:3], a[112:127]
	v_mfma_f32_32x32x16_bf16 a[96:111], v[24:27], v[0:3], a[96:111]
	v_mfma_f32_32x32x16_bf16 a[80:95], v[20:23], v[8:11], a[80:95]
	v_mfma_f32_32x32x16_bf16 a[64:79], v[24:27], v[8:11], a[64:79]
	v_mfma_f32_32x32x16_bf16 a[48:63], v[20:23], v[12:15], a[48:63]
	v_mfma_f32_32x32x16_bf16 a[32:47], v[24:27], v[12:15], a[32:47]
	v_mfma_f32_32x32x16_bf16 a[16:31], v[20:23], v[16:19], a[16:31]
	v_mfma_f32_32x32x16_bf16 a[0:15], v[24:27], v[16:19], a[0:15]
	ds_read_b128 v[0:3], v70 offset:32
	ds_read_b128 v[8:11], v70 offset:4640
	ds_read_b128 v[12:15], v70 offset:9248
	ds_read_b128 v[16:19], v70 offset:13856
	ds_read_b128 v[20:23], v71 offset:32
	ds_read_b128 v[24:27], v71 offset:4640
	s_waitcnt lgkmcnt(7)
	v_mfma_f32_32x32x16_bf16 a[112:127], v[60:63], v[44:47], a[112:127]
	s_waitcnt lgkmcnt(6)
	v_mfma_f32_32x32x16_bf16 a[96:111], v[80:83], v[44:47], a[96:111]
	v_mfma_f32_32x32x16_bf16 a[80:95], v[60:63], v[48:51], a[80:95]
	v_mfma_f32_32x32x16_bf16 a[64:79], v[80:83], v[48:51], a[64:79]
	v_mfma_f32_32x32x16_bf16 a[48:63], v[60:63], v[52:55], a[48:63]
	v_mfma_f32_32x32x16_bf16 a[32:47], v[80:83], v[52:55], a[32:47]
	v_mfma_f32_32x32x16_bf16 a[16:31], v[60:63], v[56:59], a[16:31]
	v_mfma_f32_32x32x16_bf16 a[0:15], v[80:83], v[56:59], a[0:15]
	ds_read_b128 v[44:47], v70 offset:64
	ds_read_b128 v[48:51], v70 offset:4672
	ds_read_b128 v[52:55], v70 offset:9280
	ds_read_b128 v[56:59], v70 offset:13888
	ds_read_b128 v[60:63], v71 offset:64
	ds_read_b128 v[80:83], v71 offset:4672
	s_waitcnt lgkmcnt(7)
	v_mfma_f32_32x32x16_bf16 a[112:127], v[20:23], v[0:3], a[112:127]
	s_waitcnt vmcnt(11)
	ds_write_b128 v104, v[4:7] offset:36864
	s_waitcnt vmcnt(10)
	ds_write_b128 v104, v[100:103] offset:41472
	s_waitcnt lgkmcnt(8)
	v_mfma_f32_32x32x16_bf16 a[96:111], v[24:27], v[0:3], a[96:111]
	s_waitcnt vmcnt(9)
	ds_write_b128 v104, v[118:121] offset:46080
	s_waitcnt vmcnt(8)
	ds_write_b128 v104, v[96:99] offset:50688
	v_mfma_f32_32x32x16_bf16 a[80:95], v[20:23], v[8:11], a[80:95]
	s_waitcnt vmcnt(7)
	ds_write_b128 v104, v[122:125] offset:55296
	s_waitcnt vmcnt(6)
	ds_write_b128 v104, v[92:95] offset:59904
	v_mfma_f32_32x32x16_bf16 a[64:79], v[24:27], v[8:11], a[64:79]
	s_waitcnt vmcnt(5)
	ds_write_b128 v104, v[126:129] offset:64512
	s_waitcnt vmcnt(4)
	ds_write_b128 v108, v[88:91]
	v_mfma_f32_32x32x16_bf16 a[48:63], v[20:23], v[12:15], a[48:63]
	s_waitcnt vmcnt(3)
	ds_write_b128 v105, v[28:31] offset:18432
	s_waitcnt vmcnt(2)
	ds_write_b128 v105, v[32:35] offset:23040
	v_mfma_f32_32x32x16_bf16 a[32:47], v[24:27], v[12:15], a[32:47]
	s_waitcnt vmcnt(1)
	ds_write_b128 v105, v[36:39] offset:27648
	s_waitcnt vmcnt(0)
	ds_write_b128 v105, v[40:43] offset:32256
	v_mfma_f32_32x32x16_bf16 a[16:31], v[20:23], v[16:19], a[16:31]
	v_mfma_f32_32x32x16_bf16 a[0:15], v[24:27], v[16:19], a[0:15]
	ds_read_b128 v[0:3], v70 offset:96
	ds_read_b128 v[4:7], v70 offset:4704
	ds_read_b128 v[8:11], v70 offset:9312
	ds_read_b128 v[12:15], v70 offset:13920
	ds_read_b128 v[16:19], v71 offset:96
	ds_read_b128 v[20:23], v71 offset:4704
	s_waitcnt lgkmcnt(14)
	v_mfma_f32_32x32x16_bf16 a[112:127], v[60:63], v[44:47], a[112:127]
	v_mfma_f32_32x32x16_bf16 a[96:111], v[80:83], v[44:47], a[96:111]
	v_mfma_f32_32x32x16_bf16 a[80:95], v[60:63], v[48:51], a[80:95]
	v_mfma_f32_32x32x16_bf16 a[64:79], v[80:83], v[48:51], a[64:79]
	v_mfma_f32_32x32x16_bf16 a[48:63], v[60:63], v[52:55], a[48:63]
	v_mfma_f32_32x32x16_bf16 a[32:47], v[80:83], v[52:55], a[32:47]
	v_mfma_f32_32x32x16_bf16 a[16:31], v[60:63], v[56:59], a[16:31]
	v_mfma_f32_32x32x16_bf16 a[0:15], v[80:83], v[56:59], a[0:15]
	s_waitcnt lgkmcnt(0)
	s_barrier
	ds_read_b128 v[24:27], v70 offset:36864
	ds_read_b128 v[28:31], v70 offset:41472
	ds_read_b128 v[32:35], v70 offset:46080
	ds_read_b128 v[36:39], v70 offset:50688
	ds_read_b128 v[40:43], v71 offset:18432
	ds_read_b128 v[44:47], v71 offset:23040
	v_mfma_f32_32x32x16_bf16 a[112:127], v[16:19], v[0:3], a[112:127]
	v_mfma_f32_32x32x16_bf16 a[96:111], v[20:23], v[0:3], a[96:111]
	v_mfma_f32_32x32x16_bf16 a[80:95], v[16:19], v[4:7], a[80:95]
	v_mfma_f32_32x32x16_bf16 a[64:79], v[20:23], v[4:7], a[64:79]
	v_mfma_f32_32x32x16_bf16 a[48:63], v[16:19], v[8:11], a[48:63]
	v_mfma_f32_32x32x16_bf16 a[32:47], v[20:23], v[8:11], a[32:47]
	v_mfma_f32_32x32x16_bf16 a[16:31], v[16:19], v[12:15], a[16:31]
	v_mfma_f32_32x32x16_bf16 a[0:15], v[20:23], v[12:15], a[0:15]
	ds_read_b128 v[0:3], v70 offset:36896
	ds_read_b128 v[4:7], v70 offset:41504
	ds_read_b128 v[8:11], v70 offset:46112
	ds_read_b128 v[12:15], v70 offset:50720
	ds_read_b128 v[16:19], v71 offset:18464
	ds_read_b128 v[20:23], v71 offset:23072
	s_waitcnt lgkmcnt(7)
	v_mfma_f32_32x32x16_bf16 a[112:127], v[40:43], v[24:27], a[112:127]
	s_waitcnt lgkmcnt(6)
	v_mfma_f32_32x32x16_bf16 a[96:111], v[44:47], v[24:27], a[96:111]
	v_mfma_f32_32x32x16_bf16 a[80:95], v[40:43], v[28:31], a[80:95]
	v_mfma_f32_32x32x16_bf16 a[64:79], v[44:47], v[28:31], a[64:79]
	v_mfma_f32_32x32x16_bf16 a[48:63], v[40:43], v[32:35], a[48:63]
	v_mfma_f32_32x32x16_bf16 a[32:47], v[44:47], v[32:35], a[32:47]
	v_mfma_f32_32x32x16_bf16 a[16:31], v[40:43], v[36:39], a[16:31]
	v_mfma_f32_32x32x16_bf16 a[0:15], v[44:47], v[36:39], a[0:15]
	ds_read_b128 v[24:27], v70 offset:36928
	ds_read_b128 v[28:31], v70 offset:41536
	ds_read_b128 v[32:35], v70 offset:46144
	ds_read_b128 v[36:39], v70 offset:50752
	ds_read_b128 v[40:43], v71 offset:18496
	ds_read_b128 v[44:47], v71 offset:23104
	s_waitcnt lgkmcnt(7)
; DI unsigned pack2(float a, float b) { f2_t v = {a, b}; bf2_t r = __builtin_convertvector(v, bf2_t); return __builtin_bit_cast(unsigned, r); }
; template <int TJ, bool SWAP, int NK, class Epi>
; DI void gemm_phase(const u16* __restrict__ A, size_t strideAz, int lda, const u16* __restrict__ Bt, size_t strideBz, int ldb,
;                    int Z, int Mt, int Nt, int GM, int K, char* smem, const Epi& epi, int vt) {
;     ...
; #pragma unroll
;     for (int i = 0; i < 4; ++i)
; #pragma unroll
;       for (int j = 0; j < TJ; ++j) {
;         if (SWAP) epi(z, mt * 256 + 128 * wm + 32 * i + r, nt * BN + 32 * TJ * wn + 32 * j, h, acc[i][j]);
;         else epi(z, mt * 256 + 128 * wm + 32 * i, nt * BN + 32 * TJ * wn + 32 * j + r, h, acc[i][j]);
;       }
;   DI void operator()(int z, int row, int colbase, int h, const f32x16& a) const {
;     if (dry) return;
; #pragma unroll
;     for (int g = 0; g < 4; ++g) {
;       const int col = colbase + 8 * g + 4 * h;
;       if (col < ncols) {
;         u32x2 pk = {pack2(a[4 * g], a[4 * g + 1]), pack2(a[4 * g + 2], a[4 * g + 3])};
;         *(u32x2*)(C + (size_t)row * ldc + col) = pk;
;       }
;     }
	v_mfma_f32_32x32x16_bf16 a[112:127], v[16:19], v[0:3], a[112:127]
	s_waitcnt lgkmcnt(6)
	v_mfma_f32_32x32x16_bf16 a[96:111], v[20:23], v[0:3], a[96:111]
	v_mfma_f32_32x32x16_bf16 a[80:95], v[16:19], v[4:7], a[80:95]
	v_mfma_f32_32x32x16_bf16 a[64:79], v[20:23], v[4:7], a[64:79]
	v_mfma_f32_32x32x16_bf16 a[48:63], v[16:19], v[8:11], a[48:63]
	v_mfma_f32_32x32x16_bf16 a[32:47], v[20:23], v[8:11], a[32:47]
	v_mfma_f32_32x32x16_bf16 a[16:31], v[16:19], v[12:15], a[16:31]
	v_mfma_f32_32x32x16_bf16 a[0:15], v[20:23], v[12:15], a[0:15]
	ds_read_b128 v[0:3], v70 offset:36960
	ds_read_b128 v[4:7], v70 offset:41568
	ds_read_b128 v[8:11], v70 offset:46176
	ds_read_b128 v[12:15], v70 offset:50784
	ds_read_b128 v[16:19], v71 offset:18528
	ds_read_b128 v[20:23], v71 offset:23136
	s_waitcnt lgkmcnt(7)
	v_mfma_f32_32x32x16_bf16 a[112:127], v[40:43], v[24:27], a[112:127]
	s_waitcnt lgkmcnt(6)
	v_mfma_f32_32x32x16_bf16 a[96:111], v[44:47], v[24:27], a[96:111]
	v_mfma_f32_32x32x16_bf16 a[80:95], v[40:43], v[28:31], a[80:95]
	v_mfma_f32_32x32x16_bf16 a[64:79], v[44:47], v[28:31], a[64:79]
	v_mfma_f32_32x32x16_bf16 a[48:63], v[40:43], v[32:35], a[48:63]
	v_mfma_f32_32x32x16_bf16 a[32:47], v[44:47], v[32:35], a[32:47]
	v_mfma_f32_32x32x16_bf16 a[16:31], v[40:43], v[36:39], a[16:31]
	v_mfma_f32_32x32x16_bf16 a[0:15], v[44:47], v[36:39], a[0:15]
	s_waitcnt lgkmcnt(0)
	s_barrier
	v_mfma_f32_32x32x16_bf16 a[112:127], v[16:19], v[0:3], a[112:127]
	v_mfma_f32_32x32x16_bf16 a[96:111], v[20:23], v[0:3], a[96:111]
	v_mfma_f32_32x32x16_bf16 a[80:95], v[16:19], v[4:7], a[80:95]
	v_mfma_f32_32x32x16_bf16 a[64:79], v[20:23], v[4:7], a[64:79]
	v_mfma_f32_32x32x16_bf16 a[48:63], v[16:19], v[8:11], a[48:63]
	v_mfma_f32_32x32x16_bf16 a[32:47], v[20:23], v[8:11], a[32:47]
	v_mfma_f32_32x32x16_bf16 a[16:31], v[16:19], v[12:15], a[16:31]
	v_mfma_f32_32x32x16_bf16 a[0:15], v[20:23], v[12:15], a[0:15]
	v_readlane_b32 s8, v255, 20
	v_readlane_b32 s9, v255, 21
	s_andn2_b64 vcc, exec, s[8:9]
	s_cbranch_vccnz .LBB0_498
	s_nop 0
	v_add_u32_e32 v18, s0, v106
	v_or_b32_e32 v16, s6, v107
	s_movk_i32 s0, 0xcc0
	v_cmp_gt_i32_e32 vcc, s0, v16
	s_cbranch_vccz .Lmy_epi_done_mla
	v_and_b32_e32 v17, 4, v16
	v_add_u32_e32 v16, v16, v17
	v_mov_b32_e32 v17, 0
	v_mov_b64_e32 v[0:1], s[2:3]
	s_movk_i32 s8, 0x1980
	v_mad_i64_i32 v[0:1], s[6:7], v18, s8, v[0:1]
	v_lshl_add_u64 v[0:1], v[16:17], 1, v[0:1]
	s_mov_b32 s0, 0x33000
	s_mov_b32 s1, 0
	v_lshl_add_u64 v[2:3], s[0:1], 0, v[0:1]
	v_lshl_add_u64 v[4:5], s[0:1], 0, v[2:3]
	v_lshl_add_u64 v[6:7], s[0:1], 0, v[4:5]
	v_accvgpr_read_b32 v8, a112
	v_accvgpr_read_b32 v9, a113
	v_accvgpr_read_b32 v10, a114
	v_accvgpr_read_b32 v11, a115
	v_accvgpr_read_b32 v16, a116
	v_accvgpr_read_b32 v17, a117
	v_accvgpr_read_b32 v18, a118
	v_accvgpr_read_b32 v19, a119
	v_cvt_pk_bf16_f32 v12, v8, v9
	v_cvt_pk_bf16_f32 v13, v10, v11
	v_cvt_pk_bf16_f32 v14, v16, v17
	v_cvt_pk_bf16_f32 v15, v18, v19
	s_nop 1
	v_permlane32_swap_b32_e32 v12, v14
	v_permlane32_swap_b32_e32 v13, v15
	global_store_dwordx4 v[0:1], v[12:15], off
	v_accvgpr_read_b32 v8, a120
	v_accvgpr_read_b32 v9, a121
	v_accvgpr_read_b32 v10, a122
	v_accvgpr_read_b32 v11, a123
	v_accvgpr_read_b32 v16, a124
	v_accvgpr_read_b32 v17, a125
	v_accvgpr_read_b32 v18, a126
	v_accvgpr_read_b32 v19, a127
	v_cvt_pk_bf16_f32 v12, v8, v9
	v_cvt_pk_bf16_f32 v13, v10, v11
	v_cvt_pk_bf16_f32 v14, v16, v17
	v_cvt_pk_bf16_f32 v15, v18, v19
	s_nop 1
	v_permlane32_swap_b32_e32 v12, v14
	v_permlane32_swap_b32_e32 v13, v15
	global_store_dwordx4 v[0:1], v[12:15], off offset:32
	v_accvgpr_read_b32 v8, a96
	v_accvgpr_read_b32 v9, a97
	v_accvgpr_read_b32 v10, a98
	v_accvgpr_read_b32 v11, a99
	v_accvgpr_read_b32 v16, a100
	v_accvgpr_read_b32 v17, a101
	v_accvgpr_read_b32 v18, a102
	v_accvgpr_read_b32 v19, a103
	v_cvt_pk_bf16_f32 v12, v8, v9
	v_cvt_pk_bf16_f32 v13, v10, v11
	v_cvt_pk_bf16_f32 v14, v16, v17
	v_cvt_pk_bf16_f32 v15, v18, v19
	s_nop 1
	v_permlane32_swap_b32_e32 v12, v14
	v_permlane32_swap_b32_e32 v13, v15
	global_store_dwordx4 v[0:1], v[12:15], off offset:64
	v_accvgpr_read_b32 v8, a104
	v_accvgpr_read_b32 v9, a105
	v_accvgpr_read_b32 v10, a106
	v_accvgpr_read_b32 v11, a107
	v_accvgpr_read_b32 v16, a108
	v_accvgpr_read_b32 v17, a109
	v_accvgpr_read_b32 v18, a110
	v_accvgpr_read_b32 v19, a111
	v_cvt_pk_bf16_f32 v12, v8, v9
	v_cvt_pk_bf16_f32 v13, v10, v11
	v_cvt_pk_bf16_f32 v14, v16, v17
	v_cvt_pk_bf16_f32 v15, v18, v19
	s_nop 1
	v_permlane32_swap_b32_e32 v12, v14
	v_permlane32_swap_b32_e32 v13, v15
	global_store_dwordx4 v[0:1], v[12:15], off offset:96
	v_accvgpr_read_b32 v8, a80
	v_accvgpr_read_b32 v9, a81
	v_accvgpr_read_b32 v10, a82
	v_accvgpr_read_b32 v11, a83
	v_accvgpr_read_b32 v16, a84
	v_accvgpr_read_b32 v17, a85
	v_accvgpr_read_b32 v18, a86
	v_accvgpr_read_b32 v19, a87
	v_cvt_pk_bf16_f32 v12, v8, v9
	v_cvt_pk_bf16_f32 v13, v10, v11
	v_cvt_pk_bf16_f32 v14, v16, v17
	v_cvt_pk_bf16_f32 v15, v18, v19
	s_nop 1
	v_permlane32_swap_b32_e32 v12, v14
	v_permlane32_swap_b32_e32 v13, v15
	global_store_dwordx4 v[2:3], v[12:15], off
	v_accvgpr_read_b32 v8, a88
	v_accvgpr_read_b32 v9, a89
	v_accvgpr_read_b32 v10, a90
	v_accvgpr_read_b32 v11, a91
	v_accvgpr_read_b32 v16, a92
	v_accvgpr_read_b32 v17, a93
	v_accvgpr_read_b32 v18, a94
	v_accvgpr_read_b32 v19, a95
; DI unsigned pack2(float a, float b) { f2_t v = {a, b}; bf2_t r = __builtin_convertvector(v, bf2_t); return __builtin_bit_cast(unsigned, r); }
; template <int TJ, bool SWAP, int NK, class Epi>
; DI void gemm_phase(const u16* __restrict__ A, size_t strideAz, int lda, const u16* __restrict__ Bt, size_t strideBz, int ldb,
;                    int Z, int Mt, int Nt, int GM, int K, char* smem, const Epi& epi, int vt) {
;     ...
; #pragma unroll
;     for (int i = 0; i < 4; ++i)
; #pragma unroll
;       for (int j = 0; j < TJ; ++j) {
;         if (SWAP) epi(z, mt * 256 + 128 * wm + 32 * i + r, nt * BN + 32 * TJ * wn + 32 * j, h, acc[i][j]);
;         else epi(z, mt * 256 + 128 * wm + 32 * i, nt * BN + 32 * TJ * wn + 32 * j + r, h, acc[i][j]);
;       }
;   DI void operator()(int z, int row, int colbase, int h, const f32x16& a) const {
;     if (dry) return;
; #pragma unroll
;     for (int g = 0; g < 4; ++g) {
;       const int col = colbase + 8 * g + 4 * h;
;       if (col < ncols) {
;         u32x2 pk = {pack2(a[4 * g], a[4 * g + 1]), pack2(a[4 * g + 2], a[4 * g + 3])};
;         *(u32x2*)(C + (size_t)row * ldc + col) = pk;
;       }
;     }
	v_cvt_pk_bf16_f32 v12, v8, v9
	v_cvt_pk_bf16_f32 v13, v10, v11
	v_cvt_pk_bf16_f32 v14, v16, v17
	v_cvt_pk_bf16_f32 v15, v18, v19
	s_nop 1
	v_permlane32_swap_b32_e32 v12, v14
	v_permlane32_swap_b32_e32 v13, v15
	global_store_dwordx4 v[2:3], v[12:15], off offset:32
	v_accvgpr_read_b32 v8, a64
	v_accvgpr_read_b32 v9, a65
	v_accvgpr_read_b32 v10, a66
	v_accvgpr_read_b32 v11, a67
	v_accvgpr_read_b32 v16, a68
	v_accvgpr_read_b32 v17, a69
	v_accvgpr_read_b32 v18, a70
	v_accvgpr_read_b32 v19, a71
	v_cvt_pk_bf16_f32 v12, v8, v9
	v_cvt_pk_bf16_f32 v13, v10, v11
	v_cvt_pk_bf16_f32 v14, v16, v17
	v_cvt_pk_bf16_f32 v15, v18, v19
	s_nop 1
	v_permlane32_swap_b32_e32 v12, v14
	v_permlane32_swap_b32_e32 v13, v15
	global_store_dwordx4 v[2:3], v[12:15], off offset:64
	v_accvgpr_read_b32 v8, a72
	v_accvgpr_read_b32 v9, a73
	v_accvgpr_read_b32 v10, a74
	v_accvgpr_read_b32 v11, a75
	v_accvgpr_read_b32 v16, a76
	v_accvgpr_read_b32 v17, a77
	v_accvgpr_read_b32 v18, a78
	v_accvgpr_read_b32 v19, a79
	v_cvt_pk_bf16_f32 v12, v8, v9
	v_cvt_pk_bf16_f32 v13, v10, v11
	v_cvt_pk_bf16_f32 v14, v16, v17
	v_cvt_pk_bf16_f32 v15, v18, v19
	s_nop 1
	v_permlane32_swap_b32_e32 v12, v14
	v_permlane32_swap_b32_e32 v13, v15
	global_store_dwordx4 v[2:3], v[12:15], off offset:96
	v_accvgpr_read_b32 v8, a48
	v_accvgpr_read_b32 v9, a49
	v_accvgpr_read_b32 v10, a50
	v_accvgpr_read_b32 v11, a51
	v_accvgpr_read_b32 v16, a52
	v_accvgpr_read_b32 v17, a53
	v_accvgpr_read_b32 v18, a54
	v_accvgpr_read_b32 v19, a55
	v_cvt_pk_bf16_f32 v12, v8, v9
	v_cvt_pk_bf16_f32 v13, v10, v11
	v_cvt_pk_bf16_f32 v14, v16, v17
	v_cvt_pk_bf16_f32 v15, v18, v19
	s_nop 1
	v_permlane32_swap_b32_e32 v12, v14
	v_permlane32_swap_b32_e32 v13, v15
	global_store_dwordx4 v[4:5], v[12:15], off
	v_accvgpr_read_b32 v8, a56
	v_accvgpr_read_b32 v9, a57
	v_accvgpr_read_b32 v10, a58
	v_accvgpr_read_b32 v11, a59
	v_accvgpr_read_b32 v16, a60
	v_accvgpr_read_b32 v17, a61
	v_accvgpr_read_b32 v18, a62
	v_accvgpr_read_b32 v19, a63
	v_cvt_pk_bf16_f32 v12, v8, v9
	v_cvt_pk_bf16_f32 v13, v10, v11
	v_cvt_pk_bf16_f32 v14, v16, v17
	v_cvt_pk_bf16_f32 v15, v18, v19
	s_nop 1
	v_permlane32_swap_b32_e32 v12, v14
	v_permlane32_swap_b32_e32 v13, v15
	global_store_dwordx4 v[4:5], v[12:15], off offset:32
	v_accvgpr_read_b32 v8, a32
	v_accvgpr_read_b32 v9, a33
	v_accvgpr_read_b32 v10, a34
	v_accvgpr_read_b32 v11, a35
	v_accvgpr_read_b32 v16, a36
	v_accvgpr_read_b32 v17, a37
	v_accvgpr_read_b32 v18, a38
	v_accvgpr_read_b32 v19, a39
	v_cvt_pk_bf16_f32 v12, v8, v9
	v_cvt_pk_bf16_f32 v13, v10, v11
	v_cvt_pk_bf16_f32 v14, v16, v17
	v_cvt_pk_bf16_f32 v15, v18, v19
	s_nop 1
	v_permlane32_swap_b32_e32 v12, v14
	v_permlane32_swap_b32_e32 v13, v15
	global_store_dwordx4 v[4:5], v[12:15], off offset:64
	v_accvgpr_read_b32 v8, a40
	v_accvgpr_read_b32 v9, a41
	v_accvgpr_read_b32 v10, a42
	v_accvgpr_read_b32 v11, a43
	v_accvgpr_read_b32 v16, a44
	v_accvgpr_read_b32 v17, a45
	v_accvgpr_read_b32 v18, a46
	v_accvgpr_read_b32 v19, a47
	v_cvt_pk_bf16_f32 v12, v8, v9
	v_cvt_pk_bf16_f32 v13, v10, v11
	v_cvt_pk_bf16_f32 v14, v16, v17
	v_cvt_pk_bf16_f32 v15, v18, v19
	s_nop 1
	v_permlane32_swap_b32_e32 v12, v14
	v_permlane32_swap_b32_e32 v13, v15
	global_store_dwordx4 v[4:5], v[12:15], off offset:96
	v_accvgpr_read_b32 v8, a16
	v_accvgpr_read_b32 v9, a17
	v_accvgpr_read_b32 v10, a18
	v_accvgpr_read_b32 v11, a19
	v_accvgpr_read_b32 v16, a20
	v_accvgpr_read_b32 v17, a21
	v_accvgpr_read_b32 v18, a22
	v_accvgpr_read_b32 v19, a23
	v_cvt_pk_bf16_f32 v12, v8, v9
	v_cvt_pk_bf16_f32 v13, v10, v11
	v_cvt_pk_bf16_f32 v14, v16, v17
	v_cvt_pk_bf16_f32 v15, v18, v19
	s_nop 1
	v_permlane32_swap_b32_e32 v12, v14
	v_permlane32_swap_b32_e32 v13, v15
	global_store_dwordx4 v[6:7], v[12:15], off
	v_accvgpr_read_b32 v8, a24
	v_accvgpr_read_b32 v9, a25
	v_accvgpr_read_b32 v10, a26
	v_accvgpr_read_b32 v11, a27
	v_accvgpr_read_b32 v16, a28
	v_accvgpr_read_b32 v17, a29
	v_accvgpr_read_b32 v18, a30
	v_accvgpr_read_b32 v19, a31
	v_cvt_pk_bf16_f32 v12, v8, v9
	v_cvt_pk_bf16_f32 v13, v10, v11
	v_cvt_pk_bf16_f32 v14, v16, v17
	v_cvt_pk_bf16_f32 v15, v18, v19
	s_nop 1
	v_permlane32_swap_b32_e32 v12, v14
	v_permlane32_swap_b32_e32 v13, v15
	global_store_dwordx4 v[6:7], v[12:15], off offset:32
	v_accvgpr_read_b32 v8, a0
	v_accvgpr_read_b32 v9, a1
	v_accvgpr_read_b32 v10, a2
	v_accvgpr_read_b32 v11, a3
	v_accvgpr_read_b32 v16, a4
	v_accvgpr_read_b32 v17, a5
	v_accvgpr_read_b32 v18, a6
	v_accvgpr_read_b32 v19, a7
	v_cvt_pk_bf16_f32 v12, v8, v9
	v_cvt_pk_bf16_f32 v13, v10, v11
	v_cvt_pk_bf16_f32 v14, v16, v17
	v_cvt_pk_bf16_f32 v15, v18, v19
	s_nop 1
	v_permlane32_swap_b32_e32 v12, v14
	v_permlane32_swap_b32_e32 v13, v15
	global_store_dwordx4 v[6:7], v[12:15], off offset:64
	v_accvgpr_read_b32 v8, a8
	v_accvgpr_read_b32 v9, a9
	v_accvgpr_read_b32 v10, a10
	v_accvgpr_read_b32 v11, a11
	v_accvgpr_read_b32 v16, a12
	v_accvgpr_read_b32 v17, a13
	v_accvgpr_read_b32 v18, a14
	v_accvgpr_read_b32 v19, a15
	v_cvt_pk_bf16_f32 v12, v8, v9
	v_cvt_pk_bf16_f32 v13, v10, v11
	v_cvt_pk_bf16_f32 v14, v16, v17
	v_cvt_pk_bf16_f32 v15, v18, v19
	s_nop 1
	v_permlane32_swap_b32_e32 v12, v14
	v_permlane32_swap_b32_e32 v13, v15
	global_store_dwordx4 v[6:7], v[12:15], off offset:96
.Lmy_epi_done_mla:
	s_branch .LBB0_498
.LBB0_565:
	s_mov_b64 s[0:1], 0
